# chained activation-major order + no-op lgkmcnt waits and inner priority flips removed inside clusters
# speedup vs baseline: 1.0062x; 1.0062x over previous
; #define PG8_STAGE(bufoff, gbase, voff) do { _Pragma("unroll") for (int _i = 0; _i < 2; ++_i) \
;         asm volatile("s_mov_b32 m0, %2\n\ts_nop 0\n\tglobal_load_lds_dwordx4 %0, %1" :: "v"((voff)[_i]), "s"((const char*)(gbase)), "s"(ldsbase + (unsigned)(bufoff) + ldsw + (unsigned)_i * 8192u) : "memory", "m0"); } while (0)
; #define PG8_LDA(dst, b, h) do { _Pragma("unroll") for (int m = 0; m < 4; ++m) _Pragma("unroll") for (int k = 0; k < 2; ++k) dst[m][k] = *(const PG8_LAS bf16x8*)(lds + PG8_SA(b, h) + aoff + m * 2048 + k * 1024); } while (0)
; #define PG8_LDB(dst, b, h) do { _Pragma("unroll") for (int n = 0; n < 2; ++n) _Pragma("unroll") for (int k = 0; k < 2; ++k) dst[n][k] = *(const PG8_LAS bf16x8*)(lds + PG8_SB(b, h) + boff + n * 2048 + k * 1024); } while (0)
; #define PG8_MMA(ai, bj, At, Bt) do { __builtin_amdgcn_s_setprio(1); _Pragma("unroll") for (int m = 0; m < 4; ++m) _Pragma("unroll") for (int n = 0; n < 2; ++n) _Pragma("unroll") for (int k = 0; k < 2; ++k) \
;         acc[ai][bj][m][n] = __builtin_amdgcn_mfma_f32_16x16x32_bf16(Bt[n][k], At[m][k], acc[ai][bj][m][n], 0, 0, 0); __builtin_amdgcn_s_setprio(0); } while (0)
; template <class Epi, class Sched, bool ALIGN_EPI = false, bool SP2 = false>
; __device__ __forceinline__ void gemm_phase(PG8_LAS unsigned char* lds, const Gemm g, const Sched& S, const Epi& E) {
;     ...
;             PG8_LDB(B0, 0, 0); PG8_LDB(B1, 0, 1); PG8_SCHED; PG8_LDA(At, 0, 0); PG8_STAGE(PG8_SA(1, 1), a1 + hstep, voffA);
;             PG8_WAIT_V(8); PG8_WAIT_L(0); PG8_BAR; PG8_MMA(0, 0, At, B0); PG8_MMA(0, 1, At, B1); PG8_BAR; PG8_SCHED;
;             PG8_LDA(At, 0, 1); PG8_STAGE(PG8_SB(0, 0), b2, voffB); PG8_STAGE(PG8_SB(0, 1), b2 + hstep, voffB); PG8_STAGE(PG8_SA(0, 0), a2, voffA);
;             PG8_WAIT_V(8); PG8_WAIT_L(0); PG8_BAR; PG8_MMA(1, 0, At, B0); PG8_MMA(1, 1, At, B1); PG8_BAR; PG8_SCHED;
;             PG8_LDB(B0, 1, 0); PG8_LDB(B1, 1, 1); PG8_SCHED; PG8_LDA(At, 1, 0); PG8_STAGE(PG8_SA(0, 1), a2 + hstep, voffA);
;             PG8_WAIT_V(8); PG8_WAIT_L(0); PG8_BAR; PG8_MMA(0, 0, At, B0); PG8_MMA(0, 1, At, B1); PG8_BAR; PG8_SCHED;
;             PG8_LDA(At, 1, 1); PG8_STAGE(PG8_SB(1, 0), b3, voffB); PG8_STAGE(PG8_SB(1, 1), b3 + hstep, voffB); PG8_STAGE(PG8_SA(1, 0), a3, voffA);
;             PG8_WAIT_V(8); PG8_WAIT_L(0); PG8_BAR; PG8_MMA(1, 0, At, B0); PG8_MMA(1, 1, At, B1); PG8_BAR; PG8_SCHED;
.LBB0_138:
	ds_read_b128 v[148:151], v142
	ds_read_b128 v[152:155], v142 offset:1024
	ds_read_b128 v[156:159], v142 offset:2048
	ds_read_b128 v[160:163], v142 offset:3072
	ds_read_b128 v[164:167], v143
	ds_read_b128 v[168:171], v143 offset:1024
	ds_read_b128 v[172:175], v143 offset:2048
	ds_read_b128 v[176:179], v143 offset:3072
	s_add_u32 s62, s66, 0x100
	s_addc_u32 s63, s67, 0
	s_cmp_eq_u32 s96, 60
	s_cselect_b32 s86, s92, s62
	s_cselect_b32 s87, s13, s63
	s_cselect_b32 s84, s93, s94
	s_cselect_b32 s85, s11, s95
	s_add_u32 s76, s86, 0x80
	s_addc_u32 s77, s87, 0
	ds_read_b128 v[180:183], v144
	ds_read_b128 v[184:187], v144 offset:1024
	ds_read_b128 v[188:191], v144 offset:2048
	ds_read_b128 v[192:195], v144 offset:3072
	ds_read_b128 v[196:199], v144 offset:4096
	ds_read_b128 v[200:203], v144 offset:5120
	ds_read_b128 v[204:207], v144 offset:6144
	ds_read_b128 v[208:211], v144 offset:7168
	s_add_u32 s66, s66, 0x100080
	s_addc_u32 s67, s67, 0
	s_mov_b32 m0, s83
	s_nop 0
	global_load_lds_dwordx4 v136, s[66:67]
	s_nop 0
	s_mov_b32 m0, s88
	s_nop 0
	global_load_lds_dwordx4 v138, s[66:67]
	s_waitcnt vmcnt(8)
	s_waitcnt lgkmcnt(0)
	s_barrier
	s_setprio 1
	s_waitcnt lgkmcnt(7)
	v_mfma_f32_16x16x32_bf16 v[126:129], v[148:151], v[180:183], v[126:129]
	v_mfma_f32_16x16x32_bf16 v[126:129], v[152:155], v[184:187], v[126:129]
	v_mfma_f32_16x16x32_bf16 v[122:125], v[160:163], v[184:187], v[122:125]
	v_mfma_f32_16x16x32_bf16 v[122:125], v[156:159], v[180:183], v[122:125]
	v_mfma_f32_16x16x32_bf16 v[118:121], v[164:167], v[180:183], v[118:121]
	v_mfma_f32_16x16x32_bf16 v[118:121], v[168:171], v[184:187], v[118:121]
	v_mfma_f32_16x16x32_bf16 v[114:117], v[176:179], v[184:187], v[114:117]
	v_mfma_f32_16x16x32_bf16 v[114:117], v[172:175], v[180:183], v[114:117]
	v_mfma_f32_16x16x32_bf16 v[98:101], v[172:175], v[188:191], v[98:101]
	v_mfma_f32_16x16x32_bf16 v[98:101], v[176:179], v[192:195], v[98:101]
	v_mfma_f32_16x16x32_bf16 v[102:105], v[168:171], v[192:195], v[102:105]
	v_mfma_f32_16x16x32_bf16 v[102:105], v[164:167], v[188:191], v[102:105]
	v_mfma_f32_16x16x32_bf16 v[106:109], v[156:159], v[188:191], v[106:109]
	v_mfma_f32_16x16x32_bf16 v[106:109], v[160:163], v[192:195], v[106:109]
	v_mfma_f32_16x16x32_bf16 v[110:113], v[152:155], v[192:195], v[110:113]
	v_mfma_f32_16x16x32_bf16 v[110:113], v[148:151], v[188:191], v[110:113]
	v_mfma_f32_16x16x32_bf16 v[94:97], v[148:151], v[196:199], v[94:97]
	v_mfma_f32_16x16x32_bf16 v[94:97], v[152:155], v[200:203], v[94:97]
	v_mfma_f32_16x16x32_bf16 v[90:93], v[160:163], v[200:203], v[90:93]
	v_mfma_f32_16x16x32_bf16 v[90:93], v[156:159], v[196:199], v[90:93]
	v_mfma_f32_16x16x32_bf16 v[86:89], v[164:167], v[196:199], v[86:89]
	v_mfma_f32_16x16x32_bf16 v[86:89], v[168:171], v[200:203], v[86:89]
	v_mfma_f32_16x16x32_bf16 v[82:85], v[176:179], v[200:203], v[82:85]
	v_mfma_f32_16x16x32_bf16 v[82:85], v[172:175], v[196:199], v[82:85]
	v_mfma_f32_16x16x32_bf16 v[66:69], v[172:175], v[204:207], v[66:69]
	v_mfma_f32_16x16x32_bf16 v[66:69], v[176:179], v[208:211], v[66:69]
	v_mfma_f32_16x16x32_bf16 v[70:73], v[168:171], v[208:211], v[70:73]
	v_mfma_f32_16x16x32_bf16 v[70:73], v[164:167], v[204:207], v[70:73]
	v_mfma_f32_16x16x32_bf16 v[74:77], v[156:159], v[204:207], v[74:77]
	v_mfma_f32_16x16x32_bf16 v[74:77], v[160:163], v[208:211], v[74:77]
	v_mfma_f32_16x16x32_bf16 v[78:81], v[152:155], v[208:211], v[78:81]
	s_setprio 2
	s_barrier
	v_mfma_f32_16x16x32_bf16 v[78:81], v[148:151], v[204:207], v[78:81]
	s_setprio 0
	ds_read_b128 v[180:183], v144 offset:16384
	ds_read_b128 v[184:187], v144 offset:17408
	ds_read_b128 v[188:191], v144 offset:18432
	ds_read_b128 v[192:195], v144 offset:19456
	ds_read_b128 v[196:199], v144 offset:20480
	ds_read_b128 v[200:203], v144 offset:21504
	ds_read_b128 v[252:255], v144 offset:22528
	ds_read_b128 v[208:211], v144 offset:23552
	s_mov_b32 m0, s55
	s_nop 0
	global_load_lds_dwordx4 v137, s[84:85]
	s_add_u32 s66, s84, 0x100000
	s_mov_b32 m0, s56
	s_nop 0
	global_load_lds_dwordx4 v139, s[84:85]
	s_addc_u32 s67, s85, 0
	s_mov_b32 m0, s57
	s_nop 0
	global_load_lds_dwordx4 v137, s[66:67]
	s_nop 0
	s_mov_b32 m0, s58
	s_nop 0
	global_load_lds_dwordx4 v139, s[66:67]
	s_nop 0
	s_mov_b32 m0, s54
	s_nop 0
	global_load_lds_dwordx4 v136, s[86:87]
	s_nop 0
	s_mov_b32 m0, s59
	s_nop 0
	global_load_lds_dwordx4 v138, s[86:87]
	s_waitcnt vmcnt(8)
	s_waitcnt lgkmcnt(0)
	s_barrier
	s_setprio 1
	s_waitcnt lgkmcnt(7)
	v_mfma_f32_16x16x32_bf16 v[62:65], v[148:151], v[180:183], v[62:65]
	v_mfma_f32_16x16x32_bf16 v[62:65], v[152:155], v[184:187], v[62:65]
	v_mfma_f32_16x16x32_bf16 v[58:61], v[160:163], v[184:187], v[58:61]
	v_mfma_f32_16x16x32_bf16 v[58:61], v[156:159], v[180:183], v[58:61]
	v_mfma_f32_16x16x32_bf16 v[54:57], v[164:167], v[180:183], v[54:57]
	v_mfma_f32_16x16x32_bf16 v[54:57], v[168:171], v[184:187], v[54:57]
	v_mfma_f32_16x16x32_bf16 v[50:53], v[176:179], v[184:187], v[50:53]
	v_mfma_f32_16x16x32_bf16 v[50:53], v[172:175], v[180:183], v[50:53]
	v_mfma_f32_16x16x32_bf16 v[34:37], v[172:175], v[188:191], v[34:37]
	v_mfma_f32_16x16x32_bf16 v[34:37], v[176:179], v[192:195], v[34:37]
	v_mfma_f32_16x16x32_bf16 v[38:41], v[168:171], v[192:195], v[38:41]
	v_mfma_f32_16x16x32_bf16 v[38:41], v[164:167], v[188:191], v[38:41]
	v_mfma_f32_16x16x32_bf16 v[42:45], v[156:159], v[188:191], v[42:45]
	v_mfma_f32_16x16x32_bf16 v[42:45], v[160:163], v[192:195], v[42:45]
	v_mfma_f32_16x16x32_bf16 v[46:49], v[152:155], v[192:195], v[46:49]
	v_mfma_f32_16x16x32_bf16 v[46:49], v[148:151], v[188:191], v[46:49]
	v_mfma_f32_16x16x32_bf16 v[30:33], v[148:151], v[196:199], v[30:33]
	v_mfma_f32_16x16x32_bf16 v[30:33], v[152:155], v[200:203], v[30:33]
	v_mfma_f32_16x16x32_bf16 v[26:29], v[160:163], v[200:203], v[26:29]
	v_mfma_f32_16x16x32_bf16 v[26:29], v[156:159], v[196:199], v[26:29]
	v_mfma_f32_16x16x32_bf16 v[22:25], v[164:167], v[196:199], v[22:25]
	v_mfma_f32_16x16x32_bf16 v[22:25], v[168:171], v[200:203], v[22:25]
	v_mfma_f32_16x16x32_bf16 v[18:21], v[176:179], v[200:203], v[18:21]
	v_mfma_f32_16x16x32_bf16 v[18:21], v[172:175], v[196:199], v[18:21]
	v_mfma_f32_16x16x32_bf16 v[2:5], v[172:175], v[252:255], v[2:5]
	v_mfma_f32_16x16x32_bf16 v[2:5], v[176:179], v[208:211], v[2:5]
	v_mfma_f32_16x16x32_bf16 v[6:9], v[168:171], v[208:211], v[6:9]
	v_mfma_f32_16x16x32_bf16 v[6:9], v[164:167], v[252:255], v[6:9]
	v_mfma_f32_16x16x32_bf16 v[10:13], v[156:159], v[252:255], v[10:13]
	v_mfma_f32_16x16x32_bf16 v[10:13], v[160:163], v[208:211], v[10:13]
	v_mfma_f32_16x16x32_bf16 v[14:17], v[152:155], v[208:211], v[14:17]
	s_setprio 2
	s_barrier
; #define PG8_STAGE(bufoff, gbase, voff) do { _Pragma("unroll") for (int _i = 0; _i < 2; ++_i) \
;         asm volatile("s_mov_b32 m0, %2\n\ts_nop 0\n\tglobal_load_lds_dwordx4 %0, %1" :: "v"((voff)[_i]), "s"((const char*)(gbase)), "s"(ldsbase + (unsigned)(bufoff) + ldsw + (unsigned)_i * 8192u) : "memory", "m0"); } while (0)
; #define PG8_LDA(dst, b, h) do { _Pragma("unroll") for (int m = 0; m < 4; ++m) _Pragma("unroll") for (int k = 0; k < 2; ++k) dst[m][k] = *(const PG8_LAS bf16x8*)(lds + PG8_SA(b, h) + aoff + m * 2048 + k * 1024); } while (0)
; #define PG8_LDB(dst, b, h) do { _Pragma("unroll") for (int n = 0; n < 2; ++n) _Pragma("unroll") for (int k = 0; k < 2; ++k) dst[n][k] = *(const PG8_LAS bf16x8*)(lds + PG8_SB(b, h) + boff + n * 2048 + k * 1024); } while (0)
; #define PG8_MMA(ai, bj, At, Bt) do { __builtin_amdgcn_s_setprio(1); _Pragma("unroll") for (int m = 0; m < 4; ++m) _Pragma("unroll") for (int n = 0; n < 2; ++n) _Pragma("unroll") for (int k = 0; k < 2; ++k) \
;         acc[ai][bj][m][n] = __builtin_amdgcn_mfma_f32_16x16x32_bf16(Bt[n][k], At[m][k], acc[ai][bj][m][n], 0, 0, 0); __builtin_amdgcn_s_setprio(0); } while (0)
; #define PG8_WAIT_V(n) asm volatile("s_waitcnt vmcnt(" #n ")" ::: "memory")
; #define PG8_WAIT_L(n) asm volatile("s_waitcnt lgkmcnt(" #n ")" ::: "memory")
; #define PG8_BAR __builtin_amdgcn_s_barrier()
; #define PG8_SCHED __builtin_amdgcn_sched_barrier(0)
; template <class Epi, class Sched, bool ALIGN_EPI = false, bool SP2 = false>
; __device__ __forceinline__ void gemm_phase(PG8_LAS unsigned char* lds, const Gemm g, const Sched& S, const Epi& E) {
;     ...
;             PG8_LDB(B0, 1, 0); PG8_LDB(B1, 1, 1); PG8_SCHED; PG8_LDA(At, 1, 0); PG8_STAGE(PG8_SA(0, 1), a2 + hstep, voffA);
;             PG8_WAIT_V(8); PG8_WAIT_L(0); PG8_BAR; PG8_MMA(0, 0, At, B0); PG8_MMA(0, 1, At, B1); PG8_BAR; PG8_SCHED;
;             PG8_LDA(At, 1, 1); PG8_STAGE(PG8_SB(1, 0), b3, voffB); PG8_STAGE(PG8_SB(1, 1), b3 + hstep, voffB); PG8_STAGE(PG8_SA(1, 0), a3, voffA);
;             PG8_WAIT_V(8); PG8_WAIT_L(0); PG8_BAR; PG8_MMA(1, 0, At, B0); PG8_MMA(1, 1, At, B1); PG8_BAR; PG8_SCHED;
	v_mfma_f32_16x16x32_bf16 v[14:17], v[148:151], v[252:255], v[14:17]
	s_setprio 0
	ds_read_b128 v[248:251], v145
	ds_read_b128 v[152:155], v145 offset:1024
	ds_read_b128 v[156:159], v145 offset:2048
	ds_read_b128 v[160:163], v145 offset:3072
	ds_read_b128 v[164:167], v146
	ds_read_b128 v[168:171], v146 offset:1024
	ds_read_b128 v[172:175], v146 offset:2048
	ds_read_b128 v[176:179], v146 offset:3072
	ds_read_b128 v[180:183], v144 offset:32768
	ds_read_b128 v[184:187], v144 offset:33792
	ds_read_b128 v[188:191], v144 offset:34816
	ds_read_b128 v[192:195], v144 offset:35840
	ds_read_b128 v[196:199], v144 offset:36864
	ds_read_b128 v[200:203], v144 offset:37888
	ds_read_b128 v[204:207], v144 offset:38912
	ds_read_b128 v[208:211], v144 offset:39936
	s_add_u32 s66, s86, 0x100000
	s_addc_u32 s67, s87, 0
	s_mov_b32 m0, s60
	s_nop 0
	global_load_lds_dwordx4 v136, s[66:67]
	s_nop 0
	s_mov_b32 m0, s61
	s_nop 0
	global_load_lds_dwordx4 v138, s[66:67]
	s_waitcnt vmcnt(8)
	s_waitcnt lgkmcnt(0)
	s_barrier
	s_setprio 1
	s_waitcnt lgkmcnt(7)
	v_mfma_f32_16x16x32_bf16 v[126:129], v[248:251], v[180:183], v[126:129]
	v_mfma_f32_16x16x32_bf16 v[126:129], v[152:155], v[184:187], v[126:129]
	v_mfma_f32_16x16x32_bf16 v[122:125], v[160:163], v[184:187], v[122:125]
	v_mfma_f32_16x16x32_bf16 v[122:125], v[156:159], v[180:183], v[122:125]
	v_mfma_f32_16x16x32_bf16 v[118:121], v[164:167], v[180:183], v[118:121]
	v_mfma_f32_16x16x32_bf16 v[118:121], v[168:171], v[184:187], v[118:121]
	v_mfma_f32_16x16x32_bf16 v[114:117], v[176:179], v[184:187], v[114:117]
	v_mfma_f32_16x16x32_bf16 v[114:117], v[172:175], v[180:183], v[114:117]
	v_mfma_f32_16x16x32_bf16 v[98:101], v[172:175], v[188:191], v[98:101]
	v_mfma_f32_16x16x32_bf16 v[98:101], v[176:179], v[192:195], v[98:101]
	v_mfma_f32_16x16x32_bf16 v[102:105], v[168:171], v[192:195], v[102:105]
	v_mfma_f32_16x16x32_bf16 v[102:105], v[164:167], v[188:191], v[102:105]
	v_mfma_f32_16x16x32_bf16 v[106:109], v[156:159], v[188:191], v[106:109]
	v_mfma_f32_16x16x32_bf16 v[106:109], v[160:163], v[192:195], v[106:109]
	v_mfma_f32_16x16x32_bf16 v[110:113], v[152:155], v[192:195], v[110:113]
	v_mfma_f32_16x16x32_bf16 v[110:113], v[248:251], v[188:191], v[110:113]
	v_mfma_f32_16x16x32_bf16 v[94:97], v[248:251], v[196:199], v[94:97]
	v_mfma_f32_16x16x32_bf16 v[94:97], v[152:155], v[200:203], v[94:97]
	v_mfma_f32_16x16x32_bf16 v[90:93], v[160:163], v[200:203], v[90:93]
	v_mfma_f32_16x16x32_bf16 v[90:93], v[156:159], v[196:199], v[90:93]
	v_mfma_f32_16x16x32_bf16 v[86:89], v[164:167], v[196:199], v[86:89]
	v_mfma_f32_16x16x32_bf16 v[86:89], v[168:171], v[200:203], v[86:89]
	v_mfma_f32_16x16x32_bf16 v[82:85], v[176:179], v[200:203], v[82:85]
	v_mfma_f32_16x16x32_bf16 v[82:85], v[172:175], v[196:199], v[82:85]
	v_mfma_f32_16x16x32_bf16 v[66:69], v[172:175], v[204:207], v[66:69]
	v_mfma_f32_16x16x32_bf16 v[66:69], v[176:179], v[208:211], v[66:69]
	v_mfma_f32_16x16x32_bf16 v[70:73], v[168:171], v[208:211], v[70:73]
	v_mfma_f32_16x16x32_bf16 v[70:73], v[164:167], v[204:207], v[70:73]
	v_mfma_f32_16x16x32_bf16 v[74:77], v[156:159], v[204:207], v[74:77]
	v_mfma_f32_16x16x32_bf16 v[74:77], v[160:163], v[208:211], v[74:77]
	v_mfma_f32_16x16x32_bf16 v[78:81], v[152:155], v[208:211], v[78:81]
	s_setprio 2
	s_barrier
	v_mfma_f32_16x16x32_bf16 v[78:81], v[248:251], v[204:207], v[78:81]
	s_setprio 0
	ds_read_b128 v[180:183], v144 offset:49152
	ds_read_b128 v[184:187], v144 offset:50176
	ds_read_b128 v[188:191], v144 offset:51200
	ds_read_b128 v[192:195], v144 offset:52224
	ds_read_b128 v[196:199], v144 offset:53248
	ds_read_b128 v[200:203], v144 offset:54272
	ds_read_b128 v[252:255], v144 offset:55296
	ds_read_b128 v[208:211], v144 offset:56320
	s_add_u32 s66, s84, 0x80
	s_addc_u32 s67, s85, 0
	s_mov_b32 m0, s64
	s_nop 0
	global_load_lds_dwordx4 v137, s[66:67]
	s_nop 0
	s_mov_b32 m0, s65
	s_nop 0
	global_load_lds_dwordx4 v139, s[66:67]
	s_add_u32 s66, s84, 0x100080
	s_addc_u32 s67, s85, 0
	s_mov_b32 m0, s70
	s_nop 0
	global_load_lds_dwordx4 v137, s[66:67]
	s_nop 0
	s_mov_b32 m0, s71
	s_nop 0
	global_load_lds_dwordx4 v139, s[66:67]
	s_nop 0
	s_mov_b32 m0, s68
	s_nop 0
	global_load_lds_dwordx4 v136, s[76:77]
	s_nop 0
	s_mov_b32 m0, s69
	s_nop 0
	global_load_lds_dwordx4 v138, s[76:77]
	s_waitcnt vmcnt(8)
	s_waitcnt lgkmcnt(0)
	s_barrier
	s_setprio 1
	s_waitcnt lgkmcnt(7)
	v_mfma_f32_16x16x32_bf16 v[62:65], v[248:251], v[180:183], v[62:65]
	v_mfma_f32_16x16x32_bf16 v[62:65], v[152:155], v[184:187], v[62:65]
	v_mfma_f32_16x16x32_bf16 v[58:61], v[160:163], v[184:187], v[58:61]
	v_mfma_f32_16x16x32_bf16 v[58:61], v[156:159], v[180:183], v[58:61]
	v_mfma_f32_16x16x32_bf16 v[54:57], v[164:167], v[180:183], v[54:57]
	v_mfma_f32_16x16x32_bf16 v[54:57], v[168:171], v[184:187], v[54:57]
	v_mfma_f32_16x16x32_bf16 v[50:53], v[176:179], v[184:187], v[50:53]
	v_mfma_f32_16x16x32_bf16 v[50:53], v[172:175], v[180:183], v[50:53]
	v_mfma_f32_16x16x32_bf16 v[34:37], v[172:175], v[188:191], v[34:37]
	v_mfma_f32_16x16x32_bf16 v[34:37], v[176:179], v[192:195], v[34:37]
	v_mfma_f32_16x16x32_bf16 v[38:41], v[168:171], v[192:195], v[38:41]
	v_mfma_f32_16x16x32_bf16 v[38:41], v[164:167], v[188:191], v[38:41]
	v_mfma_f32_16x16x32_bf16 v[42:45], v[156:159], v[188:191], v[42:45]
	v_mfma_f32_16x16x32_bf16 v[42:45], v[160:163], v[192:195], v[42:45]
	v_mfma_f32_16x16x32_bf16 v[46:49], v[152:155], v[192:195], v[46:49]
	v_mfma_f32_16x16x32_bf16 v[46:49], v[248:251], v[188:191], v[46:49]
	v_mfma_f32_16x16x32_bf16 v[30:33], v[248:251], v[196:199], v[30:33]
	v_mfma_f32_16x16x32_bf16 v[30:33], v[152:155], v[200:203], v[30:33]
	v_mfma_f32_16x16x32_bf16 v[26:29], v[160:163], v[200:203], v[26:29]
	v_mfma_f32_16x16x32_bf16 v[26:29], v[156:159], v[196:199], v[26:29]
	v_mfma_f32_16x16x32_bf16 v[22:25], v[164:167], v[196:199], v[22:25]
	v_mfma_f32_16x16x32_bf16 v[22:25], v[168:171], v[200:203], v[22:25]
	v_mfma_f32_16x16x32_bf16 v[18:21], v[176:179], v[200:203], v[18:21]
	v_mfma_f32_16x16x32_bf16 v[18:21], v[172:175], v[196:199], v[18:21]
	v_mfma_f32_16x16x32_bf16 v[2:5], v[172:175], v[252:255], v[2:5]
	v_mfma_f32_16x16x32_bf16 v[2:5], v[176:179], v[208:211], v[2:5]
	v_mfma_f32_16x16x32_bf16 v[6:9], v[168:171], v[208:211], v[6:9]
	v_mfma_f32_16x16x32_bf16 v[6:9], v[164:167], v[252:255], v[6:9]
	v_mfma_f32_16x16x32_bf16 v[10:13], v[156:159], v[252:255], v[10:13]
	v_mfma_f32_16x16x32_bf16 v[10:13], v[160:163], v[208:211], v[10:13]
	v_mfma_f32_16x16x32_bf16 v[14:17], v[152:155], v[208:211], v[14:17]
	s_setprio 2
	s_barrier
; __device__ __forceinline__ unsigned cvt_pk_bf16(float lo, float hi) { unsigned r; asm volatile("v_cvt_pk_bf16_f32 %0, %1, %2" : "=v"(r) : "v"(lo), "v"(hi)); return r; }
; __device__ __forceinline__ float silu_f(float x) { return x * sigmoid_f(x); }
; #define PG8_MMA(ai, bj, At, Bt) do { __builtin_amdgcn_s_setprio(1); _Pragma("unroll") for (int m = 0; m < 4; ++m) _Pragma("unroll") for (int n = 0; n < 2; ++n) _Pragma("unroll") for (int k = 0; k < 2; ++k) \
;         acc[ai][bj][m][n] = __builtin_amdgcn_mfma_f32_16x16x32_bf16(Bt[n][k], At[m][k], acc[ai][bj][m][n], 0, 0, 0); __builtin_amdgcn_s_setprio(0); } while (0)
; #define PG8_WAIT_V(n) asm volatile("s_waitcnt vmcnt(" #n ")" ::: "memory")
; #define PG8_WAIT_L(n) asm volatile("s_waitcnt lgkmcnt(" #n ")" ::: "memory")
; #define PG8_BAR __builtin_amdgcn_s_barrier()
; #define PG8_SCHED __builtin_amdgcn_sched_barrier(0)
;     __device__ __forceinline__ void operator()(const f32x4 (&acc)[2][2][4][2], const Unit& u, int wr, int wc, int fr, int fq) const {
;         const int row0 = u.pm * BM + wr * 64 + fr, col0 = u.pn * HALF + wc * 32 + 8 * fq;
; #pragma unroll
;         for (int ai = 0; ai < 2; ++ai)
; #pragma unroll
;             for (int m = 0; m < 4; ++m) { bf16_t* rowp = O + (size_t)(row0 + ai * HALF + m * 16) * ldc + col0;
;                 const f32x4 g0 = acc[ai][0][m][0], g1 = acc[ai][0][m][1], u0 = acc[ai][1][m][0], u1 = acc[ai][1][m][1];
;                 f32x4 v0, v1;
; #pragma unroll
;                 for (int j = 0; j < 4; ++j) { v0[j] = silu_f(g0[j]) * u0[j]; v1[j] = silu_f(g1[j]) * u1[j]; }
;                 u32x4 w; w.x = cvt_pk_bf16(v0[0], v0[1]); w.y = cvt_pk_bf16(v0[2], v0[3]); w.z = cvt_pk_bf16(v1[0], v1[1]); w.w = cvt_pk_bf16(v1[2], v1[3]);
;                 *(u32x4*)rowp = w; }
; template <class Epi, class Sched, bool ALIGN_EPI = false, bool SP2 = false>
; __device__ __forceinline__ void gemm_phase(PG8_LAS unsigned char* lds, const Gemm g, const Sched& S, const Epi& E) {
;     ...
;             PG8_WAIT_V(8); PG8_WAIT_L(0); PG8_BAR; PG8_MMA(1, 0, At, B0); PG8_MMA(1, 1, At, B1); PG8_BAR; PG8_SCHED;
	v_mfma_f32_16x16x32_bf16 v[14:17], v[248:251], v[252:255], v[14:17]
	s_setprio 0
	s_add_i32 s96, s96, 2
	s_add_u32 s94, s94, 0x100
	s_addc_u32 s95, s95, 0
	s_cmp_gt_u32 s96, 61
	s_mov_b64 s[66:67], s[62:63]
	s_cbranch_scc0 .LBB0_138
	v_mul_f32_e32 v134, 0xbfb8aa3b, v126
	v_exp_f32_e32 v150, v134
	v_mul_f32_e32 v134, 0xbfb8aa3b, v122
	v_exp_f32_e32 v151, v134
	v_lshl_or_b32 v148, s91, 7, v141
	v_add_f32_e32 v150, 1.0, v150
	v_rcp_f32_e32 v152, v150
	v_add_f32_e32 v150, 1.0, v151
	v_rcp_f32_e32 v153, v150
	v_lshl_add_u32 v147, s82, 8, v140
	v_mul_f32_e32 v126, v126, v152
	v_mul_f32_e32 v118, v126, v118
	v_mul_f32_e32 v126, 0xbfb8aa3b, v127
	v_exp_f32_e32 v126, v126
	v_mul_f32_e32 v152, 0xbfb8aa3b, v123
	v_exp_f32_e32 v152, v152
	v_mul_f32_e32 v122, v122, v153
	v_mul_f32_e32 v122, v122, v114
	v_add_f32_e32 v114, 1.0, v126
	v_rcp_f32_e32 v114, v114
	v_add_f32_e32 v126, 1.0, v152
	v_mul_f32_e32 v152, 0xbfb8aa3b, v128
	v_rcp_f32_e32 v126, v126
	v_exp_f32_e32 v152, v152
	v_mul_f32_e32 v114, v127, v114
	v_mul_f32_e32 v119, v114, v119
	v_mul_f32_e32 v114, v123, v126
	v_add_f32_e32 v123, 1.0, v152
	v_rcp_f32_e32 v123, v123
	v_mul_f32_e32 v126, 0xbfb8aa3b, v124
	v_exp_f32_e32 v126, v126
	v_mul_f32_e32 v127, v114, v115
	v_mul_f32_e32 v114, v128, v123
	v_mul_f32_e32 v115, 0xbfb8aa3b, v129
	v_mul_f32_e32 v123, v114, v120
	v_exp_f32_e32 v115, v115
	v_mul_f32_e32 v120, 0xbfb8aa3b, v125
	v_exp_f32_e32 v120, v120
	v_add_f32_e32 v114, 1.0, v126
	v_rcp_f32_e32 v114, v114
	v_add_f32_e32 v115, 1.0, v115
	v_rcp_f32_e32 v115, v115
	v_add_f32_e32 v120, 1.0, v120
	v_rcp_f32_e32 v120, v120
	v_mul_f32_e32 v114, v124, v114
	v_mul_f32_e32 v124, v114, v116
	v_mul_f32_e32 v114, v129, v115
	v_ashrrev_i32_e32 v149, 31, v148
	v_mov_b64_e32 v[134:135], s[72:73]
	v_mul_f32_e32 v126, v114, v121
	v_mul_f32_e32 v114, v125, v120
	v_mad_i64_i32 v[150:151], s[62:63], v147, s90, v[134:135]
	v_mul_f32_e32 v125, v114, v117
	v_lshlrev_b64 v[114:115], 1, v[148:149]
	v_lshl_add_u64 v[120:121], v[150:151], 0, v[114:115]
	v_cvt_pk_bf16_f32 v116, v118, v119
	v_cvt_pk_bf16_f32 v117, v123, v126
	v_cvt_pk_bf16_f32 v118, v122, v127
	v_cvt_pk_bf16_f32 v119, v124, v125
	global_store_dwordx4 v[120:121], v[116:119], off
	s_and_b64 vcc, exec, s[0:1]
	s_mov_b32 s91, s10
	v_mul_f32_e32 v116, 0xbfb8aa3b, v110
	v_exp_f32_e32 v116, v116
	v_mul_f32_e32 v117, 0xbfb8aa3b, v106
	v_exp_f32_e32 v117, v117
	v_or_b32_e32 v118, 16, v147
	v_add_f32_e32 v116, 1.0, v116
	v_rcp_f32_e32 v119, v116
	v_add_f32_e32 v116, 1.0, v117
	v_rcp_f32_e32 v120, v116
	v_mad_i64_i32 v[116:117], s[62:63], v118, s90, v[134:135]
	v_mul_f32_e32 v110, v110, v119
	v_mul_f32_e32 v110, v110, v102
	v_mul_f32_e32 v102, v106, v120
	v_mul_f32_e32 v106, 0xbfb8aa3b, v111
	v_exp_f32_e32 v106, v106
	v_mul_f32_e32 v118, 0xbfb8aa3b, v107
	v_mul_f32_e32 v119, v102, v98
	v_exp_f32_e32 v118, v118
	v_add_f32_e32 v98, 1.0, v106
	v_rcp_f32_e32 v98, v98
	v_mul_f32_e32 v106, 0xbfb8aa3b, v112
	v_exp_f32_e32 v106, v106
	v_add_f32_e32 v102, 1.0, v118
	v_mul_f32_e32 v98, v111, v98
	v_rcp_f32_e32 v102, v102
	v_mul_f32_e32 v98, v98, v103
	v_add_f32_e32 v103, 1.0, v106
	v_rcp_f32_e32 v103, v103
	v_mul_f32_e32 v102, v107, v102
	v_mul_f32_e32 v106, 0xbfb8aa3b, v108
	v_mul_f32_e32 v107, v102, v99
	v_mul_f32_e32 v99, v112, v103
	v_exp_f32_e32 v106, v106
	v_mul_f32_e32 v99, v99, v104
	v_mul_f32_e32 v103, 0xbfb8aa3b, v113
	v_mul_f32_e32 v104, 0xbfb8aa3b, v109
	v_exp_f32_e32 v103, v103
	v_exp_f32_e32 v104, v104
	v_add_f32_e32 v102, 1.0, v106
	v_rcp_f32_e32 v102, v102
	v_add_f32_e32 v103, 1.0, v103
	v_add_f32_e32 v104, 1.0, v104
	v_rcp_f32_e32 v103, v103
	v_rcp_f32_e32 v104, v104
	v_mul_f32_e32 v102, v108, v102
	v_mul_f32_e32 v106, v102, v100
	v_mul_f32_e32 v100, v113, v103
	v_mul_f32_e32 v102, v109, v104
	v_mul_f32_e32 v100, v100, v105
	v_mul_f32_e32 v101, v102, v101
	v_lshl_add_u64 v[102:103], v[116:117], 0, v[114:115]
	v_cvt_pk_bf16_f32 v98, v110, v98
	v_cvt_pk_bf16_f32 v99, v99, v100
	v_cvt_pk_bf16_f32 v100, v119, v107
	v_cvt_pk_bf16_f32 v101, v106, v101
	global_store_dwordx4 v[102:103], v[98:101], off
	s_mov_b32 s82, s12
	s_mov_b64 s[66:67], s[14:15]
	v_mul_f32_e32 v98, 0xbfb8aa3b, v94
	v_exp_f32_e32 v98, v98
	v_mul_f32_e32 v99, 0xbfb8aa3b, v90
	v_exp_f32_e32 v99, v99
	v_or_b32_e32 v100, 32, v147
	v_add_f32_e32 v98, 1.0, v98
	v_rcp_f32_e32 v101, v98
	v_add_f32_e32 v98, 1.0, v99
	v_rcp_f32_e32 v102, v98
	v_mad_i64_i32 v[98:99], s[62:63], v100, s90, v[134:135]
	v_mul_f32_e32 v94, v94, v101
	v_mul_f32_e32 v94, v94, v86
	v_mul_f32_e32 v86, v90, v102
	v_mul_f32_e32 v90, 0xbfb8aa3b, v95
	v_exp_f32_e32 v90, v90
	v_mul_f32_e32 v100, 0xbfb8aa3b, v91
	v_mul_f32_e32 v101, v86, v82
	v_exp_f32_e32 v100, v100
	v_add_f32_e32 v82, 1.0, v90
	v_rcp_f32_e32 v82, v82
	v_mul_f32_e32 v90, 0xbfb8aa3b, v96
	v_exp_f32_e32 v90, v90
	v_add_f32_e32 v86, 1.0, v100
	v_mul_f32_e32 v82, v95, v82
	v_rcp_f32_e32 v86, v86
	v_mul_f32_e32 v82, v82, v87
	v_add_f32_e32 v87, 1.0, v90
	v_rcp_f32_e32 v87, v87
	v_mul_f32_e32 v86, v91, v86
	v_mul_f32_e32 v90, 0xbfb8aa3b, v92
	v_mul_f32_e32 v91, v86, v83
	v_mul_f32_e32 v83, v96, v87
	v_exp_f32_e32 v90, v90
	v_mul_f32_e32 v83, v83, v88
	v_mul_f32_e32 v87, 0xbfb8aa3b, v97
	v_mul_f32_e32 v88, 0xbfb8aa3b, v93
	v_exp_f32_e32 v87, v87
	v_exp_f32_e32 v88, v88
	v_add_f32_e32 v86, 1.0, v90
	v_rcp_f32_e32 v86, v86
	v_add_f32_e32 v87, 1.0, v87
	v_add_f32_e32 v88, 1.0, v88
	v_rcp_f32_e32 v87, v87
	v_rcp_f32_e32 v88, v88
	v_mul_f32_e32 v86, v92, v86
	v_mul_f32_e32 v90, v86, v84
	v_mul_f32_e32 v84, v97, v87
	v_mul_f32_e32 v86, v93, v88
	v_mul_f32_e32 v84, v84, v89
	v_mul_f32_e32 v85, v86, v85
	v_lshl_add_u64 v[86:87], v[98:99], 0, v[114:115]
	v_cvt_pk_bf16_f32 v82, v94, v82
; __device__ __forceinline__ unsigned cvt_pk_bf16(float lo, float hi) { unsigned r; asm volatile("v_cvt_pk_bf16_f32 %0, %1, %2" : "=v"(r) : "v"(lo), "v"(hi)); return r; }
; __device__ __forceinline__ float silu_f(float x) { return x * sigmoid_f(x); }
;     __device__ __forceinline__ void operator()(const f32x4 (&acc)[2][2][4][2], const Unit& u, int wr, int wc, int fr, int fq) const {
;     ...
;         for (int ai = 0; ai < 2; ++ai)
; #pragma unroll
;             for (int m = 0; m < 4; ++m) { bf16_t* rowp = O + (size_t)(row0 + ai * HALF + m * 16) * ldc + col0;
;                 const f32x4 g0 = acc[ai][0][m][0], g1 = acc[ai][0][m][1], u0 = acc[ai][1][m][0], u1 = acc[ai][1][m][1];
;                 f32x4 v0, v1;
; #pragma unroll
;                 for (int j = 0; j < 4; ++j) { v0[j] = silu_f(g0[j]) * u0[j]; v1[j] = silu_f(g1[j]) * u1[j]; }
;                 u32x4 w; w.x = cvt_pk_bf16(v0[0], v0[1]); w.y = cvt_pk_bf16(v0[2], v0[3]); w.z = cvt_pk_bf16(v1[0], v1[1]); w.w = cvt_pk_bf16(v1[2], v1[3]);
;                 *(u32x4*)rowp = w; }
	v_cvt_pk_bf16_f32 v83, v83, v84
	v_cvt_pk_bf16_f32 v84, v101, v91
	v_cvt_pk_bf16_f32 v85, v90, v85
	global_store_dwordx4 v[86:87], v[82:85], off
	s_nop 1
	v_mul_f32_e32 v82, 0xbfb8aa3b, v78
	v_exp_f32_e32 v82, v82
	v_mul_f32_e32 v83, 0xbfb8aa3b, v74
	v_exp_f32_e32 v83, v83
	v_or_b32_e32 v84, 48, v147
	v_add_f32_e32 v82, 1.0, v82
	v_rcp_f32_e32 v85, v82
	v_add_f32_e32 v82, 1.0, v83
	v_rcp_f32_e32 v86, v82
	v_mad_i64_i32 v[82:83], s[62:63], v84, s90, v[134:135]
	v_mul_f32_e32 v78, v78, v85
	v_mul_f32_e32 v78, v78, v70
	v_mul_f32_e32 v70, v74, v86
	v_mul_f32_e32 v74, 0xbfb8aa3b, v79
	v_exp_f32_e32 v74, v74
	v_mul_f32_e32 v84, 0xbfb8aa3b, v75
	v_mul_f32_e32 v85, v70, v66
	v_exp_f32_e32 v84, v84
	v_add_f32_e32 v66, 1.0, v74
	v_rcp_f32_e32 v66, v66
	v_mul_f32_e32 v74, 0xbfb8aa3b, v80
	v_exp_f32_e32 v74, v74
	v_add_f32_e32 v70, 1.0, v84
	v_mul_f32_e32 v66, v79, v66
	v_rcp_f32_e32 v70, v70
	v_mul_f32_e32 v66, v66, v71
	v_add_f32_e32 v71, 1.0, v74
	v_rcp_f32_e32 v71, v71
	v_mul_f32_e32 v70, v75, v70
	v_mul_f32_e32 v74, 0xbfb8aa3b, v76
	v_mul_f32_e32 v75, v70, v67
	v_mul_f32_e32 v67, v80, v71
	v_exp_f32_e32 v74, v74
	v_mul_f32_e32 v67, v67, v72
	v_mul_f32_e32 v71, 0xbfb8aa3b, v81
	v_mul_f32_e32 v72, 0xbfb8aa3b, v77
	v_exp_f32_e32 v71, v71
	v_exp_f32_e32 v72, v72
	v_add_f32_e32 v70, 1.0, v74
	v_rcp_f32_e32 v70, v70
	v_add_f32_e32 v71, 1.0, v71
	v_add_f32_e32 v72, 1.0, v72
	v_rcp_f32_e32 v71, v71
	v_rcp_f32_e32 v72, v72
	v_mul_f32_e32 v70, v76, v70
	v_mul_f32_e32 v74, v70, v68
	v_mul_f32_e32 v68, v81, v71
	v_mul_f32_e32 v70, v77, v72
	v_mul_f32_e32 v68, v68, v73
	v_mul_f32_e32 v69, v70, v69
	v_lshl_add_u64 v[70:71], v[82:83], 0, v[114:115]
	v_cvt_pk_bf16_f32 v66, v78, v66
	v_cvt_pk_bf16_f32 v67, v67, v68
	v_cvt_pk_bf16_f32 v68, v85, v75
	v_cvt_pk_bf16_f32 v69, v74, v69
	global_store_dwordx4 v[70:71], v[66:69], off
	s_nop 1
	v_mul_f32_e32 v66, 0xbfb8aa3b, v62
	v_exp_f32_e32 v66, v66
	v_mul_f32_e32 v67, 0xbfb8aa3b, v58
	v_exp_f32_e32 v67, v67
	v_add_u32_e32 v68, 0x80, v147
	v_add_f32_e32 v66, 1.0, v66
	v_rcp_f32_e32 v69, v66
	v_add_f32_e32 v66, 1.0, v67
	v_rcp_f32_e32 v70, v66
	v_mad_i64_i32 v[66:67], s[62:63], v68, s90, v[134:135]
	v_mul_f32_e32 v62, v62, v69
	v_mul_f32_e32 v62, v62, v54
	v_mul_f32_e32 v54, v58, v70
	v_mul_f32_e32 v58, 0xbfb8aa3b, v63
	v_exp_f32_e32 v58, v58
	v_mul_f32_e32 v68, 0xbfb8aa3b, v59
	v_mul_f32_e32 v69, v54, v50
	v_exp_f32_e32 v68, v68
	v_add_f32_e32 v50, 1.0, v58
	v_rcp_f32_e32 v50, v50
	v_mul_f32_e32 v58, 0xbfb8aa3b, v64
	v_exp_f32_e32 v58, v58
	v_add_f32_e32 v54, 1.0, v68
	v_mul_f32_e32 v50, v63, v50
	v_rcp_f32_e32 v54, v54
	v_mul_f32_e32 v50, v50, v55
	v_add_f32_e32 v55, 1.0, v58
	v_rcp_f32_e32 v55, v55
	v_mul_f32_e32 v54, v59, v54
	v_mul_f32_e32 v58, 0xbfb8aa3b, v60
	v_mul_f32_e32 v59, v54, v51
	v_mul_f32_e32 v51, v64, v55
	v_exp_f32_e32 v58, v58
	v_mul_f32_e32 v51, v51, v56
	v_mul_f32_e32 v55, 0xbfb8aa3b, v65
	v_mul_f32_e32 v56, 0xbfb8aa3b, v61
	v_exp_f32_e32 v55, v55
	v_exp_f32_e32 v56, v56
	v_add_f32_e32 v54, 1.0, v58
	v_rcp_f32_e32 v54, v54
	v_add_f32_e32 v55, 1.0, v55
	v_add_f32_e32 v56, 1.0, v56
	v_rcp_f32_e32 v55, v55
	v_rcp_f32_e32 v56, v56
	v_mul_f32_e32 v54, v60, v54
	v_mul_f32_e32 v58, v54, v52
	v_mul_f32_e32 v52, v65, v55
	v_mul_f32_e32 v54, v61, v56
	v_mul_f32_e32 v52, v52, v57
	v_mul_f32_e32 v53, v54, v53
	v_lshl_add_u64 v[54:55], v[66:67], 0, v[114:115]
	v_cvt_pk_bf16_f32 v50, v62, v50
	v_cvt_pk_bf16_f32 v51, v51, v52
	v_cvt_pk_bf16_f32 v52, v69, v59
	v_cvt_pk_bf16_f32 v53, v58, v53
	global_store_dwordx4 v[54:55], v[50:53], off
	s_nop 1
	v_mul_f32_e32 v50, 0xbfb8aa3b, v46
	v_exp_f32_e32 v50, v50
	v_mul_f32_e32 v51, 0xbfb8aa3b, v42
	v_exp_f32_e32 v51, v51
	v_add_u32_e32 v52, 0x90, v147
	v_add_f32_e32 v50, 1.0, v50
	v_rcp_f32_e32 v53, v50
	v_add_f32_e32 v50, 1.0, v51
	v_rcp_f32_e32 v54, v50
	v_mad_i64_i32 v[50:51], s[62:63], v52, s90, v[134:135]
	v_mul_f32_e32 v46, v46, v53
	v_mul_f32_e32 v46, v46, v38
	v_mul_f32_e32 v38, v42, v54
	v_mul_f32_e32 v42, 0xbfb8aa3b, v47
	v_exp_f32_e32 v42, v42
	v_mul_f32_e32 v52, 0xbfb8aa3b, v43
	v_mul_f32_e32 v53, v38, v34
	v_exp_f32_e32 v52, v52
	v_add_f32_e32 v34, 1.0, v42
	v_rcp_f32_e32 v34, v34
	v_mul_f32_e32 v42, 0xbfb8aa3b, v48
	v_exp_f32_e32 v42, v42
	v_add_f32_e32 v38, 1.0, v52
	v_mul_f32_e32 v34, v47, v34
	v_rcp_f32_e32 v38, v38
	v_mul_f32_e32 v34, v34, v39
	v_add_f32_e32 v39, 1.0, v42
; __device__ __forceinline__ unsigned cvt_pk_bf16(float lo, float hi) { unsigned r; asm volatile("v_cvt_pk_bf16_f32 %0, %1, %2" : "=v"(r) : "v"(lo), "v"(hi)); return r; }
; __device__ __forceinline__ float silu_f(float x) { return x * sigmoid_f(x); }
;     __device__ __forceinline__ void operator()(const f32x4 (&acc)[2][2][4][2], const Unit& u, int wr, int wc, int fr, int fq) const {
;     ...
;         for (int ai = 0; ai < 2; ++ai)
; #pragma unroll
;             for (int m = 0; m < 4; ++m) { bf16_t* rowp = O + (size_t)(row0 + ai * HALF + m * 16) * ldc + col0;
;                 const f32x4 g0 = acc[ai][0][m][0], g1 = acc[ai][0][m][1], u0 = acc[ai][1][m][0], u1 = acc[ai][1][m][1];
;                 f32x4 v0, v1;
; #pragma unroll
;                 for (int j = 0; j < 4; ++j) { v0[j] = silu_f(g0[j]) * u0[j]; v1[j] = silu_f(g1[j]) * u1[j]; }
;                 u32x4 w; w.x = cvt_pk_bf16(v0[0], v0[1]); w.y = cvt_pk_bf16(v0[2], v0[3]); w.z = cvt_pk_bf16(v1[0], v1[1]); w.w = cvt_pk_bf16(v1[2], v1[3]);
;                 *(u32x4*)rowp = w; }
	v_rcp_f32_e32 v39, v39
	v_mul_f32_e32 v38, v43, v38
	v_mul_f32_e32 v42, 0xbfb8aa3b, v44
	v_mul_f32_e32 v43, v38, v35
	v_mul_f32_e32 v35, v48, v39
	v_exp_f32_e32 v42, v42
	v_mul_f32_e32 v35, v35, v40
	v_mul_f32_e32 v39, 0xbfb8aa3b, v49
	v_mul_f32_e32 v40, 0xbfb8aa3b, v45
	v_exp_f32_e32 v39, v39
	v_exp_f32_e32 v40, v40
	v_add_f32_e32 v38, 1.0, v42
	v_rcp_f32_e32 v38, v38
	v_add_f32_e32 v39, 1.0, v39
	v_add_f32_e32 v40, 1.0, v40
	v_rcp_f32_e32 v39, v39
	v_rcp_f32_e32 v40, v40
	v_mul_f32_e32 v38, v44, v38
	v_mul_f32_e32 v42, v38, v36
	v_mul_f32_e32 v36, v49, v39
	v_mul_f32_e32 v38, v45, v40
	v_mul_f32_e32 v36, v36, v41
	v_mul_f32_e32 v37, v38, v37
	v_lshl_add_u64 v[38:39], v[50:51], 0, v[114:115]
	v_cvt_pk_bf16_f32 v34, v46, v34
	v_cvt_pk_bf16_f32 v35, v35, v36
	v_cvt_pk_bf16_f32 v36, v53, v43
	v_cvt_pk_bf16_f32 v37, v42, v37
	global_store_dwordx4 v[38:39], v[34:37], off
	s_nop 1
	v_mul_f32_e32 v34, 0xbfb8aa3b, v30
	v_exp_f32_e32 v34, v34
	v_mul_f32_e32 v35, 0xbfb8aa3b, v26
	v_exp_f32_e32 v35, v35
	v_add_u32_e32 v36, 0xa0, v147
	v_add_f32_e32 v34, 1.0, v34
	v_rcp_f32_e32 v37, v34
	v_add_f32_e32 v34, 1.0, v35
	v_rcp_f32_e32 v38, v34
	v_mad_i64_i32 v[34:35], s[62:63], v36, s90, v[134:135]
	v_mul_f32_e32 v30, v30, v37
	v_mul_f32_e32 v30, v30, v22
	v_mul_f32_e32 v22, v26, v38
	v_mul_f32_e32 v26, 0xbfb8aa3b, v31
	v_exp_f32_e32 v26, v26
	v_mul_f32_e32 v36, 0xbfb8aa3b, v27
	v_mul_f32_e32 v37, v22, v18
	v_exp_f32_e32 v36, v36
	v_add_f32_e32 v18, 1.0, v26
	v_rcp_f32_e32 v18, v18
	v_mul_f32_e32 v26, 0xbfb8aa3b, v32
	v_exp_f32_e32 v26, v26
	v_add_f32_e32 v22, 1.0, v36
	v_mul_f32_e32 v18, v31, v18
	v_rcp_f32_e32 v22, v22
	v_mul_f32_e32 v18, v18, v23
	v_add_f32_e32 v23, 1.0, v26
	v_rcp_f32_e32 v23, v23
	v_mul_f32_e32 v22, v27, v22
	v_mul_f32_e32 v26, 0xbfb8aa3b, v28
	v_mul_f32_e32 v27, v22, v19
	v_mul_f32_e32 v19, v32, v23
	v_exp_f32_e32 v26, v26
	v_mul_f32_e32 v19, v19, v24
	v_mul_f32_e32 v23, 0xbfb8aa3b, v33
	v_mul_f32_e32 v24, 0xbfb8aa3b, v29
	v_exp_f32_e32 v23, v23
	v_exp_f32_e32 v24, v24
	v_add_f32_e32 v22, 1.0, v26
	v_rcp_f32_e32 v22, v22
	v_add_f32_e32 v23, 1.0, v23
	v_add_f32_e32 v24, 1.0, v24
	v_rcp_f32_e32 v23, v23
	v_rcp_f32_e32 v24, v24
	v_mul_f32_e32 v22, v28, v22
	v_mul_f32_e32 v26, v22, v20
	v_mul_f32_e32 v20, v33, v23
	v_mul_f32_e32 v22, v29, v24
	v_mul_f32_e32 v20, v20, v25
	v_mul_f32_e32 v21, v22, v21
	v_lshl_add_u64 v[22:23], v[34:35], 0, v[114:115]
	v_cvt_pk_bf16_f32 v18, v30, v18
	v_cvt_pk_bf16_f32 v19, v19, v20
	v_cvt_pk_bf16_f32 v20, v37, v27
	v_cvt_pk_bf16_f32 v21, v26, v21
	global_store_dwordx4 v[22:23], v[18:21], off
	s_nop 1
	v_mul_f32_e32 v18, 0xbfb8aa3b, v14
	v_exp_f32_e32 v18, v18
	v_mul_f32_e32 v19, 0xbfb8aa3b, v10
	v_exp_f32_e32 v19, v19
	v_add_u32_e32 v20, 0xb0, v147
	v_add_f32_e32 v18, 1.0, v18
	v_rcp_f32_e32 v21, v18
	v_add_f32_e32 v18, 1.0, v19
	v_rcp_f32_e32 v22, v18
	v_mad_i64_i32 v[18:19], s[62:63], v20, s90, v[134:135]
	v_mul_f32_e32 v14, v14, v21
	v_mul_f32_e32 v14, v14, v6
	v_mul_f32_e32 v6, v10, v22
	v_mul_f32_e32 v10, 0xbfb8aa3b, v15
	v_exp_f32_e32 v10, v10
	v_mul_f32_e32 v20, 0xbfb8aa3b, v11
	v_mul_f32_e32 v21, v6, v2
	v_exp_f32_e32 v20, v20
	v_add_f32_e32 v2, 1.0, v10
	v_rcp_f32_e32 v2, v2
	v_mul_f32_e32 v10, 0xbfb8aa3b, v16
	v_exp_f32_e32 v10, v10
	v_add_f32_e32 v6, 1.0, v20
	v_mul_f32_e32 v2, v15, v2
	v_rcp_f32_e32 v6, v6
	v_mul_f32_e32 v2, v2, v7
	v_add_f32_e32 v7, 1.0, v10
	v_rcp_f32_e32 v7, v7
	v_mul_f32_e32 v6, v11, v6
	v_mul_f32_e32 v10, 0xbfb8aa3b, v12
	v_mul_f32_e32 v11, v6, v3
	v_mul_f32_e32 v3, v16, v7
	v_exp_f32_e32 v10, v10
	v_mul_f32_e32 v3, v3, v8
	v_mul_f32_e32 v7, 0xbfb8aa3b, v17
	v_mul_f32_e32 v8, 0xbfb8aa3b, v13
	v_exp_f32_e32 v7, v7
	v_exp_f32_e32 v8, v8
	v_add_f32_e32 v6, 1.0, v10
	v_rcp_f32_e32 v6, v6
	v_add_f32_e32 v7, 1.0, v7
	v_add_f32_e32 v8, 1.0, v8
	v_rcp_f32_e32 v7, v7
	v_rcp_f32_e32 v8, v8
	v_mul_f32_e32 v6, v12, v6
	v_mul_f32_e32 v10, v6, v4
	v_mul_f32_e32 v4, v17, v7
	v_mul_f32_e32 v6, v13, v8
	v_mul_f32_e32 v4, v4, v9
	v_mul_f32_e32 v5, v6, v5
	v_lshl_add_u64 v[6:7], v[18:19], 0, v[114:115]
	s_mov_b64 s[62:63], s[16:17]
	v_cvt_pk_bf16_f32 v2, v14, v2
	v_cvt_pk_bf16_f32 v3, v3, v4
	v_cvt_pk_bf16_f32 v4, v21, v11
	v_cvt_pk_bf16_f32 v5, v10, v5
	global_store_dwordx4 v[6:7], v[2:5], off
	s_cbranch_vccz .LBB0_135
	s_waitcnt vmcnt(0)
	s_cmpk_gt_u32 s3, 0xff
	s_cbranch_scc1 .LBB0_142
	s_barrier

; #define PG8_STAGE(bufoff, gbase, voff) do { _Pragma("unroll") for (int _i = 0; _i < 2; ++_i) \
;         asm volatile("s_mov_b32 m0, %2\n\ts_nop 0\n\tglobal_load_lds_dwordx4 %0, %1" :: "v"((voff)[_i]), "s"((const char*)(gbase)), "s"(ldsbase + (unsigned)(bufoff) + ldsw + (unsigned)_i * 8192u) : "memory", "m0"); } while (0)
; #define PG8_LDA(dst, b, h) do { _Pragma("unroll") for (int m = 0; m < 4; ++m) _Pragma("unroll") for (int k = 0; k < 2; ++k) dst[m][k] = *(const PG8_LAS bf16x8*)(lds + PG8_SA(b, h) + aoff + m * 2048 + k * 1024); } while (0)
; #define PG8_LDB(dst, b, h) do { _Pragma("unroll") for (int n = 0; n < 2; ++n) _Pragma("unroll") for (int k = 0; k < 2; ++k) dst[n][k] = *(const PG8_LAS bf16x8*)(lds + PG8_SB(b, h) + boff + n * 2048 + k * 1024); } while (0)
; #define PG8_MMA(ai, bj, At, Bt) do { __builtin_amdgcn_s_setprio(1); _Pragma("unroll") for (int m = 0; m < 4; ++m) _Pragma("unroll") for (int n = 0; n < 2; ++n) _Pragma("unroll") for (int k = 0; k < 2; ++k) \
;         acc[ai][bj][m][n] = __builtin_amdgcn_mfma_f32_16x16x32_bf16(Bt[n][k], At[m][k], acc[ai][bj][m][n], 0, 0, 0); __builtin_amdgcn_s_setprio(0); } while (0)
; template <class Epi, class Sched, bool ALIGN_EPI = false, bool SP2 = false>
; __device__ __forceinline__ void gemm_phase(PG8_LAS unsigned char* lds, const Gemm g, const Sched& S, const Epi& E) {
;     ...
;             PG8_LDB(B0, 0, 0); PG8_LDB(B1, 0, 1); PG8_SCHED; PG8_LDA(At, 0, 0); PG8_STAGE(PG8_SA(1, 1), a1 + hstep, voffA);
;             PG8_WAIT_V(8); PG8_WAIT_L(0); PG8_BAR; PG8_MMA(0, 0, At, B0); PG8_MMA(0, 1, At, B1); PG8_BAR; PG8_SCHED;
;             PG8_LDA(At, 0, 1); PG8_STAGE(PG8_SB(0, 0), b2, voffB); PG8_STAGE(PG8_SB(0, 1), b2 + hstep, voffB); PG8_STAGE(PG8_SA(0, 0), a2, voffA);
;             PG8_WAIT_V(8); PG8_WAIT_L(0); PG8_BAR; PG8_MMA(1, 0, At, B0); PG8_MMA(1, 1, At, B1); PG8_BAR; PG8_SCHED;
;             PG8_LDB(B0, 1, 0); PG8_LDB(B1, 1, 1); PG8_SCHED; PG8_LDA(At, 1, 0); PG8_STAGE(PG8_SA(0, 1), a2 + hstep, voffA);
;             PG8_WAIT_V(8); PG8_WAIT_L(0); PG8_BAR; PG8_MMA(0, 0, At, B0); PG8_MMA(0, 1, At, B1); PG8_BAR; PG8_SCHED;
;             PG8_LDA(At, 1, 1); PG8_STAGE(PG8_SB(1, 0), b3, voffB); PG8_STAGE(PG8_SB(1, 1), b3 + hstep, voffB); PG8_STAGE(PG8_SA(1, 0), a3, voffA);
;             PG8_WAIT_V(8); PG8_WAIT_L(0); PG8_BAR; PG8_MMA(1, 0, At, B0); PG8_MMA(1, 1, At, B1); PG8_BAR; PG8_SCHED;
.LBB0_234:
	ds_read_b128 v[134:137], v145
	ds_read_b128 v[152:155], v145 offset:1024
	ds_read_b128 v[156:159], v145 offset:2048
	ds_read_b128 v[160:163], v145 offset:3072
	ds_read_b128 v[164:167], v146
	ds_read_b128 v[168:171], v146 offset:1024
	ds_read_b128 v[172:175], v146 offset:2048
	ds_read_b128 v[176:179], v146 offset:3072
	s_cmpk_eq_i32 s57, 0xa8
	s_cselect_b32 s76, s4, s53
	s_cselect_b32 s77, s5, s54
	s_cselect_b32 s66, s46, s55
	s_cselect_b32 s67, s47, s56
	s_add_u32 s62, s76, 0x80
	s_addc_u32 s63, s77, 0
	ds_read_b128 v[180:183], v147
	ds_read_b128 v[184:187], v147 offset:1024
	ds_read_b128 v[188:191], v147 offset:2048
	ds_read_b128 v[192:195], v147 offset:3072
	ds_read_b128 v[196:199], v147 offset:4096
	ds_read_b128 v[200:203], v147 offset:5120
	ds_read_b128 v[204:207], v147 offset:6144
	ds_read_b128 v[208:211], v147 offset:7168
	s_mov_b32 m0, s94
	s_nop 0
	global_load_lds_dwordx4 v1, s[50:51]
	s_nop 0
	s_mov_b32 m0, s95
	s_nop 0
	global_load_lds_dwordx4 v141, s[50:51]
	s_waitcnt vmcnt(8)
	s_waitcnt lgkmcnt(0)
	s_barrier
	s_setprio 1
	s_waitcnt lgkmcnt(7)
	v_mfma_f32_16x16x32_bf16 v[126:129], v[134:137], v[180:183], v[126:129]
	v_mfma_f32_16x16x32_bf16 v[126:129], v[152:155], v[184:187], v[126:129]
	v_mfma_f32_16x16x32_bf16 v[122:125], v[160:163], v[184:187], v[122:125]
	v_mfma_f32_16x16x32_bf16 v[122:125], v[156:159], v[180:183], v[122:125]
	v_mfma_f32_16x16x32_bf16 v[118:121], v[164:167], v[180:183], v[118:121]
	v_mfma_f32_16x16x32_bf16 v[118:121], v[168:171], v[184:187], v[118:121]
	v_mfma_f32_16x16x32_bf16 v[114:117], v[176:179], v[184:187], v[114:117]
	v_mfma_f32_16x16x32_bf16 v[114:117], v[172:175], v[180:183], v[114:117]
	v_mfma_f32_16x16x32_bf16 v[98:101], v[172:175], v[188:191], v[98:101]
	v_mfma_f32_16x16x32_bf16 v[98:101], v[176:179], v[192:195], v[98:101]
	v_mfma_f32_16x16x32_bf16 v[102:105], v[168:171], v[192:195], v[102:105]
	v_mfma_f32_16x16x32_bf16 v[102:105], v[164:167], v[188:191], v[102:105]
	v_mfma_f32_16x16x32_bf16 v[106:109], v[156:159], v[188:191], v[106:109]
	v_mfma_f32_16x16x32_bf16 v[106:109], v[160:163], v[192:195], v[106:109]
	v_mfma_f32_16x16x32_bf16 v[110:113], v[152:155], v[192:195], v[110:113]
	v_mfma_f32_16x16x32_bf16 v[110:113], v[134:137], v[188:191], v[110:113]
	v_mfma_f32_16x16x32_bf16 v[94:97], v[134:137], v[196:199], v[94:97]
	v_mfma_f32_16x16x32_bf16 v[94:97], v[152:155], v[200:203], v[94:97]
	v_mfma_f32_16x16x32_bf16 v[90:93], v[160:163], v[200:203], v[90:93]
	v_mfma_f32_16x16x32_bf16 v[90:93], v[156:159], v[196:199], v[90:93]
	v_mfma_f32_16x16x32_bf16 v[86:89], v[164:167], v[196:199], v[86:89]
	v_mfma_f32_16x16x32_bf16 v[86:89], v[168:171], v[200:203], v[86:89]
	v_mfma_f32_16x16x32_bf16 v[82:85], v[176:179], v[200:203], v[82:85]
	v_mfma_f32_16x16x32_bf16 v[82:85], v[172:175], v[196:199], v[82:85]
	v_mfma_f32_16x16x32_bf16 v[66:69], v[172:175], v[204:207], v[66:69]
	v_mfma_f32_16x16x32_bf16 v[66:69], v[176:179], v[208:211], v[66:69]
	v_mfma_f32_16x16x32_bf16 v[70:73], v[168:171], v[208:211], v[70:73]
	v_mfma_f32_16x16x32_bf16 v[70:73], v[164:167], v[204:207], v[70:73]
	v_mfma_f32_16x16x32_bf16 v[74:77], v[156:159], v[204:207], v[74:77]
	v_mfma_f32_16x16x32_bf16 v[74:77], v[160:163], v[208:211], v[74:77]
	v_mfma_f32_16x16x32_bf16 v[78:81], v[152:155], v[208:211], v[78:81]
	s_setprio 2
	s_barrier
	v_mfma_f32_16x16x32_bf16 v[78:81], v[134:137], v[204:207], v[78:81]
	s_setprio 0
	ds_read_b128 v[180:183], v147 offset:16384
	ds_read_b128 v[184:187], v147 offset:17408
	ds_read_b128 v[188:191], v147 offset:18432
	ds_read_b128 v[192:195], v147 offset:19456
	ds_read_b128 v[196:199], v147 offset:20480
	ds_read_b128 v[200:203], v147 offset:21504
	ds_read_b128 v[252:255], v147 offset:22528
	ds_read_b128 v[208:211], v147 offset:23552
	s_mov_b32 m0, s64
	s_nop 0
	global_load_lds_dwordx4 v140, s[66:67]
	s_add_u32 s58, s66, 0x2b0000
	s_mov_b32 m0, s65
	s_nop 0
	global_load_lds_dwordx4 v142, s[66:67]
	s_addc_u32 s59, s67, 0
	s_mov_b32 m0, s82
	s_nop 0
	global_load_lds_dwordx4 v140, s[58:59]
	s_nop 0
	s_mov_b32 m0, s83
	s_nop 0
	global_load_lds_dwordx4 v142, s[58:59]
	s_nop 0
	s_mov_b32 m0, s35
	s_nop 0
	global_load_lds_dwordx4 v1, s[76:77]
	s_nop 0
	s_mov_b32 m0, s84
	s_nop 0
	global_load_lds_dwordx4 v141, s[76:77]
	s_waitcnt vmcnt(8)
	s_waitcnt lgkmcnt(0)
	s_barrier
	s_setprio 1
	s_waitcnt lgkmcnt(7)
	v_mfma_f32_16x16x32_bf16 v[62:65], v[134:137], v[180:183], v[62:65]
	v_mfma_f32_16x16x32_bf16 v[62:65], v[152:155], v[184:187], v[62:65]
	v_mfma_f32_16x16x32_bf16 v[58:61], v[160:163], v[184:187], v[58:61]
	v_mfma_f32_16x16x32_bf16 v[58:61], v[156:159], v[180:183], v[58:61]
	v_mfma_f32_16x16x32_bf16 v[54:57], v[164:167], v[180:183], v[54:57]
	v_mfma_f32_16x16x32_bf16 v[54:57], v[168:171], v[184:187], v[54:57]
	v_mfma_f32_16x16x32_bf16 v[50:53], v[176:179], v[184:187], v[50:53]
	v_mfma_f32_16x16x32_bf16 v[50:53], v[172:175], v[180:183], v[50:53]
	v_mfma_f32_16x16x32_bf16 v[34:37], v[172:175], v[188:191], v[34:37]
	v_mfma_f32_16x16x32_bf16 v[34:37], v[176:179], v[192:195], v[34:37]
	v_mfma_f32_16x16x32_bf16 v[38:41], v[168:171], v[192:195], v[38:41]
	v_mfma_f32_16x16x32_bf16 v[38:41], v[164:167], v[188:191], v[38:41]
	v_mfma_f32_16x16x32_bf16 v[42:45], v[156:159], v[188:191], v[42:45]
	v_mfma_f32_16x16x32_bf16 v[42:45], v[160:163], v[192:195], v[42:45]
	v_mfma_f32_16x16x32_bf16 v[46:49], v[152:155], v[192:195], v[46:49]
	v_mfma_f32_16x16x32_bf16 v[46:49], v[134:137], v[188:191], v[46:49]
	v_mfma_f32_16x16x32_bf16 v[30:33], v[134:137], v[196:199], v[30:33]
	v_mfma_f32_16x16x32_bf16 v[30:33], v[152:155], v[200:203], v[30:33]
	v_mfma_f32_16x16x32_bf16 v[26:29], v[160:163], v[200:203], v[26:29]
	v_mfma_f32_16x16x32_bf16 v[26:29], v[156:159], v[196:199], v[26:29]
	v_mfma_f32_16x16x32_bf16 v[22:25], v[164:167], v[196:199], v[22:25]
	v_mfma_f32_16x16x32_bf16 v[22:25], v[168:171], v[200:203], v[22:25]
	v_mfma_f32_16x16x32_bf16 v[18:21], v[176:179], v[200:203], v[18:21]
	v_mfma_f32_16x16x32_bf16 v[18:21], v[172:175], v[196:199], v[18:21]
	v_mfma_f32_16x16x32_bf16 v[2:5], v[172:175], v[252:255], v[2:5]
	v_mfma_f32_16x16x32_bf16 v[2:5], v[176:179], v[208:211], v[2:5]
	v_mfma_f32_16x16x32_bf16 v[6:9], v[168:171], v[208:211], v[6:9]
	v_mfma_f32_16x16x32_bf16 v[6:9], v[164:167], v[252:255], v[6:9]
	v_mfma_f32_16x16x32_bf16 v[10:13], v[156:159], v[252:255], v[10:13]
	v_mfma_f32_16x16x32_bf16 v[10:13], v[160:163], v[208:211], v[10:13]
	v_mfma_f32_16x16x32_bf16 v[14:17], v[152:155], v[208:211], v[14:17]
	s_setprio 2
	s_barrier
; #define PG8_STAGE(bufoff, gbase, voff) do { _Pragma("unroll") for (int _i = 0; _i < 2; ++_i) \
;         asm volatile("s_mov_b32 m0, %2\n\ts_nop 0\n\tglobal_load_lds_dwordx4 %0, %1" :: "v"((voff)[_i]), "s"((const char*)(gbase)), "s"(ldsbase + (unsigned)(bufoff) + ldsw + (unsigned)_i * 8192u) : "memory", "m0"); } while (0)
; #define PG8_LDA(dst, b, h) do { _Pragma("unroll") for (int m = 0; m < 4; ++m) _Pragma("unroll") for (int k = 0; k < 2; ++k) dst[m][k] = *(const PG8_LAS bf16x8*)(lds + PG8_SA(b, h) + aoff + m * 2048 + k * 1024); } while (0)
; #define PG8_LDB(dst, b, h) do { _Pragma("unroll") for (int n = 0; n < 2; ++n) _Pragma("unroll") for (int k = 0; k < 2; ++k) dst[n][k] = *(const PG8_LAS bf16x8*)(lds + PG8_SB(b, h) + boff + n * 2048 + k * 1024); } while (0)
; #define PG8_MMA(ai, bj, At, Bt) do { __builtin_amdgcn_s_setprio(1); _Pragma("unroll") for (int m = 0; m < 4; ++m) _Pragma("unroll") for (int n = 0; n < 2; ++n) _Pragma("unroll") for (int k = 0; k < 2; ++k) \
;         acc[ai][bj][m][n] = __builtin_amdgcn_mfma_f32_16x16x32_bf16(Bt[n][k], At[m][k], acc[ai][bj][m][n], 0, 0, 0); __builtin_amdgcn_s_setprio(0); } while (0)
; #define PG8_WAIT_V(n) asm volatile("s_waitcnt vmcnt(" #n ")" ::: "memory")
; #define PG8_WAIT_L(n) asm volatile("s_waitcnt lgkmcnt(" #n ")" ::: "memory")
; #define PG8_BAR __builtin_amdgcn_s_barrier()
; #define PG8_SCHED __builtin_amdgcn_sched_barrier(0)
; template <class Epi, class Sched, bool ALIGN_EPI = false, bool SP2 = false>
; __device__ __forceinline__ void gemm_phase(PG8_LAS unsigned char* lds, const Gemm g, const Sched& S, const Epi& E) {
;     ...
;         for (int t = 0; t < nt; t += 2) {
;             const bool last = (t == nt - 2);
;     ...
;             PG8_LDB(B0, 1, 0); PG8_LDB(B1, 1, 1); PG8_SCHED; PG8_LDA(At, 1, 0); PG8_STAGE(PG8_SA(0, 1), a2 + hstep, voffA);
;             PG8_WAIT_V(8); PG8_WAIT_L(0); PG8_BAR; PG8_MMA(0, 0, At, B0); PG8_MMA(0, 1, At, B1); PG8_BAR; PG8_SCHED;
;             PG8_LDA(At, 1, 1); PG8_STAGE(PG8_SB(1, 0), b3, voffB); PG8_STAGE(PG8_SB(1, 1), b3 + hstep, voffB); PG8_STAGE(PG8_SA(1, 0), a3, voffA);
;             PG8_WAIT_V(8); PG8_WAIT_L(0); PG8_BAR; PG8_MMA(1, 0, At, B0); PG8_MMA(1, 1, At, B1); PG8_BAR; PG8_SCHED;
	v_mfma_f32_16x16x32_bf16 v[14:17], v[134:137], v[252:255], v[14:17]
	s_setprio 0
	ds_read_b128 v[248:251], v148
	ds_read_b128 v[152:155], v148 offset:1024
	ds_read_b128 v[156:159], v148 offset:2048
	ds_read_b128 v[160:163], v148 offset:3072
	ds_read_b128 v[164:167], v149
	ds_read_b128 v[168:171], v149 offset:1024
	ds_read_b128 v[172:175], v149 offset:2048
	ds_read_b128 v[176:179], v149 offset:3072
	ds_read_b128 v[180:183], v147 offset:32768
	ds_read_b128 v[184:187], v147 offset:33792
	ds_read_b128 v[188:191], v147 offset:34816
	ds_read_b128 v[192:195], v147 offset:35840
	ds_read_b128 v[196:199], v147 offset:36864
	ds_read_b128 v[200:203], v147 offset:37888
	ds_read_b128 v[204:207], v147 offset:38912
	ds_read_b128 v[208:211], v147 offset:39936
	s_add_u32 s58, s76, 0x2b0000
	s_addc_u32 s59, s77, 0
	s_mov_b32 m0, s85
	s_nop 0
	global_load_lds_dwordx4 v1, s[58:59]
	s_nop 0
	s_mov_b32 m0, s86
	s_nop 0
	global_load_lds_dwordx4 v141, s[58:59]
	s_waitcnt vmcnt(8)
	s_waitcnt lgkmcnt(0)
	s_barrier
	s_setprio 1
	s_waitcnt lgkmcnt(7)
	v_mfma_f32_16x16x32_bf16 v[126:129], v[248:251], v[180:183], v[126:129]
	v_mfma_f32_16x16x32_bf16 v[126:129], v[152:155], v[184:187], v[126:129]
	v_mfma_f32_16x16x32_bf16 v[122:125], v[160:163], v[184:187], v[122:125]
	v_mfma_f32_16x16x32_bf16 v[122:125], v[156:159], v[180:183], v[122:125]
	v_mfma_f32_16x16x32_bf16 v[118:121], v[164:167], v[180:183], v[118:121]
	v_mfma_f32_16x16x32_bf16 v[118:121], v[168:171], v[184:187], v[118:121]
	v_mfma_f32_16x16x32_bf16 v[114:117], v[176:179], v[184:187], v[114:117]
	v_mfma_f32_16x16x32_bf16 v[114:117], v[172:175], v[180:183], v[114:117]
	v_mfma_f32_16x16x32_bf16 v[98:101], v[172:175], v[188:191], v[98:101]
	v_mfma_f32_16x16x32_bf16 v[98:101], v[176:179], v[192:195], v[98:101]
	v_mfma_f32_16x16x32_bf16 v[102:105], v[168:171], v[192:195], v[102:105]
	v_mfma_f32_16x16x32_bf16 v[102:105], v[164:167], v[188:191], v[102:105]
	v_mfma_f32_16x16x32_bf16 v[106:109], v[156:159], v[188:191], v[106:109]
	v_mfma_f32_16x16x32_bf16 v[106:109], v[160:163], v[192:195], v[106:109]
	v_mfma_f32_16x16x32_bf16 v[110:113], v[152:155], v[192:195], v[110:113]
	v_mfma_f32_16x16x32_bf16 v[110:113], v[248:251], v[188:191], v[110:113]
	v_mfma_f32_16x16x32_bf16 v[94:97], v[248:251], v[196:199], v[94:97]
	v_mfma_f32_16x16x32_bf16 v[94:97], v[152:155], v[200:203], v[94:97]
	v_mfma_f32_16x16x32_bf16 v[90:93], v[160:163], v[200:203], v[90:93]
	v_mfma_f32_16x16x32_bf16 v[90:93], v[156:159], v[196:199], v[90:93]
	v_mfma_f32_16x16x32_bf16 v[86:89], v[164:167], v[196:199], v[86:89]
	v_mfma_f32_16x16x32_bf16 v[86:89], v[168:171], v[200:203], v[86:89]
	v_mfma_f32_16x16x32_bf16 v[82:85], v[176:179], v[200:203], v[82:85]
	v_mfma_f32_16x16x32_bf16 v[82:85], v[172:175], v[196:199], v[82:85]
	v_mfma_f32_16x16x32_bf16 v[66:69], v[172:175], v[204:207], v[66:69]
	v_mfma_f32_16x16x32_bf16 v[66:69], v[176:179], v[208:211], v[66:69]
	v_mfma_f32_16x16x32_bf16 v[70:73], v[168:171], v[208:211], v[70:73]
	v_mfma_f32_16x16x32_bf16 v[70:73], v[164:167], v[204:207], v[70:73]
	v_mfma_f32_16x16x32_bf16 v[74:77], v[156:159], v[204:207], v[74:77]
	v_mfma_f32_16x16x32_bf16 v[74:77], v[160:163], v[208:211], v[74:77]
	v_mfma_f32_16x16x32_bf16 v[78:81], v[152:155], v[208:211], v[78:81]
	s_setprio 2
	s_barrier
	v_mfma_f32_16x16x32_bf16 v[78:81], v[248:251], v[204:207], v[78:81]
	s_setprio 0
	ds_read_b128 v[180:183], v147 offset:49152
	ds_read_b128 v[184:187], v147 offset:50176
	ds_read_b128 v[188:191], v147 offset:51200
	ds_read_b128 v[192:195], v147 offset:52224
	ds_read_b128 v[196:199], v147 offset:53248
	ds_read_b128 v[200:203], v147 offset:54272
	ds_read_b128 v[252:255], v147 offset:55296
	ds_read_b128 v[208:211], v147 offset:56320
	s_add_u32 s58, s66, 0x80
	s_addc_u32 s59, s67, 0
	s_mov_b32 m0, s88
	s_nop 0
	global_load_lds_dwordx4 v140, s[58:59]
	s_nop 0
	s_mov_b32 m0, s89
	s_nop 0
	global_load_lds_dwordx4 v142, s[58:59]
	s_add_u32 s58, s66, 0x2b0080
	s_addc_u32 s59, s67, 0
	s_mov_b32 m0, s92
	s_nop 0
	global_load_lds_dwordx4 v140, s[58:59]
	s_nop 0
	s_mov_b32 m0, s93
	s_nop 0
	global_load_lds_dwordx4 v142, s[58:59]
	s_nop 0
	s_mov_b32 m0, s90
	s_nop 0
	global_load_lds_dwordx4 v1, s[62:63]
	s_nop 0
	s_mov_b32 m0, s91
	s_nop 0
	global_load_lds_dwordx4 v141, s[62:63]
	s_waitcnt vmcnt(8)
	s_waitcnt lgkmcnt(0)
	s_barrier
	s_setprio 1
	s_waitcnt lgkmcnt(7)
	v_mfma_f32_16x16x32_bf16 v[62:65], v[248:251], v[180:183], v[62:65]
	v_mfma_f32_16x16x32_bf16 v[62:65], v[152:155], v[184:187], v[62:65]
	v_mfma_f32_16x16x32_bf16 v[58:61], v[160:163], v[184:187], v[58:61]
	v_mfma_f32_16x16x32_bf16 v[58:61], v[156:159], v[180:183], v[58:61]
	v_mfma_f32_16x16x32_bf16 v[54:57], v[164:167], v[180:183], v[54:57]
	v_mfma_f32_16x16x32_bf16 v[54:57], v[168:171], v[184:187], v[54:57]
	v_mfma_f32_16x16x32_bf16 v[50:53], v[176:179], v[184:187], v[50:53]
	v_mfma_f32_16x16x32_bf16 v[50:53], v[172:175], v[180:183], v[50:53]
	v_mfma_f32_16x16x32_bf16 v[34:37], v[172:175], v[188:191], v[34:37]
	v_mfma_f32_16x16x32_bf16 v[34:37], v[176:179], v[192:195], v[34:37]
	v_mfma_f32_16x16x32_bf16 v[38:41], v[168:171], v[192:195], v[38:41]
	v_mfma_f32_16x16x32_bf16 v[38:41], v[164:167], v[188:191], v[38:41]
	v_mfma_f32_16x16x32_bf16 v[42:45], v[156:159], v[188:191], v[42:45]
	v_mfma_f32_16x16x32_bf16 v[42:45], v[160:163], v[192:195], v[42:45]
	v_mfma_f32_16x16x32_bf16 v[46:49], v[152:155], v[192:195], v[46:49]
	v_mfma_f32_16x16x32_bf16 v[46:49], v[248:251], v[188:191], v[46:49]
	v_mfma_f32_16x16x32_bf16 v[30:33], v[248:251], v[196:199], v[30:33]
	v_mfma_f32_16x16x32_bf16 v[30:33], v[152:155], v[200:203], v[30:33]
	v_mfma_f32_16x16x32_bf16 v[26:29], v[160:163], v[200:203], v[26:29]
	v_mfma_f32_16x16x32_bf16 v[26:29], v[156:159], v[196:199], v[26:29]
	v_mfma_f32_16x16x32_bf16 v[22:25], v[164:167], v[196:199], v[22:25]
	v_mfma_f32_16x16x32_bf16 v[22:25], v[168:171], v[200:203], v[22:25]
	v_mfma_f32_16x16x32_bf16 v[18:21], v[176:179], v[200:203], v[18:21]
	v_mfma_f32_16x16x32_bf16 v[18:21], v[172:175], v[196:199], v[18:21]
	v_mfma_f32_16x16x32_bf16 v[2:5], v[172:175], v[252:255], v[2:5]
	v_mfma_f32_16x16x32_bf16 v[2:5], v[176:179], v[208:211], v[2:5]
	v_mfma_f32_16x16x32_bf16 v[6:9], v[168:171], v[208:211], v[6:9]
	v_mfma_f32_16x16x32_bf16 v[6:9], v[164:167], v[252:255], v[6:9]
	v_mfma_f32_16x16x32_bf16 v[10:13], v[156:159], v[252:255], v[10:13]
	v_mfma_f32_16x16x32_bf16 v[10:13], v[160:163], v[208:211], v[10:13]
	v_mfma_f32_16x16x32_bf16 v[14:17], v[152:155], v[208:211], v[14:17]
	s_setprio 2
	s_barrier
	v_mfma_f32_16x16x32_bf16 v[14:17], v[248:251], v[252:255], v[14:17]
	s_setprio 0
	s_add_i32 s57, s57, 2
	s_add_u32 s53, s53, 0x100
	s_addc_u32 s54, s54, 0
	s_add_u32 s55, s55, 0x100
	s_addc_u32 s56, s56, 0
	s_add_u32 s50, s50, 0x100
	s_addc_u32 s51, s51, 0
	s_cmpk_gt_u32 s57, 0xa9
	s_cbranch_scc0 .LBB0_234
	s_and_b64 vcc, exec, s[16:17]
	s_cbranch_vccz .LBB0_237
	s_barrier

; #define PG8_STAGE(bufoff, gbase, voff) do { _Pragma("unroll") for (int _i = 0; _i < 2; ++_i) \
;         asm volatile("s_mov_b32 m0, %2\n\ts_nop 0\n\tglobal_load_lds_dwordx4 %0, %1" :: "v"((voff)[_i]), "s"((const char*)(gbase)), "s"(ldsbase + (unsigned)(bufoff) + ldsw + (unsigned)_i * 8192u) : "memory", "m0"); } while (0)
; #define PG8_LDA(dst, b, h) do { _Pragma("unroll") for (int m = 0; m < 4; ++m) _Pragma("unroll") for (int k = 0; k < 2; ++k) dst[m][k] = *(const PG8_LAS bf16x8*)(lds + PG8_SA(b, h) + aoff + m * 2048 + k * 1024); } while (0)
; #define PG8_LDB(dst, b, h) do { _Pragma("unroll") for (int n = 0; n < 2; ++n) _Pragma("unroll") for (int k = 0; k < 2; ++k) dst[n][k] = *(const PG8_LAS bf16x8*)(lds + PG8_SB(b, h) + boff + n * 2048 + k * 1024); } while (0)
; #define PG8_MMA(ai, bj, At, Bt) do { __builtin_amdgcn_s_setprio(1); _Pragma("unroll") for (int m = 0; m < 4; ++m) _Pragma("unroll") for (int n = 0; n < 2; ++n) _Pragma("unroll") for (int k = 0; k < 2; ++k) \
;         acc[ai][bj][m][n] = __builtin_amdgcn_mfma_f32_16x16x32_bf16(Bt[n][k], At[m][k], acc[ai][bj][m][n], 0, 0, 0); __builtin_amdgcn_s_setprio(0); } while (0)
; #define PG8_WAIT_V(n) asm volatile("s_waitcnt vmcnt(" #n ")" ::: "memory")
; #define PG8_WAIT_L(n) asm volatile("s_waitcnt lgkmcnt(" #n ")" ::: "memory")
; #define PG8_BAR __builtin_amdgcn_s_barrier()
; #define PG8_SCHED __builtin_amdgcn_sched_barrier(0)
; template <class Epi, class Sched, bool ALIGN_EPI = false, bool SP2 = false>
; __device__ __forceinline__ void gemm_phase(PG8_LAS unsigned char* lds, const Gemm g, const Sched& S, const Epi& E) {
;     ...
;             PG8_LDB(B0, 0, 0); PG8_LDB(B1, 0, 1); PG8_SCHED; PG8_LDA(At, 0, 0); PG8_STAGE(PG8_SA(1, 1), a1 + hstep, voffA);
;             PG8_WAIT_V(8); PG8_WAIT_L(0); PG8_BAR; PG8_MMA(0, 0, At, B0); PG8_MMA(0, 1, At, B1); PG8_BAR; PG8_SCHED;
;             PG8_LDA(At, 0, 1); PG8_STAGE(PG8_SB(0, 0), b2, voffB); PG8_STAGE(PG8_SB(0, 1), b2 + hstep, voffB); PG8_STAGE(PG8_SA(0, 0), a2, voffA);
;             PG8_WAIT_V(8); PG8_WAIT_L(0); PG8_BAR; PG8_MMA(1, 0, At, B0); PG8_MMA(1, 1, At, B1); PG8_BAR; PG8_SCHED;
.LBB0_325:
	v_add_u32_e32 v138, 0x10000, v151
	ds_read_b128 v[154:157], v138
	ds_read_b128 v[158:161], v138 offset:1024
	ds_read_b128 v[162:165], v138 offset:2048
	ds_read_b128 v[166:169], v138 offset:3072
	v_add_u32_e32 v138, 0x14000, v151
	s_add_u32 s8, s82, 0x100
	ds_read_b128 v[170:173], v138
	ds_read_b128 v[174:177], v138 offset:1024
	ds_read_b128 v[178:181], v138 offset:2048
	ds_read_b128 v[182:185], v138 offset:3072
	s_addc_u32 s9, s83, 0
	s_and_b64 s[60:61], s[62:63], exec
	s_cselect_b32 s84, s54, s8
	s_cselect_b32 s85, s19, s9
	s_cselect_b32 s63, s17, s57
	s_cselect_b32 s62, s55, s56
	s_add_u32 s66, s84, 0x80
	s_addc_u32 s67, s85, 0
	s_add_u32 s76, s62, 0x80
	s_addc_u32 s77, s63, 0
	ds_read_b128 v[186:189], v152
	ds_read_b128 v[190:193], v152 offset:1024
	ds_read_b128 v[194:197], v152 offset:2048
	ds_read_b128 v[198:201], v152 offset:3072
	ds_read_b128 v[202:205], v152 offset:4096
	ds_read_b128 v[206:209], v152 offset:5120
	ds_read_b128 v[210:213], v152 offset:6144
	ds_read_b128 v[214:217], v152 offset:7168
	s_add_u32 s60, s82, 0x100080
	s_addc_u32 s61, s83, 0
	s_mov_b32 m0, s97
	s_nop 0
	global_load_lds_dwordx4 v141, s[60:61]
	s_nop 0
	s_mov_b32 m0, s70
	s_nop 0
	global_load_lds_dwordx4 v143, s[60:61]
	s_waitcnt vmcnt(8)
	s_waitcnt lgkmcnt(0)
	s_barrier
	s_setprio 1
	s_waitcnt lgkmcnt(7)
	v_mfma_f32_16x16x32_bf16 v[126:129], v[154:157], v[186:189], v[126:129]
	v_mfma_f32_16x16x32_bf16 v[126:129], v[158:161], v[190:193], v[126:129]
	v_mfma_f32_16x16x32_bf16 v[122:125], v[166:169], v[190:193], v[122:125]
	v_mfma_f32_16x16x32_bf16 v[122:125], v[162:165], v[186:189], v[122:125]
	v_mfma_f32_16x16x32_bf16 v[118:121], v[170:173], v[186:189], v[118:121]
	v_mfma_f32_16x16x32_bf16 v[118:121], v[174:177], v[190:193], v[118:121]
	v_mfma_f32_16x16x32_bf16 v[114:117], v[182:185], v[190:193], v[114:117]
	v_mfma_f32_16x16x32_bf16 v[114:117], v[178:181], v[186:189], v[114:117]
	v_mfma_f32_16x16x32_bf16 v[98:101], v[178:181], v[194:197], v[98:101]
	v_mfma_f32_16x16x32_bf16 v[98:101], v[182:185], v[198:201], v[98:101]
	v_mfma_f32_16x16x32_bf16 v[102:105], v[174:177], v[198:201], v[102:105]
	v_mfma_f32_16x16x32_bf16 v[102:105], v[170:173], v[194:197], v[102:105]
	v_mfma_f32_16x16x32_bf16 v[106:109], v[162:165], v[194:197], v[106:109]
	v_mfma_f32_16x16x32_bf16 v[106:109], v[166:169], v[198:201], v[106:109]
	v_mfma_f32_16x16x32_bf16 v[110:113], v[158:161], v[198:201], v[110:113]
	v_mfma_f32_16x16x32_bf16 v[110:113], v[154:157], v[194:197], v[110:113]
	v_mfma_f32_16x16x32_bf16 v[94:97], v[154:157], v[202:205], v[94:97]
	v_mfma_f32_16x16x32_bf16 v[94:97], v[158:161], v[206:209], v[94:97]
	v_mfma_f32_16x16x32_bf16 v[90:93], v[166:169], v[206:209], v[90:93]
	v_mfma_f32_16x16x32_bf16 v[90:93], v[162:165], v[202:205], v[90:93]
	v_mfma_f32_16x16x32_bf16 v[86:89], v[170:173], v[202:205], v[86:89]
	v_mfma_f32_16x16x32_bf16 v[86:89], v[174:177], v[206:209], v[86:89]
	v_mfma_f32_16x16x32_bf16 v[82:85], v[182:185], v[206:209], v[82:85]
	v_mfma_f32_16x16x32_bf16 v[82:85], v[178:181], v[202:205], v[82:85]
	v_mfma_f32_16x16x32_bf16 v[66:69], v[178:181], v[210:213], v[66:69]
	v_mfma_f32_16x16x32_bf16 v[66:69], v[182:185], v[214:217], v[66:69]
	v_mfma_f32_16x16x32_bf16 v[70:73], v[174:177], v[214:217], v[70:73]
	v_mfma_f32_16x16x32_bf16 v[70:73], v[170:173], v[210:213], v[70:73]
	v_mfma_f32_16x16x32_bf16 v[74:77], v[162:165], v[210:213], v[74:77]
	v_mfma_f32_16x16x32_bf16 v[74:77], v[166:169], v[214:217], v[74:77]
	v_mfma_f32_16x16x32_bf16 v[78:81], v[158:161], v[214:217], v[78:81]
	s_setprio 2
	s_barrier
	v_mfma_f32_16x16x32_bf16 v[78:81], v[154:157], v[210:213], v[78:81]
	s_setprio 0
	ds_read_b128 v[186:189], v152 offset:16384
	ds_read_b128 v[190:193], v152 offset:17408
	ds_read_b128 v[194:197], v152 offset:18432
	ds_read_b128 v[198:201], v152 offset:19456
	ds_read_b128 v[202:205], v152 offset:20480
	ds_read_b128 v[206:209], v152 offset:21504
	ds_read_b128 v[252:255], v152 offset:22528
	ds_read_b128 v[214:217], v152 offset:23552
	s_mov_b32 m0, s68
	s_nop 0
	global_load_lds_dwordx4 v142, s[62:63]
	s_add_u32 s60, s62, 0x100000
	s_mov_b32 m0, s69
	s_nop 0
	global_load_lds_dwordx4 v144, s[62:63]
	s_addc_u32 s61, s63, 0
	s_mov_b32 m0, s81
	s_nop 0
	global_load_lds_dwordx4 v142, s[60:61]
	s_nop 0
	s_mov_b32 m0, s86
	s_nop 0
	global_load_lds_dwordx4 v144, s[60:61]
	s_nop 0
	s_mov_b32 m0, s65
	s_nop 0
	global_load_lds_dwordx4 v141, s[84:85]
	s_nop 0
	s_mov_b32 m0, s87
	s_nop 0
	global_load_lds_dwordx4 v143, s[84:85]
	s_waitcnt vmcnt(8)
	s_waitcnt lgkmcnt(0)
	s_barrier
	s_setprio 1
	s_waitcnt lgkmcnt(7)
	v_mfma_f32_16x16x32_bf16 v[62:65], v[154:157], v[186:189], v[62:65]
	v_mfma_f32_16x16x32_bf16 v[62:65], v[158:161], v[190:193], v[62:65]
	v_mfma_f32_16x16x32_bf16 v[58:61], v[166:169], v[190:193], v[58:61]
	v_mfma_f32_16x16x32_bf16 v[58:61], v[162:165], v[186:189], v[58:61]
	v_mfma_f32_16x16x32_bf16 v[54:57], v[170:173], v[186:189], v[54:57]
	v_mfma_f32_16x16x32_bf16 v[54:57], v[174:177], v[190:193], v[54:57]
	v_mfma_f32_16x16x32_bf16 v[50:53], v[182:185], v[190:193], v[50:53]
	v_mfma_f32_16x16x32_bf16 v[50:53], v[178:181], v[186:189], v[50:53]
	v_mfma_f32_16x16x32_bf16 v[34:37], v[178:181], v[194:197], v[34:37]
	v_mfma_f32_16x16x32_bf16 v[34:37], v[182:185], v[198:201], v[34:37]
	v_mfma_f32_16x16x32_bf16 v[38:41], v[174:177], v[198:201], v[38:41]
	v_mfma_f32_16x16x32_bf16 v[38:41], v[170:173], v[194:197], v[38:41]
	v_mfma_f32_16x16x32_bf16 v[42:45], v[162:165], v[194:197], v[42:45]
	v_mfma_f32_16x16x32_bf16 v[42:45], v[166:169], v[198:201], v[42:45]
	v_mfma_f32_16x16x32_bf16 v[46:49], v[158:161], v[198:201], v[46:49]
	v_mfma_f32_16x16x32_bf16 v[46:49], v[154:157], v[194:197], v[46:49]
	v_mfma_f32_16x16x32_bf16 v[30:33], v[154:157], v[202:205], v[30:33]
	v_mfma_f32_16x16x32_bf16 v[30:33], v[158:161], v[206:209], v[30:33]
	v_mfma_f32_16x16x32_bf16 v[26:29], v[166:169], v[206:209], v[26:29]
	v_mfma_f32_16x16x32_bf16 v[26:29], v[162:165], v[202:205], v[26:29]
	v_mfma_f32_16x16x32_bf16 v[22:25], v[170:173], v[202:205], v[22:25]
	v_mfma_f32_16x16x32_bf16 v[22:25], v[174:177], v[206:209], v[22:25]
	v_mfma_f32_16x16x32_bf16 v[18:21], v[182:185], v[206:209], v[18:21]
	v_mfma_f32_16x16x32_bf16 v[18:21], v[178:181], v[202:205], v[18:21]
	v_mfma_f32_16x16x32_bf16 v[2:5], v[178:181], v[252:255], v[2:5]
	v_mfma_f32_16x16x32_bf16 v[2:5], v[182:185], v[214:217], v[2:5]
	v_mfma_f32_16x16x32_bf16 v[6:9], v[174:177], v[214:217], v[6:9]
	v_mfma_f32_16x16x32_bf16 v[6:9], v[170:173], v[252:255], v[6:9]
	v_mfma_f32_16x16x32_bf16 v[10:13], v[162:165], v[252:255], v[10:13]
	v_mfma_f32_16x16x32_bf16 v[10:13], v[166:169], v[214:217], v[10:13]
	v_mfma_f32_16x16x32_bf16 v[14:17], v[158:161], v[214:217], v[14:17]
	s_setprio 2
	s_barrier
; #define PG8_STAGE(bufoff, gbase, voff) do { _Pragma("unroll") for (int _i = 0; _i < 2; ++_i) \
;         asm volatile("s_mov_b32 m0, %2\n\ts_nop 0\n\tglobal_load_lds_dwordx4 %0, %1" :: "v"((voff)[_i]), "s"((const char*)(gbase)), "s"(ldsbase + (unsigned)(bufoff) + ldsw + (unsigned)_i * 8192u) : "memory", "m0"); } while (0)
; #define PG8_LDA(dst, b, h) do { _Pragma("unroll") for (int m = 0; m < 4; ++m) _Pragma("unroll") for (int k = 0; k < 2; ++k) dst[m][k] = *(const PG8_LAS bf16x8*)(lds + PG8_SA(b, h) + aoff + m * 2048 + k * 1024); } while (0)
; #define PG8_LDB(dst, b, h) do { _Pragma("unroll") for (int n = 0; n < 2; ++n) _Pragma("unroll") for (int k = 0; k < 2; ++k) dst[n][k] = *(const PG8_LAS bf16x8*)(lds + PG8_SB(b, h) + boff + n * 2048 + k * 1024); } while (0)
; #define PG8_MMA(ai, bj, At, Bt) do { __builtin_amdgcn_s_setprio(1); _Pragma("unroll") for (int m = 0; m < 4; ++m) _Pragma("unroll") for (int n = 0; n < 2; ++n) _Pragma("unroll") for (int k = 0; k < 2; ++k) \
;         acc[ai][bj][m][n] = __builtin_amdgcn_mfma_f32_16x16x32_bf16(Bt[n][k], At[m][k], acc[ai][bj][m][n], 0, 0, 0); __builtin_amdgcn_s_setprio(0); } while (0)
; #define PG8_WAIT_V(n) asm volatile("s_waitcnt vmcnt(" #n ")" ::: "memory")
; #define PG8_WAIT_L(n) asm volatile("s_waitcnt lgkmcnt(" #n ")" ::: "memory")
; #define PG8_BAR __builtin_amdgcn_s_barrier()
; #define PG8_SCHED __builtin_amdgcn_sched_barrier(0)
; template <class Epi, class Sched, bool ALIGN_EPI = false, bool SP2 = false>
; __device__ __forceinline__ void gemm_phase(PG8_LAS unsigned char* lds, const Gemm g, const Sched& S, const Epi& E) {
;     ...
;             PG8_LDB(B0, 1, 0); PG8_LDB(B1, 1, 1); PG8_SCHED; PG8_LDA(At, 1, 0); PG8_STAGE(PG8_SA(0, 1), a2 + hstep, voffA);
;             PG8_WAIT_V(8); PG8_WAIT_L(0); PG8_BAR; PG8_MMA(0, 0, At, B0); PG8_MMA(0, 1, At, B1); PG8_BAR; PG8_SCHED;
;             PG8_LDA(At, 1, 1); PG8_STAGE(PG8_SB(1, 0), b3, voffB); PG8_STAGE(PG8_SB(1, 1), b3 + hstep, voffB); PG8_STAGE(PG8_SA(1, 0), a3, voffA);
;             PG8_WAIT_V(8); PG8_WAIT_L(0); PG8_BAR; PG8_MMA(1, 0, At, B0); PG8_MMA(1, 1, At, B1); PG8_BAR; PG8_SCHED;
	v_mfma_f32_16x16x32_bf16 v[14:17], v[154:157], v[252:255], v[14:17]
	s_setprio 0
	v_add_u32_e32 v138, 0x18000, v151
	ds_read_b128 v[248:251], v138
	ds_read_b128 v[158:161], v138 offset:1024
	ds_read_b128 v[162:165], v138 offset:2048
	ds_read_b128 v[166:169], v138 offset:3072
	v_add_u32_e32 v138, 0x1c000, v151
	ds_read_b128 v[170:173], v138
	ds_read_b128 v[174:177], v138 offset:1024
	ds_read_b128 v[178:181], v138 offset:2048
	ds_read_b128 v[182:185], v138 offset:3072
	ds_read_b128 v[186:189], v152 offset:32768
	ds_read_b128 v[190:193], v152 offset:33792
	ds_read_b128 v[194:197], v152 offset:34816
	ds_read_b128 v[198:201], v152 offset:35840
	ds_read_b128 v[202:205], v152 offset:36864
	ds_read_b128 v[206:209], v152 offset:37888
	ds_read_b128 v[210:213], v152 offset:38912
	ds_read_b128 v[214:217], v152 offset:39936
	s_add_u32 s60, s84, 0x100000
	s_addc_u32 s61, s85, 0
	s_mov_b32 m0, s88
	s_nop 0
	global_load_lds_dwordx4 v141, s[60:61]
	s_nop 0
	s_mov_b32 m0, s89
	s_nop 0
	global_load_lds_dwordx4 v143, s[60:61]
	s_waitcnt vmcnt(8)
	s_waitcnt lgkmcnt(0)
	s_barrier
	s_setprio 1
	s_waitcnt lgkmcnt(7)
	v_mfma_f32_16x16x32_bf16 v[126:129], v[248:251], v[186:189], v[126:129]
	v_mfma_f32_16x16x32_bf16 v[126:129], v[158:161], v[190:193], v[126:129]
	v_mfma_f32_16x16x32_bf16 v[122:125], v[166:169], v[190:193], v[122:125]
	v_mfma_f32_16x16x32_bf16 v[122:125], v[162:165], v[186:189], v[122:125]
	v_mfma_f32_16x16x32_bf16 v[118:121], v[170:173], v[186:189], v[118:121]
	v_mfma_f32_16x16x32_bf16 v[118:121], v[174:177], v[190:193], v[118:121]
	v_mfma_f32_16x16x32_bf16 v[114:117], v[182:185], v[190:193], v[114:117]
	v_mfma_f32_16x16x32_bf16 v[114:117], v[178:181], v[186:189], v[114:117]
	v_mfma_f32_16x16x32_bf16 v[98:101], v[178:181], v[194:197], v[98:101]
	v_mfma_f32_16x16x32_bf16 v[98:101], v[182:185], v[198:201], v[98:101]
	v_mfma_f32_16x16x32_bf16 v[102:105], v[174:177], v[198:201], v[102:105]
	v_mfma_f32_16x16x32_bf16 v[102:105], v[170:173], v[194:197], v[102:105]
	v_mfma_f32_16x16x32_bf16 v[106:109], v[162:165], v[194:197], v[106:109]
	v_mfma_f32_16x16x32_bf16 v[106:109], v[166:169], v[198:201], v[106:109]
	v_mfma_f32_16x16x32_bf16 v[110:113], v[158:161], v[198:201], v[110:113]
	v_mfma_f32_16x16x32_bf16 v[110:113], v[248:251], v[194:197], v[110:113]
	v_mfma_f32_16x16x32_bf16 v[94:97], v[248:251], v[202:205], v[94:97]
	v_mfma_f32_16x16x32_bf16 v[94:97], v[158:161], v[206:209], v[94:97]
	v_mfma_f32_16x16x32_bf16 v[90:93], v[166:169], v[206:209], v[90:93]
	v_mfma_f32_16x16x32_bf16 v[90:93], v[162:165], v[202:205], v[90:93]
	v_mfma_f32_16x16x32_bf16 v[86:89], v[170:173], v[202:205], v[86:89]
	v_mfma_f32_16x16x32_bf16 v[86:89], v[174:177], v[206:209], v[86:89]
	v_mfma_f32_16x16x32_bf16 v[82:85], v[182:185], v[206:209], v[82:85]
	v_mfma_f32_16x16x32_bf16 v[82:85], v[178:181], v[202:205], v[82:85]
	v_mfma_f32_16x16x32_bf16 v[66:69], v[178:181], v[210:213], v[66:69]
	v_mfma_f32_16x16x32_bf16 v[66:69], v[182:185], v[214:217], v[66:69]
	v_mfma_f32_16x16x32_bf16 v[70:73], v[174:177], v[214:217], v[70:73]
	v_mfma_f32_16x16x32_bf16 v[70:73], v[170:173], v[210:213], v[70:73]
	v_mfma_f32_16x16x32_bf16 v[74:77], v[162:165], v[210:213], v[74:77]
	v_mfma_f32_16x16x32_bf16 v[74:77], v[166:169], v[214:217], v[74:77]
	v_mfma_f32_16x16x32_bf16 v[78:81], v[158:161], v[214:217], v[78:81]
	s_setprio 2
	s_barrier
	v_mfma_f32_16x16x32_bf16 v[78:81], v[248:251], v[210:213], v[78:81]
	s_setprio 0
	ds_read_b128 v[186:189], v152 offset:49152
	ds_read_b128 v[190:193], v152 offset:50176
	ds_read_b128 v[194:197], v152 offset:51200
	ds_read_b128 v[198:201], v152 offset:52224
	ds_read_b128 v[202:205], v152 offset:53248
	ds_read_b128 v[206:209], v152 offset:54272
	ds_read_b128 v[252:255], v152 offset:55296
	ds_read_b128 v[214:217], v152 offset:56320
	s_mov_b32 m0, s90
	s_nop 0
	global_load_lds_dwordx4 v142, s[76:77]
	s_add_u32 s60, s62, 0x100080
	s_mov_b32 m0, s91
	s_nop 0
	global_load_lds_dwordx4 v144, s[76:77]
	s_addc_u32 s61, s63, 0
	s_mov_b32 m0, s95
	s_nop 0
	global_load_lds_dwordx4 v142, s[60:61]
	s_nop 0
	s_mov_b32 m0, s96
	s_nop 0
	global_load_lds_dwordx4 v144, s[60:61]
	s_nop 0
	s_mov_b32 m0, s92
	s_nop 0
	global_load_lds_dwordx4 v141, s[66:67]
	s_nop 0
	s_mov_b32 m0, s94
	s_nop 0
	global_load_lds_dwordx4 v143, s[66:67]
	s_waitcnt vmcnt(8)
	s_waitcnt lgkmcnt(0)
	s_barrier
	s_setprio 1
	s_waitcnt lgkmcnt(7)
	v_mfma_f32_16x16x32_bf16 v[62:65], v[248:251], v[186:189], v[62:65]
	v_mfma_f32_16x16x32_bf16 v[62:65], v[158:161], v[190:193], v[62:65]
	v_mfma_f32_16x16x32_bf16 v[58:61], v[166:169], v[190:193], v[58:61]
	v_mfma_f32_16x16x32_bf16 v[58:61], v[162:165], v[186:189], v[58:61]
	v_mfma_f32_16x16x32_bf16 v[54:57], v[170:173], v[186:189], v[54:57]
	v_mfma_f32_16x16x32_bf16 v[54:57], v[174:177], v[190:193], v[54:57]
	v_mfma_f32_16x16x32_bf16 v[50:53], v[182:185], v[190:193], v[50:53]
	v_mfma_f32_16x16x32_bf16 v[50:53], v[178:181], v[186:189], v[50:53]
	v_mfma_f32_16x16x32_bf16 v[34:37], v[178:181], v[194:197], v[34:37]
	v_mfma_f32_16x16x32_bf16 v[34:37], v[182:185], v[198:201], v[34:37]
	v_mfma_f32_16x16x32_bf16 v[38:41], v[174:177], v[198:201], v[38:41]
	v_mfma_f32_16x16x32_bf16 v[38:41], v[170:173], v[194:197], v[38:41]
	v_mfma_f32_16x16x32_bf16 v[42:45], v[162:165], v[194:197], v[42:45]
	v_mfma_f32_16x16x32_bf16 v[42:45], v[166:169], v[198:201], v[42:45]
	v_mfma_f32_16x16x32_bf16 v[46:49], v[158:161], v[198:201], v[46:49]
	v_mfma_f32_16x16x32_bf16 v[46:49], v[248:251], v[194:197], v[46:49]
	v_mfma_f32_16x16x32_bf16 v[30:33], v[248:251], v[202:205], v[30:33]
	v_mfma_f32_16x16x32_bf16 v[30:33], v[158:161], v[206:209], v[30:33]
	v_mfma_f32_16x16x32_bf16 v[26:29], v[166:169], v[206:209], v[26:29]
	v_mfma_f32_16x16x32_bf16 v[26:29], v[162:165], v[202:205], v[26:29]
	v_mfma_f32_16x16x32_bf16 v[22:25], v[170:173], v[202:205], v[22:25]
	v_mfma_f32_16x16x32_bf16 v[22:25], v[174:177], v[206:209], v[22:25]
	v_mfma_f32_16x16x32_bf16 v[18:21], v[182:185], v[206:209], v[18:21]
	v_mfma_f32_16x16x32_bf16 v[18:21], v[178:181], v[202:205], v[18:21]
	v_mfma_f32_16x16x32_bf16 v[2:5], v[178:181], v[252:255], v[2:5]
	v_mfma_f32_16x16x32_bf16 v[2:5], v[182:185], v[214:217], v[2:5]
	v_mfma_f32_16x16x32_bf16 v[6:9], v[174:177], v[214:217], v[6:9]
	v_mfma_f32_16x16x32_bf16 v[6:9], v[170:173], v[252:255], v[6:9]
	v_mfma_f32_16x16x32_bf16 v[10:13], v[162:165], v[252:255], v[10:13]
	v_mfma_f32_16x16x32_bf16 v[10:13], v[166:169], v[214:217], v[10:13]
	v_mfma_f32_16x16x32_bf16 v[14:17], v[158:161], v[214:217], v[14:17]
	s_setprio 2
	s_barrier
	v_mfma_f32_16x16x32_bf16 v[14:17], v[248:251], v[252:255], v[14:17]
	s_setprio 0
	s_add_i32 s58, s58, 2
	s_add_u32 s56, s56, 0x100
	s_addc_u32 s57, s57, 0
	s_cmp_gt_u32 s58, 61
	s_cbranch_scc1 .LBB0_316
	s_mov_b64 s[82:83], s[8:9]
	s_branch .LBB0_320

; #define PG8_STAGE(bufoff, gbase, voff) do { _Pragma("unroll") for (int _i = 0; _i < 2; ++_i) \
;         asm volatile("s_mov_b32 m0, %2\n\ts_nop 0\n\tglobal_load_lds_dwordx4 %0, %1" :: "v"((voff)[_i]), "s"((const char*)(gbase)), "s"(ldsbase + (unsigned)(bufoff) + ldsw + (unsigned)_i * 8192u) : "memory", "m0"); } while (0)
; #define PG8_LDA(dst, b, h) do { _Pragma("unroll") for (int m = 0; m < 4; ++m) _Pragma("unroll") for (int k = 0; k < 2; ++k) dst[m][k] = *(const PG8_LAS bf16x8*)(lds + PG8_SA(b, h) + aoff + m * 2048 + k * 1024); } while (0)
; #define PG8_LDB(dst, b, h) do { _Pragma("unroll") for (int n = 0; n < 2; ++n) _Pragma("unroll") for (int k = 0; k < 2; ++k) dst[n][k] = *(const PG8_LAS bf16x8*)(lds + PG8_SB(b, h) + boff + n * 2048 + k * 1024); } while (0)
; #define PG8_MMA(ai, bj, At, Bt) do { __builtin_amdgcn_s_setprio(1); _Pragma("unroll") for (int m = 0; m < 4; ++m) _Pragma("unroll") for (int n = 0; n < 2; ++n) _Pragma("unroll") for (int k = 0; k < 2; ++k) \
;         acc[ai][bj][m][n] = __builtin_amdgcn_mfma_f32_16x16x32_bf16(Bt[n][k], At[m][k], acc[ai][bj][m][n], 0, 0, 0); __builtin_amdgcn_s_setprio(0); } while (0)
; #define PG8_WAIT_V(n) asm volatile("s_waitcnt vmcnt(" #n ")" ::: "memory")
; #define PG8_WAIT_L(n) asm volatile("s_waitcnt lgkmcnt(" #n ")" ::: "memory")
; #define PG8_BAR __builtin_amdgcn_s_barrier()
; #define PG8_SCHED __builtin_amdgcn_sched_barrier(0)
; template <class Epi, class Sched, bool ALIGN_EPI = false, bool SP2 = false>
; __device__ __forceinline__ void gemm_phase(PG8_LAS unsigned char* lds, const Gemm g, const Sched& S, const Epi& E) {
;     ...
;             PG8_LDB(B0, 0, 0); PG8_LDB(B1, 0, 1); PG8_SCHED; PG8_LDA(At, 0, 0); PG8_STAGE(PG8_SA(1, 1), a1 + hstep, voffA);
;             PG8_WAIT_V(8); PG8_WAIT_L(0); PG8_BAR; PG8_MMA(0, 0, At, B0); PG8_MMA(0, 1, At, B1); PG8_BAR; PG8_SCHED;
;             PG8_LDA(At, 0, 1); PG8_STAGE(PG8_SB(0, 0), b2, voffB); PG8_STAGE(PG8_SB(0, 1), b2 + hstep, voffB); PG8_STAGE(PG8_SA(0, 0), a2, voffA);
;             PG8_WAIT_V(8); PG8_WAIT_L(0); PG8_BAR; PG8_MMA(1, 0, At, B0); PG8_MMA(1, 1, At, B1); PG8_BAR; PG8_SCHED;
.LBB0_620:
	v_add_u32_e32 v3, 0x10000, v199
	ds_read_b128 v[134:137], v3
	ds_read_b128 v[138:141], v3 offset:1024
	ds_read_b128 v[142:145], v3 offset:2048
	ds_read_b128 v[146:149], v3 offset:3072
	v_add_u32_e32 v3, 0x14000, v199
	s_add_u32 s44, s42, 0x100
	ds_read_b128 v[158:161], v3
	ds_read_b128 v[162:165], v3 offset:1024
	ds_read_b128 v[166:169], v3 offset:2048
	ds_read_b128 v[170:173], v3 offset:3072
	s_addc_u32 s45, s43, 0
	s_cmp_eq_u32 s92, 60
	s_cselect_b32 s56, s88, s44
	s_cselect_b32 s57, s23, s45
	s_cselect_b32 s47, s19, s91
	s_cselect_b32 s46, s89, s90
	s_add_u32 s50, s56, 0x80
	s_addc_u32 s51, s57, 0
	s_add_u32 s54, s46, 0x80
	s_addc_u32 s55, s47, 0
	ds_read_b128 v[174:177], v200
	ds_read_b128 v[178:181], v200 offset:1024
	ds_read_b128 v[182:185], v200 offset:2048
	ds_read_b128 v[186:189], v200 offset:3072
	ds_read_b128 v[190:193], v200 offset:4096
	ds_read_b128 v[202:205], v200 offset:5120
	ds_read_b128 v[206:209], v200 offset:6144
	ds_read_b128 v[210:213], v200 offset:7168
	s_add_u32 s42, s42, 0x100080
	s_addc_u32 s43, s43, 0
	s_mov_b32 m0, s85
	s_nop 0
	global_load_lds_dwordx4 v1, s[42:43]
	s_nop 0
	s_mov_b32 m0, s86
	s_nop 0
	global_load_lds_dwordx4 v195, s[42:43]
	s_waitcnt vmcnt(8)
	s_waitcnt lgkmcnt(0)
	s_barrier
	s_setprio 1
	s_waitcnt lgkmcnt(7)
	v_mfma_f32_16x16x32_bf16 v[130:133], v[134:137], v[174:177], v[130:133]
	v_mfma_f32_16x16x32_bf16 v[126:129], v[142:145], v[174:177], v[126:129]
	v_mfma_f32_16x16x32_bf16 v[122:125], v[134:137], v[182:185], v[122:125]
	v_mfma_f32_16x16x32_bf16 v[118:121], v[142:145], v[182:185], v[118:121]
	v_mfma_f32_16x16x32_bf16 v[114:117], v[134:137], v[190:193], v[114:117]
	v_mfma_f32_16x16x32_bf16 v[110:113], v[142:145], v[190:193], v[110:113]
	v_mfma_f32_16x16x32_bf16 v[106:109], v[134:137], v[206:209], v[106:109]
	v_mfma_f32_16x16x32_bf16 v[102:105], v[142:145], v[206:209], v[102:105]
	v_mfma_f32_16x16x32_bf16 v[130:133], v[138:141], v[178:181], v[130:133]
	v_mfma_f32_16x16x32_bf16 v[126:129], v[146:149], v[178:181], v[126:129]
	v_mfma_f32_16x16x32_bf16 v[122:125], v[138:141], v[186:189], v[122:125]
	v_mfma_f32_16x16x32_bf16 v[118:121], v[146:149], v[186:189], v[118:121]
	v_mfma_f32_16x16x32_bf16 v[114:117], v[138:141], v[202:205], v[114:117]
	v_mfma_f32_16x16x32_bf16 v[110:113], v[146:149], v[202:205], v[110:113]
	v_mfma_f32_16x16x32_bf16 v[106:109], v[138:141], v[210:213], v[106:109]
	v_mfma_f32_16x16x32_bf16 v[102:105], v[146:149], v[210:213], v[102:105]
	v_mfma_f32_16x16x32_bf16 v[66:69], v[158:161], v[174:177], v[66:69]
	v_mfma_f32_16x16x32_bf16 v[62:65], v[166:169], v[174:177], v[62:65]
	v_mfma_f32_16x16x32_bf16 v[58:61], v[158:161], v[182:185], v[58:61]
	v_mfma_f32_16x16x32_bf16 v[54:57], v[166:169], v[182:185], v[54:57]
	v_mfma_f32_16x16x32_bf16 v[50:53], v[158:161], v[190:193], v[50:53]
	v_mfma_f32_16x16x32_bf16 v[46:49], v[166:169], v[190:193], v[46:49]
	v_mfma_f32_16x16x32_bf16 v[42:45], v[158:161], v[206:209], v[42:45]
	v_mfma_f32_16x16x32_bf16 v[38:41], v[166:169], v[206:209], v[38:41]
	v_mfma_f32_16x16x32_bf16 v[66:69], v[162:165], v[178:181], v[66:69]
	v_mfma_f32_16x16x32_bf16 v[62:65], v[170:173], v[178:181], v[62:65]
	v_mfma_f32_16x16x32_bf16 v[58:61], v[162:165], v[186:189], v[58:61]
	v_mfma_f32_16x16x32_bf16 v[54:57], v[170:173], v[186:189], v[54:57]
	v_mfma_f32_16x16x32_bf16 v[50:53], v[162:165], v[202:205], v[50:53]
	v_mfma_f32_16x16x32_bf16 v[46:49], v[170:173], v[202:205], v[46:49]
	v_mfma_f32_16x16x32_bf16 v[42:45], v[162:165], v[210:213], v[42:45]
	s_setprio 2
	s_barrier
	v_mfma_f32_16x16x32_bf16 v[38:41], v[170:173], v[210:213], v[38:41]
	s_setprio 0
	ds_read_b128 v[174:177], v200 offset:16384
	ds_read_b128 v[178:181], v200 offset:17408
	ds_read_b128 v[182:185], v200 offset:18432
	ds_read_b128 v[186:189], v200 offset:19456
	ds_read_b128 v[190:193], v200 offset:20480
	ds_read_b128 v[202:205], v200 offset:21504
	ds_read_b128 v[206:209], v200 offset:22528
	ds_read_b128 v[252:255], v200 offset:23552
	s_mov_b32 m0, s63
	s_nop 0
	global_load_lds_dwordx4 v194, s[46:47]
	s_add_u32 s42, s46, 0x100000
	s_mov_b32 m0, s64
	s_nop 0
	global_load_lds_dwordx4 v196, s[46:47]
	s_addc_u32 s43, s47, 0
	s_mov_b32 m0, s65
	s_nop 0
	global_load_lds_dwordx4 v194, s[42:43]
	s_nop 0
	s_mov_b32 m0, s66
	s_nop 0
	global_load_lds_dwordx4 v196, s[42:43]
	s_nop 0
	s_mov_b32 m0, s62
	s_nop 0
	global_load_lds_dwordx4 v1, s[56:57]
	s_nop 0
	s_mov_b32 m0, s67
	s_nop 0
	global_load_lds_dwordx4 v195, s[56:57]
	s_waitcnt vmcnt(8)
	s_waitcnt lgkmcnt(0)
	s_barrier
	s_setprio 1
	s_waitcnt lgkmcnt(7)
	v_mfma_f32_16x16x32_bf16 v[98:101], v[134:137], v[174:177], v[98:101]
	v_mfma_f32_16x16x32_bf16 v[94:97], v[142:145], v[174:177], v[94:97]
	v_mfma_f32_16x16x32_bf16 v[90:93], v[134:137], v[182:185], v[90:93]
	v_mfma_f32_16x16x32_bf16 v[86:89], v[142:145], v[182:185], v[86:89]
	v_mfma_f32_16x16x32_bf16 v[82:85], v[134:137], v[190:193], v[82:85]
	v_mfma_f32_16x16x32_bf16 v[78:81], v[142:145], v[190:193], v[78:81]
	v_mfma_f32_16x16x32_bf16 v[74:77], v[134:137], v[206:209], v[74:77]
	v_mfma_f32_16x16x32_bf16 v[70:73], v[142:145], v[206:209], v[70:73]
	v_mfma_f32_16x16x32_bf16 v[98:101], v[138:141], v[178:181], v[98:101]
	v_mfma_f32_16x16x32_bf16 v[94:97], v[146:149], v[178:181], v[94:97]
	v_mfma_f32_16x16x32_bf16 v[90:93], v[138:141], v[186:189], v[90:93]
	v_mfma_f32_16x16x32_bf16 v[86:89], v[146:149], v[186:189], v[86:89]
	v_mfma_f32_16x16x32_bf16 v[82:85], v[138:141], v[202:205], v[82:85]
	v_mfma_f32_16x16x32_bf16 v[78:81], v[146:149], v[202:205], v[78:81]
	v_mfma_f32_16x16x32_bf16 v[74:77], v[138:141], v[252:255], v[74:77]
	v_mfma_f32_16x16x32_bf16 v[70:73], v[146:149], v[252:255], v[70:73]
	v_mfma_f32_16x16x32_bf16 v[34:37], v[158:161], v[174:177], v[34:37]
	v_mfma_f32_16x16x32_bf16 v[30:33], v[166:169], v[174:177], v[30:33]
	v_mfma_f32_16x16x32_bf16 v[26:29], v[158:161], v[182:185], v[26:29]
	v_mfma_f32_16x16x32_bf16 v[22:25], v[166:169], v[182:185], v[22:25]
	v_mfma_f32_16x16x32_bf16 v[18:21], v[158:161], v[190:193], v[18:21]
	v_mfma_f32_16x16x32_bf16 v[14:17], v[166:169], v[190:193], v[14:17]
	v_mfma_f32_16x16x32_bf16 v[10:13], v[158:161], v[206:209], v[10:13]
	v_mfma_f32_16x16x32_bf16 v[4:7], v[166:169], v[206:209], v[6:9]
	v_mfma_f32_16x16x32_bf16 v[34:37], v[162:165], v[178:181], v[34:37]
	v_mfma_f32_16x16x32_bf16 v[30:33], v[170:173], v[178:181], v[30:33]
	v_mfma_f32_16x16x32_bf16 v[26:29], v[162:165], v[186:189], v[26:29]
	v_mfma_f32_16x16x32_bf16 v[22:25], v[170:173], v[186:189], v[22:25]
	v_mfma_f32_16x16x32_bf16 v[18:21], v[162:165], v[202:205], v[18:21]
	v_mfma_f32_16x16x32_bf16 v[14:17], v[170:173], v[202:205], v[14:17]
	v_mfma_f32_16x16x32_bf16 v[10:13], v[162:165], v[252:255], v[10:13]
	s_setprio 2
	s_barrier
; #define PG8_STAGE(bufoff, gbase, voff) do { _Pragma("unroll") for (int _i = 0; _i < 2; ++_i) \
;         asm volatile("s_mov_b32 m0, %2\n\ts_nop 0\n\tglobal_load_lds_dwordx4 %0, %1" :: "v"((voff)[_i]), "s"((const char*)(gbase)), "s"(ldsbase + (unsigned)(bufoff) + ldsw + (unsigned)_i * 8192u) : "memory", "m0"); } while (0)
; #define PG8_LDA(dst, b, h) do { _Pragma("unroll") for (int m = 0; m < 4; ++m) _Pragma("unroll") for (int k = 0; k < 2; ++k) dst[m][k] = *(const PG8_LAS bf16x8*)(lds + PG8_SA(b, h) + aoff + m * 2048 + k * 1024); } while (0)
; #define PG8_LDB(dst, b, h) do { _Pragma("unroll") for (int n = 0; n < 2; ++n) _Pragma("unroll") for (int k = 0; k < 2; ++k) dst[n][k] = *(const PG8_LAS bf16x8*)(lds + PG8_SB(b, h) + boff + n * 2048 + k * 1024); } while (0)
; #define PG8_MMA(ai, bj, At, Bt) do { __builtin_amdgcn_s_setprio(1); _Pragma("unroll") for (int m = 0; m < 4; ++m) _Pragma("unroll") for (int n = 0; n < 2; ++n) _Pragma("unroll") for (int k = 0; k < 2; ++k) \
;         acc[ai][bj][m][n] = __builtin_amdgcn_mfma_f32_16x16x32_bf16(Bt[n][k], At[m][k], acc[ai][bj][m][n], 0, 0, 0); __builtin_amdgcn_s_setprio(0); } while (0)
; #define PG8_WAIT_V(n) asm volatile("s_waitcnt vmcnt(" #n ")" ::: "memory")
; #define PG8_WAIT_L(n) asm volatile("s_waitcnt lgkmcnt(" #n ")" ::: "memory")
; #define PG8_BAR __builtin_amdgcn_s_barrier()
; #define PG8_SCHED __builtin_amdgcn_sched_barrier(0)
; template <class Epi, class Sched, bool ALIGN_EPI = false, bool SP2 = false>
; __device__ __forceinline__ void gemm_phase(PG8_LAS unsigned char* lds, const Gemm g, const Sched& S, const Epi& E) {
;     ...
;             if constexpr (epi_has_mid<Epi>::value) { if (t == Epi::MID_T) E.mid(acc, cur, wr, wc, fr, fq); }
;     ...
;             PG8_LDB(B0, 1, 0); PG8_LDB(B1, 1, 1); PG8_SCHED; PG8_LDA(At, 1, 0); PG8_STAGE(PG8_SA(0, 1), a2 + hstep, voffA);
;             PG8_WAIT_V(8); PG8_WAIT_L(0); PG8_BAR; PG8_MMA(0, 0, At, B0); PG8_MMA(0, 1, At, B1); PG8_BAR; PG8_SCHED;
;             PG8_LDA(At, 1, 1); PG8_STAGE(PG8_SB(1, 0), b3, voffB); PG8_STAGE(PG8_SB(1, 1), b3 + hstep, voffB); PG8_STAGE(PG8_SA(1, 0), a3, voffA);
;             PG8_WAIT_V(8); PG8_WAIT_L(0); PG8_BAR; PG8_MMA(1, 0, At, B0); PG8_MMA(1, 1, At, B1); PG8_BAR; PG8_SCHED;
	v_mfma_f32_16x16x32_bf16 v[4:7], v[170:173], v[252:255], v[4:7]
	s_setprio 0
	v_add_u32_e32 v3, 0x18000, v199
	ds_read_b128 v[134:137], v3
	ds_read_b128 v[138:141], v3 offset:1024
	ds_read_b128 v[142:145], v3 offset:2048
	ds_read_b128 v[146:149], v3 offset:3072
	v_add_u32_e32 v3, 0x1c000, v199
	ds_read_b128 v[158:161], v3
	ds_read_b128 v[162:165], v3 offset:1024
	ds_read_b128 v[166:169], v3 offset:2048
	ds_read_b128 v[248:251], v3 offset:3072
	ds_read_b128 v[174:177], v200 offset:32768
	ds_read_b128 v[178:181], v200 offset:33792
	ds_read_b128 v[182:185], v200 offset:34816
	ds_read_b128 v[186:189], v200 offset:35840
	ds_read_b128 v[190:193], v200 offset:36864
	ds_read_b128 v[202:205], v200 offset:37888
	ds_read_b128 v[206:209], v200 offset:38912
	ds_read_b128 v[210:213], v200 offset:39936
	s_add_u32 s42, s56, 0x100000
	s_addc_u32 s43, s57, 0
	s_mov_b32 m0, s76
	s_nop 0
	global_load_lds_dwordx4 v1, s[42:43]
	s_nop 0
	s_mov_b32 m0, s77
	s_nop 0
	global_load_lds_dwordx4 v195, s[42:43]
	s_waitcnt vmcnt(8)
	s_waitcnt lgkmcnt(0)
	s_barrier
	s_setprio 1
	s_waitcnt lgkmcnt(7)
	v_mfma_f32_16x16x32_bf16 v[130:133], v[134:137], v[174:177], v[130:133]
	v_mfma_f32_16x16x32_bf16 v[126:129], v[142:145], v[174:177], v[126:129]
	v_mfma_f32_16x16x32_bf16 v[122:125], v[134:137], v[182:185], v[122:125]
	v_mfma_f32_16x16x32_bf16 v[118:121], v[142:145], v[182:185], v[118:121]
	v_mfma_f32_16x16x32_bf16 v[114:117], v[134:137], v[190:193], v[114:117]
	v_mfma_f32_16x16x32_bf16 v[110:113], v[142:145], v[190:193], v[110:113]
	v_mfma_f32_16x16x32_bf16 v[106:109], v[134:137], v[206:209], v[106:109]
	v_mfma_f32_16x16x32_bf16 v[102:105], v[142:145], v[206:209], v[102:105]
	v_mfma_f32_16x16x32_bf16 v[130:133], v[138:141], v[178:181], v[130:133]
	v_mfma_f32_16x16x32_bf16 v[126:129], v[146:149], v[178:181], v[126:129]
	v_mfma_f32_16x16x32_bf16 v[122:125], v[138:141], v[186:189], v[122:125]
	v_mfma_f32_16x16x32_bf16 v[118:121], v[146:149], v[186:189], v[118:121]
	v_mfma_f32_16x16x32_bf16 v[114:117], v[138:141], v[202:205], v[114:117]
	v_mfma_f32_16x16x32_bf16 v[110:113], v[146:149], v[202:205], v[110:113]
	v_mfma_f32_16x16x32_bf16 v[106:109], v[138:141], v[210:213], v[106:109]
	v_mfma_f32_16x16x32_bf16 v[102:105], v[146:149], v[210:213], v[102:105]
	v_mfma_f32_16x16x32_bf16 v[66:69], v[158:161], v[174:177], v[66:69]
	v_mfma_f32_16x16x32_bf16 v[62:65], v[166:169], v[174:177], v[62:65]
	v_mfma_f32_16x16x32_bf16 v[58:61], v[158:161], v[182:185], v[58:61]
	v_mfma_f32_16x16x32_bf16 v[54:57], v[166:169], v[182:185], v[54:57]
	v_mfma_f32_16x16x32_bf16 v[50:53], v[158:161], v[190:193], v[50:53]
	v_mfma_f32_16x16x32_bf16 v[46:49], v[166:169], v[190:193], v[46:49]
	v_mfma_f32_16x16x32_bf16 v[42:45], v[158:161], v[206:209], v[42:45]
	v_mfma_f32_16x16x32_bf16 v[38:41], v[166:169], v[206:209], v[38:41]
	v_mfma_f32_16x16x32_bf16 v[66:69], v[162:165], v[178:181], v[66:69]
	v_mfma_f32_16x16x32_bf16 v[62:65], v[248:251], v[178:181], v[62:65]
	v_mfma_f32_16x16x32_bf16 v[58:61], v[162:165], v[186:189], v[58:61]
	v_mfma_f32_16x16x32_bf16 v[54:57], v[248:251], v[186:189], v[54:57]
	v_mfma_f32_16x16x32_bf16 v[50:53], v[162:165], v[202:205], v[50:53]
	v_mfma_f32_16x16x32_bf16 v[46:49], v[248:251], v[202:205], v[46:49]
	v_mfma_f32_16x16x32_bf16 v[42:45], v[162:165], v[210:213], v[42:45]
	s_setprio 2
	s_barrier
	v_mfma_f32_16x16x32_bf16 v[38:41], v[248:251], v[210:213], v[38:41]
	s_setprio 0
	ds_read_b128 v[174:177], v200 offset:49152
	ds_read_b128 v[178:181], v200 offset:50176
	ds_read_b128 v[182:185], v200 offset:51200
	ds_read_b128 v[186:189], v200 offset:52224
	ds_read_b128 v[190:193], v200 offset:53248
	ds_read_b128 v[202:205], v200 offset:54272
	ds_read_b128 v[206:209], v200 offset:55296
	ds_read_b128 v[252:255], v200 offset:56320
	s_mov_b32 m0, s78
	s_nop 0
	global_load_lds_dwordx4 v194, s[54:55]
	s_add_u32 s42, s46, 0x100080
	s_mov_b32 m0, s79
	s_nop 0
	global_load_lds_dwordx4 v196, s[54:55]
	s_addc_u32 s43, s47, 0
	s_mov_b32 m0, s83
	s_nop 0
	global_load_lds_dwordx4 v194, s[42:43]
	s_nop 0
	s_mov_b32 m0, s84
	s_nop 0
	global_load_lds_dwordx4 v196, s[42:43]
	s_nop 0
	s_mov_b32 m0, s80
	s_nop 0
	global_load_lds_dwordx4 v1, s[50:51]
	s_nop 0
	s_mov_b32 m0, s82
	s_nop 0
	global_load_lds_dwordx4 v195, s[50:51]
	s_waitcnt vmcnt(8)
	s_waitcnt lgkmcnt(0)
	s_barrier
	s_setprio 1
	s_waitcnt lgkmcnt(7)
	v_mfma_f32_16x16x32_bf16 v[98:101], v[134:137], v[174:177], v[98:101]
	v_mfma_f32_16x16x32_bf16 v[94:97], v[142:145], v[174:177], v[94:97]
	v_mfma_f32_16x16x32_bf16 v[90:93], v[134:137], v[182:185], v[90:93]
	v_mfma_f32_16x16x32_bf16 v[86:89], v[142:145], v[182:185], v[86:89]
	v_mfma_f32_16x16x32_bf16 v[82:85], v[134:137], v[190:193], v[82:85]
	v_mfma_f32_16x16x32_bf16 v[78:81], v[142:145], v[190:193], v[78:81]
	v_mfma_f32_16x16x32_bf16 v[74:77], v[134:137], v[206:209], v[74:77]
	v_mfma_f32_16x16x32_bf16 v[70:73], v[142:145], v[206:209], v[70:73]
	v_mfma_f32_16x16x32_bf16 v[98:101], v[138:141], v[178:181], v[98:101]
	v_mfma_f32_16x16x32_bf16 v[94:97], v[146:149], v[178:181], v[94:97]
	v_mfma_f32_16x16x32_bf16 v[90:93], v[138:141], v[186:189], v[90:93]
	v_mfma_f32_16x16x32_bf16 v[86:89], v[146:149], v[186:189], v[86:89]
	v_mfma_f32_16x16x32_bf16 v[82:85], v[138:141], v[202:205], v[82:85]
	v_mfma_f32_16x16x32_bf16 v[78:81], v[146:149], v[202:205], v[78:81]
	v_mfma_f32_16x16x32_bf16 v[74:77], v[138:141], v[252:255], v[74:77]
	v_mfma_f32_16x16x32_bf16 v[70:73], v[146:149], v[252:255], v[70:73]
	v_mfma_f32_16x16x32_bf16 v[34:37], v[158:161], v[174:177], v[34:37]
	v_mfma_f32_16x16x32_bf16 v[30:33], v[166:169], v[174:177], v[30:33]
	v_mfma_f32_16x16x32_bf16 v[26:29], v[158:161], v[182:185], v[26:29]
	v_mfma_f32_16x16x32_bf16 v[22:25], v[166:169], v[182:185], v[22:25]
	v_mfma_f32_16x16x32_bf16 v[18:21], v[158:161], v[190:193], v[18:21]
	v_mfma_f32_16x16x32_bf16 v[14:17], v[166:169], v[190:193], v[14:17]
	v_mfma_f32_16x16x32_bf16 v[8:11], v[158:161], v[206:209], v[10:13]
	v_mfma_f32_16x16x32_bf16 v[4:7], v[166:169], v[206:209], v[4:7]
	v_mfma_f32_16x16x32_bf16 v[34:37], v[162:165], v[178:181], v[34:37]
	v_mfma_f32_16x16x32_bf16 v[30:33], v[248:251], v[178:181], v[30:33]
	v_mfma_f32_16x16x32_bf16 v[26:29], v[162:165], v[186:189], v[26:29]
	v_mfma_f32_16x16x32_bf16 v[22:25], v[248:251], v[186:189], v[22:25]
	v_mfma_f32_16x16x32_bf16 v[18:21], v[162:165], v[202:205], v[18:21]
	v_mfma_f32_16x16x32_bf16 v[14:17], v[248:251], v[202:205], v[14:17]
	v_mfma_f32_16x16x32_bf16 v[10:13], v[162:165], v[252:255], v[8:11]
	s_setprio 2
	s_barrier
	v_mfma_f32_16x16x32_bf16 v[6:9], v[248:251], v[252:255], v[4:7]
	s_setprio 0
	s_add_i32 s92, s92, 2
	s_add_u32 s90, s90, 0x100
	s_addc_u32 s91, s91, 0
	s_cmp_gt_u32 s92, 61
	s_cbranch_scc1 .LBB0_622
	s_mov_b64 s[42:43], s[44:45]
	s_cmp_lg_u32 s92, 30
	s_cbranch_scc0 .LBB0_619
	s_branch .LBB0_620

; #define PG8_STAGE(bufoff, gbase, voff) do { _Pragma("unroll") for (int _i = 0; _i < 2; ++_i) \
;         asm volatile("s_mov_b32 m0, %2\n\ts_nop 0\n\tglobal_load_lds_dwordx4 %0, %1" :: "v"((voff)[_i]), "s"((const char*)(gbase)), "s"(ldsbase + (unsigned)(bufoff) + ldsw + (unsigned)_i * 8192u) : "memory", "m0"); } while (0)
; #define PG8_LDA(dst, b, h) do { _Pragma("unroll") for (int m = 0; m < 4; ++m) _Pragma("unroll") for (int k = 0; k < 2; ++k) dst[m][k] = *(const PG8_LAS bf16x8*)(lds + PG8_SA(b, h) + aoff + m * 2048 + k * 1024); } while (0)
; #define PG8_LDB(dst, b, h) do { _Pragma("unroll") for (int n = 0; n < 2; ++n) _Pragma("unroll") for (int k = 0; k < 2; ++k) dst[n][k] = *(const PG8_LAS bf16x8*)(lds + PG8_SB(b, h) + boff + n * 2048 + k * 1024); } while (0)
; #define PG8_MMA(ai, bj, At, Bt) do { __builtin_amdgcn_s_setprio(1); _Pragma("unroll") for (int m = 0; m < 4; ++m) _Pragma("unroll") for (int n = 0; n < 2; ++n) _Pragma("unroll") for (int k = 0; k < 2; ++k) \
;         acc[ai][bj][m][n] = __builtin_amdgcn_mfma_f32_16x16x32_bf16(Bt[n][k], At[m][k], acc[ai][bj][m][n], 0, 0, 0); __builtin_amdgcn_s_setprio(0); } while (0)
; #define PG8_WAIT_V(n) asm volatile("s_waitcnt vmcnt(" #n ")" ::: "memory")
; #define PG8_WAIT_L(n) asm volatile("s_waitcnt lgkmcnt(" #n ")" ::: "memory")
; #define PG8_BAR __builtin_amdgcn_s_barrier()
; #define PG8_SCHED __builtin_amdgcn_sched_barrier(0)
; template <class Epi, class Sched, bool ALIGN_EPI = false, bool SP2 = false>
; __device__ __forceinline__ void gemm_phase(PG8_LAS unsigned char* lds, const Gemm g, const Sched& S, const Epi& E) {
;     ...
;             PG8_LDB(B0, 0, 0); PG8_LDB(B1, 0, 1); PG8_SCHED; PG8_LDA(At, 0, 0); PG8_STAGE(PG8_SA(1, 1), a1 + hstep, voffA);
;             PG8_WAIT_V(8); PG8_WAIT_L(0); PG8_BAR; PG8_MMA(0, 0, At, B0); PG8_MMA(0, 1, At, B1); PG8_BAR; PG8_SCHED;
;             PG8_LDA(At, 0, 1); PG8_STAGE(PG8_SB(0, 0), b2, voffB); PG8_STAGE(PG8_SB(0, 1), b2 + hstep, voffB); PG8_STAGE(PG8_SA(0, 0), a2, voffA);
;             PG8_WAIT_V(8); PG8_WAIT_L(0); PG8_BAR; PG8_MMA(1, 0, At, B0); PG8_MMA(1, 1, At, B1); PG8_BAR; PG8_SCHED;
.LBB0_698:
	ds_read_b128 v[134:137], v145
	ds_read_b128 v[152:155], v145 offset:1024
	ds_read_b128 v[156:159], v145 offset:2048
	ds_read_b128 v[160:163], v145 offset:3072
	ds_read_b128 v[164:167], v146
	ds_read_b128 v[168:171], v146 offset:1024
	ds_read_b128 v[172:175], v146 offset:2048
	ds_read_b128 v[176:179], v146 offset:3072
	s_cmp_eq_u32 s69, 60
	s_cselect_b32 s48, s41, s53
	s_cselect_b32 s49, s19, s58
	s_cselect_b32 s46, s52, s59
	s_cselect_b32 s47, s17, s68
	s_add_u32 s44, s48, 0x80
	s_addc_u32 s45, s49, 0
	ds_read_b128 v[180:183], v147
	ds_read_b128 v[184:187], v147 offset:1024
	ds_read_b128 v[188:191], v147 offset:2048
	ds_read_b128 v[192:195], v147 offset:3072
	ds_read_b128 v[196:199], v147 offset:4096
	ds_read_b128 v[200:203], v147 offset:5120
	ds_read_b128 v[204:207], v147 offset:6144
	ds_read_b128 v[208:211], v147 offset:7168
	s_mov_b32 m0, s67
	s_nop 0
	global_load_lds_dwordx4 v1, s[42:43]
	s_nop 0
	s_mov_b32 m0, s74
	s_nop 0
	global_load_lds_dwordx4 v141, s[42:43]
	s_waitcnt vmcnt(8)
	s_waitcnt lgkmcnt(0)
	s_barrier
	s_setprio 1
	s_waitcnt lgkmcnt(7)
	v_mfma_f32_16x16x32_bf16 v[126:129], v[134:137], v[180:183], v[126:129]
	v_mfma_f32_16x16x32_bf16 v[126:129], v[152:155], v[184:187], v[126:129]
	v_mfma_f32_16x16x32_bf16 v[122:125], v[160:163], v[184:187], v[122:125]
	v_mfma_f32_16x16x32_bf16 v[122:125], v[156:159], v[180:183], v[122:125]
	v_mfma_f32_16x16x32_bf16 v[118:121], v[164:167], v[180:183], v[118:121]
	v_mfma_f32_16x16x32_bf16 v[118:121], v[168:171], v[184:187], v[118:121]
	v_mfma_f32_16x16x32_bf16 v[114:117], v[176:179], v[184:187], v[114:117]
	v_mfma_f32_16x16x32_bf16 v[114:117], v[172:175], v[180:183], v[114:117]
	v_mfma_f32_16x16x32_bf16 v[98:101], v[172:175], v[188:191], v[98:101]
	v_mfma_f32_16x16x32_bf16 v[98:101], v[176:179], v[192:195], v[98:101]
	v_mfma_f32_16x16x32_bf16 v[102:105], v[168:171], v[192:195], v[102:105]
	v_mfma_f32_16x16x32_bf16 v[102:105], v[164:167], v[188:191], v[102:105]
	v_mfma_f32_16x16x32_bf16 v[106:109], v[156:159], v[188:191], v[106:109]
	v_mfma_f32_16x16x32_bf16 v[106:109], v[160:163], v[192:195], v[106:109]
	v_mfma_f32_16x16x32_bf16 v[110:113], v[152:155], v[192:195], v[110:113]
	v_mfma_f32_16x16x32_bf16 v[110:113], v[134:137], v[188:191], v[110:113]
	v_mfma_f32_16x16x32_bf16 v[94:97], v[134:137], v[196:199], v[94:97]
	v_mfma_f32_16x16x32_bf16 v[94:97], v[152:155], v[200:203], v[94:97]
	v_mfma_f32_16x16x32_bf16 v[90:93], v[160:163], v[200:203], v[90:93]
	v_mfma_f32_16x16x32_bf16 v[90:93], v[156:159], v[196:199], v[90:93]
	v_mfma_f32_16x16x32_bf16 v[86:89], v[164:167], v[196:199], v[86:89]
	v_mfma_f32_16x16x32_bf16 v[86:89], v[168:171], v[200:203], v[86:89]
	v_mfma_f32_16x16x32_bf16 v[82:85], v[176:179], v[200:203], v[82:85]
	v_mfma_f32_16x16x32_bf16 v[82:85], v[172:175], v[196:199], v[82:85]
	v_mfma_f32_16x16x32_bf16 v[66:69], v[172:175], v[204:207], v[66:69]
	v_mfma_f32_16x16x32_bf16 v[66:69], v[176:179], v[208:211], v[66:69]
	v_mfma_f32_16x16x32_bf16 v[70:73], v[168:171], v[208:211], v[70:73]
	v_mfma_f32_16x16x32_bf16 v[70:73], v[164:167], v[204:207], v[70:73]
	v_mfma_f32_16x16x32_bf16 v[74:77], v[156:159], v[204:207], v[74:77]
	v_mfma_f32_16x16x32_bf16 v[74:77], v[160:163], v[208:211], v[74:77]
	v_mfma_f32_16x16x32_bf16 v[78:81], v[152:155], v[208:211], v[78:81]
	s_setprio 2
	s_barrier
	v_mfma_f32_16x16x32_bf16 v[78:81], v[134:137], v[204:207], v[78:81]
	s_setprio 0
	ds_read_b128 v[180:183], v147 offset:16384
	ds_read_b128 v[184:187], v147 offset:17408
	ds_read_b128 v[188:191], v147 offset:18432
	ds_read_b128 v[192:195], v147 offset:19456
	ds_read_b128 v[196:199], v147 offset:20480
	ds_read_b128 v[200:203], v147 offset:21504
	ds_read_b128 v[252:255], v147 offset:22528
	ds_read_b128 v[208:211], v147 offset:23552
	s_mov_b32 m0, s35
	s_nop 0
	global_load_lds_dwordx4 v140, s[46:47]
	s_add_u32 s70, s46, 0x100000
	s_mov_b32 m0, s50
	s_nop 0
	global_load_lds_dwordx4 v142, s[46:47]
	s_addc_u32 s71, s47, 0
	s_mov_b32 m0, s51
	s_nop 0
	global_load_lds_dwordx4 v140, s[70:71]
	s_nop 0
	s_mov_b32 m0, s54
	s_nop 0
	global_load_lds_dwordx4 v142, s[70:71]
	s_nop 0
	s_mov_b32 m0, s3
	s_nop 0
	global_load_lds_dwordx4 v1, s[48:49]
	s_nop 0
	s_mov_b32 m0, s55
	s_nop 0
	global_load_lds_dwordx4 v141, s[48:49]
	s_waitcnt vmcnt(8)
	s_waitcnt lgkmcnt(0)
	s_barrier
	s_setprio 1
	s_waitcnt lgkmcnt(7)
	v_mfma_f32_16x16x32_bf16 v[62:65], v[134:137], v[180:183], v[62:65]
	v_mfma_f32_16x16x32_bf16 v[62:65], v[152:155], v[184:187], v[62:65]
	v_mfma_f32_16x16x32_bf16 v[58:61], v[160:163], v[184:187], v[58:61]
	v_mfma_f32_16x16x32_bf16 v[58:61], v[156:159], v[180:183], v[58:61]
	v_mfma_f32_16x16x32_bf16 v[54:57], v[164:167], v[180:183], v[54:57]
	v_mfma_f32_16x16x32_bf16 v[54:57], v[168:171], v[184:187], v[54:57]
	v_mfma_f32_16x16x32_bf16 v[50:53], v[176:179], v[184:187], v[50:53]
	v_mfma_f32_16x16x32_bf16 v[50:53], v[172:175], v[180:183], v[50:53]
	v_mfma_f32_16x16x32_bf16 v[34:37], v[172:175], v[188:191], v[34:37]
	v_mfma_f32_16x16x32_bf16 v[34:37], v[176:179], v[192:195], v[34:37]
	v_mfma_f32_16x16x32_bf16 v[38:41], v[168:171], v[192:195], v[38:41]
	v_mfma_f32_16x16x32_bf16 v[38:41], v[164:167], v[188:191], v[38:41]
	v_mfma_f32_16x16x32_bf16 v[42:45], v[156:159], v[188:191], v[42:45]
	v_mfma_f32_16x16x32_bf16 v[42:45], v[160:163], v[192:195], v[42:45]
	v_mfma_f32_16x16x32_bf16 v[46:49], v[152:155], v[192:195], v[46:49]
	v_mfma_f32_16x16x32_bf16 v[46:49], v[134:137], v[188:191], v[46:49]
	v_mfma_f32_16x16x32_bf16 v[30:33], v[134:137], v[196:199], v[30:33]
	v_mfma_f32_16x16x32_bf16 v[30:33], v[152:155], v[200:203], v[30:33]
	v_mfma_f32_16x16x32_bf16 v[26:29], v[160:163], v[200:203], v[26:29]
	v_mfma_f32_16x16x32_bf16 v[26:29], v[156:159], v[196:199], v[26:29]
	v_mfma_f32_16x16x32_bf16 v[22:25], v[164:167], v[196:199], v[22:25]
	v_mfma_f32_16x16x32_bf16 v[22:25], v[168:171], v[200:203], v[22:25]
	v_mfma_f32_16x16x32_bf16 v[18:21], v[176:179], v[200:203], v[18:21]
	v_mfma_f32_16x16x32_bf16 v[18:21], v[172:175], v[196:199], v[18:21]
	v_mfma_f32_16x16x32_bf16 v[2:5], v[172:175], v[252:255], v[2:5]
	v_mfma_f32_16x16x32_bf16 v[2:5], v[176:179], v[208:211], v[2:5]
	v_mfma_f32_16x16x32_bf16 v[6:9], v[168:171], v[208:211], v[6:9]
	v_mfma_f32_16x16x32_bf16 v[6:9], v[164:167], v[252:255], v[6:9]
	v_mfma_f32_16x16x32_bf16 v[10:13], v[156:159], v[252:255], v[10:13]
	v_mfma_f32_16x16x32_bf16 v[10:13], v[160:163], v[208:211], v[10:13]
	v_mfma_f32_16x16x32_bf16 v[14:17], v[152:155], v[208:211], v[14:17]
	s_setprio 2
	s_barrier
; #define PG8_STAGE(bufoff, gbase, voff) do { _Pragma("unroll") for (int _i = 0; _i < 2; ++_i) \
;         asm volatile("s_mov_b32 m0, %2\n\ts_nop 0\n\tglobal_load_lds_dwordx4 %0, %1" :: "v"((voff)[_i]), "s"((const char*)(gbase)), "s"(ldsbase + (unsigned)(bufoff) + ldsw + (unsigned)_i * 8192u) : "memory", "m0"); } while (0)
; #define PG8_LDA(dst, b, h) do { _Pragma("unroll") for (int m = 0; m < 4; ++m) _Pragma("unroll") for (int k = 0; k < 2; ++k) dst[m][k] = *(const PG8_LAS bf16x8*)(lds + PG8_SA(b, h) + aoff + m * 2048 + k * 1024); } while (0)
; #define PG8_LDB(dst, b, h) do { _Pragma("unroll") for (int n = 0; n < 2; ++n) _Pragma("unroll") for (int k = 0; k < 2; ++k) dst[n][k] = *(const PG8_LAS bf16x8*)(lds + PG8_SB(b, h) + boff + n * 2048 + k * 1024); } while (0)
; #define PG8_MMA(ai, bj, At, Bt) do { __builtin_amdgcn_s_setprio(1); _Pragma("unroll") for (int m = 0; m < 4; ++m) _Pragma("unroll") for (int n = 0; n < 2; ++n) _Pragma("unroll") for (int k = 0; k < 2; ++k) \
;         acc[ai][bj][m][n] = __builtin_amdgcn_mfma_f32_16x16x32_bf16(Bt[n][k], At[m][k], acc[ai][bj][m][n], 0, 0, 0); __builtin_amdgcn_s_setprio(0); } while (0)
; #define PG8_WAIT_V(n) asm volatile("s_waitcnt vmcnt(" #n ")" ::: "memory")
; #define PG8_WAIT_L(n) asm volatile("s_waitcnt lgkmcnt(" #n ")" ::: "memory")
; #define PG8_BAR __builtin_amdgcn_s_barrier()
; #define PG8_SCHED __builtin_amdgcn_sched_barrier(0)
; template <class Epi, class Sched, bool ALIGN_EPI = false, bool SP2 = false>
; __device__ __forceinline__ void gemm_phase(PG8_LAS unsigned char* lds, const Gemm g, const Sched& S, const Epi& E) {
;     ...
;             PG8_WAIT_V(8); PG8_WAIT_L(0); PG8_BAR; PG8_MMA(1, 0, At, B0); PG8_MMA(1, 1, At, B1); PG8_BAR; PG8_SCHED;
;             PG8_LDB(B0, 1, 0); PG8_LDB(B1, 1, 1); PG8_SCHED; PG8_LDA(At, 1, 0); PG8_STAGE(PG8_SA(0, 1), a2 + hstep, voffA);
;             PG8_WAIT_V(8); PG8_WAIT_L(0); PG8_BAR; PG8_MMA(0, 0, At, B0); PG8_MMA(0, 1, At, B1); PG8_BAR; PG8_SCHED;
;             PG8_LDA(At, 1, 1); PG8_STAGE(PG8_SB(1, 0), b3, voffB); PG8_STAGE(PG8_SB(1, 1), b3 + hstep, voffB); PG8_STAGE(PG8_SA(1, 0), a3, voffA);
;             PG8_WAIT_V(8); PG8_WAIT_L(0); PG8_BAR; PG8_MMA(1, 0, At, B0); PG8_MMA(1, 1, At, B1); PG8_BAR; PG8_SCHED;
	v_mfma_f32_16x16x32_bf16 v[14:17], v[134:137], v[252:255], v[14:17]
	s_setprio 0
	ds_read_b128 v[248:251], v148
	ds_read_b128 v[152:155], v148 offset:1024
	ds_read_b128 v[156:159], v148 offset:2048
	ds_read_b128 v[160:163], v148 offset:3072
	ds_read_b128 v[164:167], v149
	ds_read_b128 v[168:171], v149 offset:1024
	ds_read_b128 v[172:175], v149 offset:2048
	ds_read_b128 v[176:179], v149 offset:3072
	ds_read_b128 v[180:183], v147 offset:32768
	ds_read_b128 v[184:187], v147 offset:33792
	ds_read_b128 v[188:191], v147 offset:34816
	ds_read_b128 v[192:195], v147 offset:35840
	ds_read_b128 v[196:199], v147 offset:36864
	ds_read_b128 v[200:203], v147 offset:37888
	ds_read_b128 v[204:207], v147 offset:38912
	ds_read_b128 v[208:211], v147 offset:39936
	s_add_u32 s48, s48, 0x100000
	s_addc_u32 s49, s49, 0
	s_mov_b32 m0, s56
	s_nop 0
	global_load_lds_dwordx4 v1, s[48:49]
	s_nop 0
	s_mov_b32 m0, s57
	s_nop 0
	global_load_lds_dwordx4 v141, s[48:49]
	s_waitcnt vmcnt(8)
	s_waitcnt lgkmcnt(0)
	s_barrier
	s_setprio 1
	s_waitcnt lgkmcnt(7)
	v_mfma_f32_16x16x32_bf16 v[126:129], v[248:251], v[180:183], v[126:129]
	v_mfma_f32_16x16x32_bf16 v[126:129], v[152:155], v[184:187], v[126:129]
	v_mfma_f32_16x16x32_bf16 v[122:125], v[160:163], v[184:187], v[122:125]
	v_mfma_f32_16x16x32_bf16 v[122:125], v[156:159], v[180:183], v[122:125]
	v_mfma_f32_16x16x32_bf16 v[118:121], v[164:167], v[180:183], v[118:121]
	v_mfma_f32_16x16x32_bf16 v[118:121], v[168:171], v[184:187], v[118:121]
	v_mfma_f32_16x16x32_bf16 v[114:117], v[176:179], v[184:187], v[114:117]
	v_mfma_f32_16x16x32_bf16 v[114:117], v[172:175], v[180:183], v[114:117]
	v_mfma_f32_16x16x32_bf16 v[98:101], v[172:175], v[188:191], v[98:101]
	v_mfma_f32_16x16x32_bf16 v[98:101], v[176:179], v[192:195], v[98:101]
	v_mfma_f32_16x16x32_bf16 v[102:105], v[168:171], v[192:195], v[102:105]
	v_mfma_f32_16x16x32_bf16 v[102:105], v[164:167], v[188:191], v[102:105]
	v_mfma_f32_16x16x32_bf16 v[106:109], v[156:159], v[188:191], v[106:109]
	v_mfma_f32_16x16x32_bf16 v[106:109], v[160:163], v[192:195], v[106:109]
	v_mfma_f32_16x16x32_bf16 v[110:113], v[152:155], v[192:195], v[110:113]
	v_mfma_f32_16x16x32_bf16 v[110:113], v[248:251], v[188:191], v[110:113]
	v_mfma_f32_16x16x32_bf16 v[94:97], v[248:251], v[196:199], v[94:97]
	v_mfma_f32_16x16x32_bf16 v[94:97], v[152:155], v[200:203], v[94:97]
	v_mfma_f32_16x16x32_bf16 v[90:93], v[160:163], v[200:203], v[90:93]
	v_mfma_f32_16x16x32_bf16 v[90:93], v[156:159], v[196:199], v[90:93]
	v_mfma_f32_16x16x32_bf16 v[86:89], v[164:167], v[196:199], v[86:89]
	v_mfma_f32_16x16x32_bf16 v[86:89], v[168:171], v[200:203], v[86:89]
	v_mfma_f32_16x16x32_bf16 v[82:85], v[176:179], v[200:203], v[82:85]
	v_mfma_f32_16x16x32_bf16 v[82:85], v[172:175], v[196:199], v[82:85]
	v_mfma_f32_16x16x32_bf16 v[66:69], v[172:175], v[204:207], v[66:69]
	v_mfma_f32_16x16x32_bf16 v[66:69], v[176:179], v[208:211], v[66:69]
	v_mfma_f32_16x16x32_bf16 v[70:73], v[168:171], v[208:211], v[70:73]
	v_mfma_f32_16x16x32_bf16 v[70:73], v[164:167], v[204:207], v[70:73]
	v_mfma_f32_16x16x32_bf16 v[74:77], v[156:159], v[204:207], v[74:77]
	v_mfma_f32_16x16x32_bf16 v[74:77], v[160:163], v[208:211], v[74:77]
	v_mfma_f32_16x16x32_bf16 v[78:81], v[152:155], v[208:211], v[78:81]
	s_setprio 2
	s_barrier
	v_mfma_f32_16x16x32_bf16 v[78:81], v[248:251], v[204:207], v[78:81]
	s_setprio 0
	ds_read_b128 v[180:183], v147 offset:49152
	ds_read_b128 v[184:187], v147 offset:50176
	ds_read_b128 v[188:191], v147 offset:51200
	ds_read_b128 v[192:195], v147 offset:52224
	ds_read_b128 v[196:199], v147 offset:53248
	ds_read_b128 v[200:203], v147 offset:54272
	ds_read_b128 v[252:255], v147 offset:55296
	ds_read_b128 v[208:211], v147 offset:56320
	s_add_u32 s48, s46, 0x80
	s_addc_u32 s49, s47, 0
	s_mov_b32 m0, s61
	s_nop 0
	global_load_lds_dwordx4 v140, s[48:49]
	s_add_u32 s46, s46, 0x100080
	s_mov_b32 m0, s62
	s_nop 0
	global_load_lds_dwordx4 v142, s[48:49]
	s_addc_u32 s47, s47, 0
	s_mov_b32 m0, s65
	s_nop 0
	global_load_lds_dwordx4 v140, s[46:47]
	s_nop 0
	s_mov_b32 m0, s66
	s_nop 0
	global_load_lds_dwordx4 v142, s[46:47]
	s_nop 0
	s_mov_b32 m0, s63
	s_nop 0
	global_load_lds_dwordx4 v1, s[44:45]
	s_nop 0
	s_mov_b32 m0, s64
	s_nop 0
	global_load_lds_dwordx4 v141, s[44:45]
	s_waitcnt vmcnt(8)
	s_waitcnt lgkmcnt(0)
	s_barrier
	s_setprio 1
	s_waitcnt lgkmcnt(7)
	v_mfma_f32_16x16x32_bf16 v[62:65], v[248:251], v[180:183], v[62:65]
	v_mfma_f32_16x16x32_bf16 v[62:65], v[152:155], v[184:187], v[62:65]
	v_mfma_f32_16x16x32_bf16 v[58:61], v[160:163], v[184:187], v[58:61]
	v_mfma_f32_16x16x32_bf16 v[58:61], v[156:159], v[180:183], v[58:61]
	v_mfma_f32_16x16x32_bf16 v[54:57], v[164:167], v[180:183], v[54:57]
	v_mfma_f32_16x16x32_bf16 v[54:57], v[168:171], v[184:187], v[54:57]
	v_mfma_f32_16x16x32_bf16 v[50:53], v[176:179], v[184:187], v[50:53]
	v_mfma_f32_16x16x32_bf16 v[50:53], v[172:175], v[180:183], v[50:53]
	v_mfma_f32_16x16x32_bf16 v[34:37], v[172:175], v[188:191], v[34:37]
	v_mfma_f32_16x16x32_bf16 v[34:37], v[176:179], v[192:195], v[34:37]
	v_mfma_f32_16x16x32_bf16 v[38:41], v[168:171], v[192:195], v[38:41]
	v_mfma_f32_16x16x32_bf16 v[38:41], v[164:167], v[188:191], v[38:41]
	v_mfma_f32_16x16x32_bf16 v[42:45], v[156:159], v[188:191], v[42:45]
	v_mfma_f32_16x16x32_bf16 v[42:45], v[160:163], v[192:195], v[42:45]
	v_mfma_f32_16x16x32_bf16 v[46:49], v[152:155], v[192:195], v[46:49]
	v_mfma_f32_16x16x32_bf16 v[46:49], v[248:251], v[188:191], v[46:49]
	v_mfma_f32_16x16x32_bf16 v[30:33], v[248:251], v[196:199], v[30:33]
	v_mfma_f32_16x16x32_bf16 v[30:33], v[152:155], v[200:203], v[30:33]
	v_mfma_f32_16x16x32_bf16 v[26:29], v[160:163], v[200:203], v[26:29]
	v_mfma_f32_16x16x32_bf16 v[26:29], v[156:159], v[196:199], v[26:29]
	v_mfma_f32_16x16x32_bf16 v[22:25], v[164:167], v[196:199], v[22:25]
	v_mfma_f32_16x16x32_bf16 v[22:25], v[168:171], v[200:203], v[22:25]
	v_mfma_f32_16x16x32_bf16 v[18:21], v[176:179], v[200:203], v[18:21]
	v_mfma_f32_16x16x32_bf16 v[18:21], v[172:175], v[196:199], v[18:21]
	v_mfma_f32_16x16x32_bf16 v[2:5], v[172:175], v[252:255], v[2:5]
	v_mfma_f32_16x16x32_bf16 v[2:5], v[176:179], v[208:211], v[2:5]
	v_mfma_f32_16x16x32_bf16 v[6:9], v[168:171], v[208:211], v[6:9]
	v_mfma_f32_16x16x32_bf16 v[6:9], v[164:167], v[252:255], v[6:9]
	v_mfma_f32_16x16x32_bf16 v[10:13], v[156:159], v[252:255], v[10:13]
	v_mfma_f32_16x16x32_bf16 v[10:13], v[160:163], v[208:211], v[10:13]
	v_mfma_f32_16x16x32_bf16 v[14:17], v[152:155], v[208:211], v[14:17]
	s_setprio 2
	s_barrier
	v_mfma_f32_16x16x32_bf16 v[14:17], v[248:251], v[252:255], v[14:17]
	s_setprio 0
	s_add_i32 s69, s69, 2
	s_add_u32 s53, s53, 0x100
	s_addc_u32 s58, s58, 0
	s_add_u32 s59, s59, 0x100
	s_addc_u32 s68, s68, 0
	s_add_u32 s42, s42, 0x100
	s_addc_u32 s43, s43, 0
	s_cmp_gt_u32 s69, 61
	s_cbranch_scc0 .LBB0_698
	s_and_b64 vcc, exec, s[14:15]
	s_cbranch_vccz .LBB0_701
	s_barrier

; #define PG8_STAGE(bufoff, gbase, voff) do { _Pragma("unroll") for (int _i = 0; _i < 2; ++_i) \
;         asm volatile("s_mov_b32 m0, %2\n\ts_nop 0\n\tglobal_load_lds_dwordx4 %0, %1" :: "v"((voff)[_i]), "s"((const char*)(gbase)), "s"(ldsbase + (unsigned)(bufoff) + ldsw + (unsigned)_i * 8192u) : "memory", "m0"); } while (0)
; #define PG8_LDA(dst, b, h) do { _Pragma("unroll") for (int m = 0; m < 4; ++m) _Pragma("unroll") for (int k = 0; k < 2; ++k) dst[m][k] = *(const PG8_LAS bf16x8*)(lds + PG8_SA(b, h) + aoff + m * 2048 + k * 1024); } while (0)
; #define PG8_LDB(dst, b, h) do { _Pragma("unroll") for (int n = 0; n < 2; ++n) _Pragma("unroll") for (int k = 0; k < 2; ++k) dst[n][k] = *(const PG8_LAS bf16x8*)(lds + PG8_SB(b, h) + boff + n * 2048 + k * 1024); } while (0)
; #define PG8_MMA(ai, bj, At, Bt) do { __builtin_amdgcn_s_setprio(1); _Pragma("unroll") for (int m = 0; m < 4; ++m) _Pragma("unroll") for (int n = 0; n < 2; ++n) _Pragma("unroll") for (int k = 0; k < 2; ++k) \
;         acc[ai][bj][m][n] = __builtin_amdgcn_mfma_f32_16x16x32_bf16(Bt[n][k], At[m][k], acc[ai][bj][m][n], 0, 0, 0); __builtin_amdgcn_s_setprio(0); } while (0)
; #define PG8_WAIT_V(n) asm volatile("s_waitcnt vmcnt(" #n ")" ::: "memory")
; #define PG8_WAIT_L(n) asm volatile("s_waitcnt lgkmcnt(" #n ")" ::: "memory")
; #define PG8_BAR __builtin_amdgcn_s_barrier()
; #define PG8_SCHED __builtin_amdgcn_sched_barrier(0)
; template <class Epi, class Sched, bool ALIGN_EPI = false, bool SP2 = false>
; __device__ __forceinline__ void gemm_phase(PG8_LAS unsigned char* lds, const Gemm g, const Sched& S, const Epi& E) {
;     ...
;             PG8_LDB(B0, 0, 0); PG8_LDB(B1, 0, 1); PG8_SCHED; PG8_LDA(At, 0, 0); PG8_STAGE(PG8_SA(1, 1), a1 + hstep, voffA);
;             PG8_WAIT_V(8); PG8_WAIT_L(0); PG8_BAR; PG8_MMA(0, 0, At, B0); PG8_MMA(0, 1, At, B1); PG8_BAR; PG8_SCHED;
;             PG8_LDA(At, 0, 1); PG8_STAGE(PG8_SB(0, 0), b2, voffB); PG8_STAGE(PG8_SB(0, 1), b2 + hstep, voffB); PG8_STAGE(PG8_SA(0, 0), a2, voffA);
;             PG8_WAIT_V(8); PG8_WAIT_L(0); PG8_BAR; PG8_MMA(1, 0, At, B0); PG8_MMA(1, 1, At, B1); PG8_BAR; PG8_SCHED;
.LBB0_789:
	v_add_u32_e32 v164, 0x10000, v149
	v_add_u32_e32 v180, 0x14000, v149
	s_add_u32 s8, s40, 0x100
	s_waitcnt lgkmcnt(0)
	ds_read_b128 v[152:155], v164
	ds_read_b128 v[156:159], v164 offset:1024
	ds_read_b128 v[160:163], v164 offset:2048
	ds_read_b128 v[164:167], v164 offset:3072
	ds_read_b128 v[168:171], v180
	ds_read_b128 v[172:175], v180 offset:1024
	ds_read_b128 v[176:179], v180 offset:2048
	ds_read_b128 v[180:183], v180 offset:3072
	s_addc_u32 s9, s41, 0
	s_and_b64 s[38:39], s[38:39], exec
	s_cselect_b32 s46, s59, s8
	s_cselect_b32 s47, s17, s9
	s_cselect_b32 s39, s15, s75
	s_cselect_b32 s38, s71, s74
	s_add_u32 s42, s46, 0x80
	s_addc_u32 s43, s47, 0
	s_add_u32 s44, s38, 0x80
	s_addc_u32 s45, s39, 0
	ds_read_b128 v[184:187], v150
	ds_read_b128 v[188:191], v150 offset:1024
	ds_read_b128 v[192:195], v150 offset:2048
	ds_read_b128 v[196:199], v150 offset:3072
	ds_read_b128 v[200:203], v150 offset:4096
	ds_read_b128 v[204:207], v150 offset:5120
	ds_read_b128 v[208:211], v150 offset:6144
	ds_read_b128 v[212:215], v150 offset:7168
	s_add_u32 s40, s40, 0x100080
	s_addc_u32 s41, s41, 0
	s_mov_b32 m0, s64
	s_nop 0
	global_load_lds_dwordx4 v139, s[40:41]
	s_nop 0
	s_mov_b32 m0, s65
	s_nop 0
	global_load_lds_dwordx4 v141, s[40:41]
	s_waitcnt vmcnt(8)
	s_waitcnt lgkmcnt(0)
	s_barrier
	s_setprio 1
	s_waitcnt lgkmcnt(7)
	v_mfma_f32_16x16x32_bf16 v[126:129], v[152:155], v[184:187], v[126:129]
	v_mfma_f32_16x16x32_bf16 v[126:129], v[156:159], v[188:191], v[126:129]
	v_mfma_f32_16x16x32_bf16 v[122:125], v[164:167], v[188:191], v[122:125]
	v_mfma_f32_16x16x32_bf16 v[122:125], v[160:163], v[184:187], v[122:125]
	v_mfma_f32_16x16x32_bf16 v[118:121], v[168:171], v[184:187], v[118:121]
	v_mfma_f32_16x16x32_bf16 v[118:121], v[172:175], v[188:191], v[118:121]
	v_mfma_f32_16x16x32_bf16 v[114:117], v[180:183], v[188:191], v[114:117]
	v_mfma_f32_16x16x32_bf16 v[114:117], v[176:179], v[184:187], v[114:117]
	v_mfma_f32_16x16x32_bf16 v[98:101], v[176:179], v[192:195], v[98:101]
	v_mfma_f32_16x16x32_bf16 v[98:101], v[180:183], v[196:199], v[98:101]
	v_mfma_f32_16x16x32_bf16 v[102:105], v[172:175], v[196:199], v[102:105]
	v_mfma_f32_16x16x32_bf16 v[102:105], v[168:171], v[192:195], v[102:105]
	v_mfma_f32_16x16x32_bf16 v[106:109], v[160:163], v[192:195], v[106:109]
	v_mfma_f32_16x16x32_bf16 v[106:109], v[164:167], v[196:199], v[106:109]
	v_mfma_f32_16x16x32_bf16 v[110:113], v[156:159], v[196:199], v[110:113]
	v_mfma_f32_16x16x32_bf16 v[110:113], v[152:155], v[192:195], v[110:113]
	v_mfma_f32_16x16x32_bf16 v[94:97], v[152:155], v[200:203], v[94:97]
	v_mfma_f32_16x16x32_bf16 v[94:97], v[156:159], v[204:207], v[94:97]
	v_mfma_f32_16x16x32_bf16 v[90:93], v[164:167], v[204:207], v[90:93]
	v_mfma_f32_16x16x32_bf16 v[90:93], v[160:163], v[200:203], v[90:93]
	v_mfma_f32_16x16x32_bf16 v[86:89], v[168:171], v[200:203], v[86:89]
	v_mfma_f32_16x16x32_bf16 v[86:89], v[172:175], v[204:207], v[86:89]
	v_mfma_f32_16x16x32_bf16 v[82:85], v[180:183], v[204:207], v[82:85]
	v_mfma_f32_16x16x32_bf16 v[82:85], v[176:179], v[200:203], v[82:85]
	v_mfma_f32_16x16x32_bf16 v[66:69], v[176:179], v[208:211], v[66:69]
	v_mfma_f32_16x16x32_bf16 v[66:69], v[180:183], v[212:215], v[66:69]
	v_mfma_f32_16x16x32_bf16 v[70:73], v[172:175], v[212:215], v[70:73]
	v_mfma_f32_16x16x32_bf16 v[70:73], v[168:171], v[208:211], v[70:73]
	v_mfma_f32_16x16x32_bf16 v[74:77], v[160:163], v[208:211], v[74:77]
	v_mfma_f32_16x16x32_bf16 v[74:77], v[164:167], v[212:215], v[74:77]
	v_mfma_f32_16x16x32_bf16 v[78:81], v[156:159], v[212:215], v[78:81]
	s_setprio 2
	s_barrier
	v_mfma_f32_16x16x32_bf16 v[78:81], v[152:155], v[208:211], v[78:81]
	s_setprio 0
	ds_read_b128 v[184:187], v150 offset:16384
	ds_read_b128 v[188:191], v150 offset:17408
	ds_read_b128 v[192:195], v150 offset:18432
	ds_read_b128 v[196:199], v150 offset:19456
	ds_read_b128 v[200:203], v150 offset:20480
	ds_read_b128 v[204:207], v150 offset:21504
	ds_read_b128 v[252:255], v150 offset:22528
	ds_read_b128 v[212:215], v150 offset:23552
	s_mov_b32 m0, s49
	s_nop 0
	global_load_lds_dwordx4 v140, s[38:39]
	s_add_u32 s40, s38, 0x100000
	s_mov_b32 m0, s50
	s_nop 0
	global_load_lds_dwordx4 v142, s[38:39]
	s_addc_u32 s41, s39, 0
	s_mov_b32 m0, s51
	s_nop 0
	global_load_lds_dwordx4 v140, s[40:41]
	s_nop 0
	s_mov_b32 m0, s52
	s_nop 0
	global_load_lds_dwordx4 v142, s[40:41]
	s_nop 0
	s_mov_b32 m0, s37
	s_nop 0
	global_load_lds_dwordx4 v139, s[46:47]
	s_nop 0
	s_mov_b32 m0, s53
	s_nop 0
	global_load_lds_dwordx4 v141, s[46:47]
	s_waitcnt vmcnt(8)
	s_waitcnt lgkmcnt(0)
	s_barrier
	s_setprio 1
	s_waitcnt lgkmcnt(7)
	v_mfma_f32_16x16x32_bf16 v[62:65], v[152:155], v[184:187], v[62:65]
	v_mfma_f32_16x16x32_bf16 v[62:65], v[156:159], v[188:191], v[62:65]
	v_mfma_f32_16x16x32_bf16 v[58:61], v[164:167], v[188:191], v[58:61]
	v_mfma_f32_16x16x32_bf16 v[58:61], v[160:163], v[184:187], v[58:61]
	v_mfma_f32_16x16x32_bf16 v[54:57], v[168:171], v[184:187], v[54:57]
	v_mfma_f32_16x16x32_bf16 v[54:57], v[172:175], v[188:191], v[54:57]
	v_mfma_f32_16x16x32_bf16 v[50:53], v[180:183], v[188:191], v[50:53]
	v_mfma_f32_16x16x32_bf16 v[50:53], v[176:179], v[184:187], v[50:53]
	v_mfma_f32_16x16x32_bf16 v[34:37], v[176:179], v[192:195], v[34:37]
	v_mfma_f32_16x16x32_bf16 v[34:37], v[180:183], v[196:199], v[34:37]
	v_mfma_f32_16x16x32_bf16 v[38:41], v[172:175], v[196:199], v[38:41]
	v_mfma_f32_16x16x32_bf16 v[38:41], v[168:171], v[192:195], v[38:41]
	v_mfma_f32_16x16x32_bf16 v[42:45], v[160:163], v[192:195], v[42:45]
	v_mfma_f32_16x16x32_bf16 v[42:45], v[164:167], v[196:199], v[42:45]
	v_mfma_f32_16x16x32_bf16 v[46:49], v[156:159], v[196:199], v[46:49]
	v_mfma_f32_16x16x32_bf16 v[46:49], v[152:155], v[192:195], v[46:49]
	v_mfma_f32_16x16x32_bf16 v[30:33], v[152:155], v[200:203], v[30:33]
	v_mfma_f32_16x16x32_bf16 v[30:33], v[156:159], v[204:207], v[30:33]
	v_mfma_f32_16x16x32_bf16 v[26:29], v[164:167], v[204:207], v[26:29]
	v_mfma_f32_16x16x32_bf16 v[26:29], v[160:163], v[200:203], v[26:29]
	v_mfma_f32_16x16x32_bf16 v[22:25], v[168:171], v[200:203], v[22:25]
	v_mfma_f32_16x16x32_bf16 v[22:25], v[172:175], v[204:207], v[22:25]
	v_mfma_f32_16x16x32_bf16 v[18:21], v[180:183], v[204:207], v[18:21]
	v_mfma_f32_16x16x32_bf16 v[18:21], v[176:179], v[200:203], v[18:21]
	v_mfma_f32_16x16x32_bf16 v[2:5], v[176:179], v[252:255], v[2:5]
	v_mfma_f32_16x16x32_bf16 v[2:5], v[180:183], v[212:215], v[2:5]
	v_mfma_f32_16x16x32_bf16 v[6:9], v[172:175], v[212:215], v[6:9]
	v_mfma_f32_16x16x32_bf16 v[6:9], v[168:171], v[252:255], v[6:9]
	v_mfma_f32_16x16x32_bf16 v[10:13], v[160:163], v[252:255], v[10:13]
	v_mfma_f32_16x16x32_bf16 v[10:13], v[164:167], v[212:215], v[10:13]
	v_mfma_f32_16x16x32_bf16 v[14:17], v[156:159], v[212:215], v[14:17]
	s_setprio 2
	s_barrier
; #define PG8_STAGE(bufoff, gbase, voff) do { _Pragma("unroll") for (int _i = 0; _i < 2; ++_i) \
;         asm volatile("s_mov_b32 m0, %2\n\ts_nop 0\n\tglobal_load_lds_dwordx4 %0, %1" :: "v"((voff)[_i]), "s"((const char*)(gbase)), "s"(ldsbase + (unsigned)(bufoff) + ldsw + (unsigned)_i * 8192u) : "memory", "m0"); } while (0)
; #define PG8_LDA(dst, b, h) do { _Pragma("unroll") for (int m = 0; m < 4; ++m) _Pragma("unroll") for (int k = 0; k < 2; ++k) dst[m][k] = *(const PG8_LAS bf16x8*)(lds + PG8_SA(b, h) + aoff + m * 2048 + k * 1024); } while (0)
; #define PG8_LDB(dst, b, h) do { _Pragma("unroll") for (int n = 0; n < 2; ++n) _Pragma("unroll") for (int k = 0; k < 2; ++k) dst[n][k] = *(const PG8_LAS bf16x8*)(lds + PG8_SB(b, h) + boff + n * 2048 + k * 1024); } while (0)
; #define PG8_MMA(ai, bj, At, Bt) do { __builtin_amdgcn_s_setprio(1); _Pragma("unroll") for (int m = 0; m < 4; ++m) _Pragma("unroll") for (int n = 0; n < 2; ++n) _Pragma("unroll") for (int k = 0; k < 2; ++k) \
;         acc[ai][bj][m][n] = __builtin_amdgcn_mfma_f32_16x16x32_bf16(Bt[n][k], At[m][k], acc[ai][bj][m][n], 0, 0, 0); __builtin_amdgcn_s_setprio(0); } while (0)
; #define PG8_WAIT_V(n) asm volatile("s_waitcnt vmcnt(" #n ")" ::: "memory")
; #define PG8_WAIT_L(n) asm volatile("s_waitcnt lgkmcnt(" #n ")" ::: "memory")
; #define PG8_BAR __builtin_amdgcn_s_barrier()
; #define PG8_SCHED __builtin_amdgcn_sched_barrier(0)
; template <class Epi, class Sched, bool ALIGN_EPI = false, bool SP2 = false>
; __device__ __forceinline__ void gemm_phase(PG8_LAS unsigned char* lds, const Gemm g, const Sched& S, const Epi& E) {
;     ...
;         for (int t = 0; t < nt; t += 2) {
;             const bool last = (t == nt - 2);
;     ...
;             PG8_LDB(B0, 1, 0); PG8_LDB(B1, 1, 1); PG8_SCHED; PG8_LDA(At, 1, 0); PG8_STAGE(PG8_SA(0, 1), a2 + hstep, voffA);
;             PG8_WAIT_V(8); PG8_WAIT_L(0); PG8_BAR; PG8_MMA(0, 0, At, B0); PG8_MMA(0, 1, At, B1); PG8_BAR; PG8_SCHED;
;             PG8_LDA(At, 1, 1); PG8_STAGE(PG8_SB(1, 0), b3, voffB); PG8_STAGE(PG8_SB(1, 1), b3 + hstep, voffB); PG8_STAGE(PG8_SA(1, 0), a3, voffA);
;             PG8_WAIT_V(8); PG8_WAIT_L(0); PG8_BAR; PG8_MMA(1, 0, At, B0); PG8_MMA(1, 1, At, B1); PG8_BAR; PG8_SCHED;
	v_mfma_f32_16x16x32_bf16 v[14:17], v[152:155], v[252:255], v[14:17]
	s_setprio 0
	v_add_u32_e32 v164, 0x18000, v149
	v_add_u32_e32 v180, 0x1c000, v149
	ds_read_b128 v[248:251], v164
	ds_read_b128 v[156:159], v164 offset:1024
	ds_read_b128 v[160:163], v164 offset:2048
	ds_read_b128 v[164:167], v164 offset:3072
	ds_read_b128 v[168:171], v180
	ds_read_b128 v[172:175], v180 offset:1024
	ds_read_b128 v[176:179], v180 offset:2048
	ds_read_b128 v[180:183], v180 offset:3072
	ds_read_b128 v[184:187], v150 offset:32768
	ds_read_b128 v[188:191], v150 offset:33792
	ds_read_b128 v[192:195], v150 offset:34816
	ds_read_b128 v[196:199], v150 offset:35840
	ds_read_b128 v[200:203], v150 offset:36864
	ds_read_b128 v[204:207], v150 offset:37888
	ds_read_b128 v[208:211], v150 offset:38912
	ds_read_b128 v[212:215], v150 offset:39936
	s_add_u32 s40, s46, 0x100000
	s_addc_u32 s41, s47, 0
	s_mov_b32 m0, s54
	s_nop 0
	global_load_lds_dwordx4 v139, s[40:41]
	s_nop 0
	s_mov_b32 m0, s55
	s_nop 0
	global_load_lds_dwordx4 v141, s[40:41]
	s_waitcnt vmcnt(8)
	s_waitcnt lgkmcnt(0)
	s_barrier
	s_setprio 1
	s_waitcnt lgkmcnt(7)
	v_mfma_f32_16x16x32_bf16 v[126:129], v[248:251], v[184:187], v[126:129]
	v_mfma_f32_16x16x32_bf16 v[126:129], v[156:159], v[188:191], v[126:129]
	v_mfma_f32_16x16x32_bf16 v[122:125], v[164:167], v[188:191], v[122:125]
	v_mfma_f32_16x16x32_bf16 v[122:125], v[160:163], v[184:187], v[122:125]
	v_mfma_f32_16x16x32_bf16 v[118:121], v[168:171], v[184:187], v[118:121]
	v_mfma_f32_16x16x32_bf16 v[118:121], v[172:175], v[188:191], v[118:121]
	v_mfma_f32_16x16x32_bf16 v[114:117], v[180:183], v[188:191], v[114:117]
	v_mfma_f32_16x16x32_bf16 v[114:117], v[176:179], v[184:187], v[114:117]
	v_mfma_f32_16x16x32_bf16 v[98:101], v[176:179], v[192:195], v[98:101]
	v_mfma_f32_16x16x32_bf16 v[98:101], v[180:183], v[196:199], v[98:101]
	v_mfma_f32_16x16x32_bf16 v[102:105], v[172:175], v[196:199], v[102:105]
	v_mfma_f32_16x16x32_bf16 v[102:105], v[168:171], v[192:195], v[102:105]
	v_mfma_f32_16x16x32_bf16 v[106:109], v[160:163], v[192:195], v[106:109]
	v_mfma_f32_16x16x32_bf16 v[106:109], v[164:167], v[196:199], v[106:109]
	v_mfma_f32_16x16x32_bf16 v[110:113], v[156:159], v[196:199], v[110:113]
	v_mfma_f32_16x16x32_bf16 v[110:113], v[248:251], v[192:195], v[110:113]
	v_mfma_f32_16x16x32_bf16 v[94:97], v[248:251], v[200:203], v[94:97]
	v_mfma_f32_16x16x32_bf16 v[94:97], v[156:159], v[204:207], v[94:97]
	v_mfma_f32_16x16x32_bf16 v[90:93], v[164:167], v[204:207], v[90:93]
	v_mfma_f32_16x16x32_bf16 v[90:93], v[160:163], v[200:203], v[90:93]
	v_mfma_f32_16x16x32_bf16 v[86:89], v[168:171], v[200:203], v[86:89]
	v_mfma_f32_16x16x32_bf16 v[86:89], v[172:175], v[204:207], v[86:89]
	v_mfma_f32_16x16x32_bf16 v[82:85], v[180:183], v[204:207], v[82:85]
	v_mfma_f32_16x16x32_bf16 v[82:85], v[176:179], v[200:203], v[82:85]
	v_mfma_f32_16x16x32_bf16 v[66:69], v[176:179], v[208:211], v[66:69]
	v_mfma_f32_16x16x32_bf16 v[66:69], v[180:183], v[212:215], v[66:69]
	v_mfma_f32_16x16x32_bf16 v[70:73], v[172:175], v[212:215], v[70:73]
	v_mfma_f32_16x16x32_bf16 v[70:73], v[168:171], v[208:211], v[70:73]
	v_mfma_f32_16x16x32_bf16 v[74:77], v[160:163], v[208:211], v[74:77]
	v_mfma_f32_16x16x32_bf16 v[74:77], v[164:167], v[212:215], v[74:77]
	v_mfma_f32_16x16x32_bf16 v[78:81], v[156:159], v[212:215], v[78:81]
	s_setprio 2
	s_barrier
	v_mfma_f32_16x16x32_bf16 v[78:81], v[248:251], v[208:211], v[78:81]
	s_setprio 0
	ds_read_b128 v[184:187], v150 offset:49152
	ds_read_b128 v[188:191], v150 offset:50176
	ds_read_b128 v[192:195], v150 offset:51200
	ds_read_b128 v[196:199], v150 offset:52224
	ds_read_b128 v[200:203], v150 offset:53248
	ds_read_b128 v[204:207], v150 offset:54272
	ds_read_b128 v[252:255], v150 offset:55296
	ds_read_b128 v[212:215], v150 offset:56320
	s_mov_b32 m0, s56
	s_nop 0
	global_load_lds_dwordx4 v140, s[44:45]
	s_add_u32 s38, s38, 0x100080
	s_mov_b32 m0, s57
	s_nop 0
	global_load_lds_dwordx4 v142, s[44:45]
	s_addc_u32 s39, s39, 0
	s_mov_b32 m0, s62
	s_nop 0
	global_load_lds_dwordx4 v140, s[38:39]
	s_nop 0
	s_mov_b32 m0, s63
	s_nop 0
	global_load_lds_dwordx4 v142, s[38:39]
	s_nop 0
	s_mov_b32 m0, s60
	s_nop 0
	global_load_lds_dwordx4 v139, s[42:43]
	s_nop 0
	s_mov_b32 m0, s61
	s_nop 0
	global_load_lds_dwordx4 v141, s[42:43]
	s_waitcnt vmcnt(8)
	s_waitcnt lgkmcnt(0)
	s_barrier
	s_setprio 1
	s_waitcnt lgkmcnt(7)
	v_mfma_f32_16x16x32_bf16 v[62:65], v[248:251], v[184:187], v[62:65]
	v_mfma_f32_16x16x32_bf16 v[62:65], v[156:159], v[188:191], v[62:65]
	v_mfma_f32_16x16x32_bf16 v[58:61], v[164:167], v[188:191], v[58:61]
	v_mfma_f32_16x16x32_bf16 v[58:61], v[160:163], v[184:187], v[58:61]
	v_mfma_f32_16x16x32_bf16 v[54:57], v[168:171], v[184:187], v[54:57]
	v_mfma_f32_16x16x32_bf16 v[54:57], v[172:175], v[188:191], v[54:57]
	v_mfma_f32_16x16x32_bf16 v[50:53], v[180:183], v[188:191], v[50:53]
	v_mfma_f32_16x16x32_bf16 v[50:53], v[176:179], v[184:187], v[50:53]
	v_mfma_f32_16x16x32_bf16 v[34:37], v[176:179], v[192:195], v[34:37]
	v_mfma_f32_16x16x32_bf16 v[34:37], v[180:183], v[196:199], v[34:37]
	v_mfma_f32_16x16x32_bf16 v[38:41], v[172:175], v[196:199], v[38:41]
	v_mfma_f32_16x16x32_bf16 v[38:41], v[168:171], v[192:195], v[38:41]
	v_mfma_f32_16x16x32_bf16 v[42:45], v[160:163], v[192:195], v[42:45]
	v_mfma_f32_16x16x32_bf16 v[42:45], v[164:167], v[196:199], v[42:45]
	v_mfma_f32_16x16x32_bf16 v[46:49], v[156:159], v[196:199], v[46:49]
	v_mfma_f32_16x16x32_bf16 v[46:49], v[248:251], v[192:195], v[46:49]
	v_mfma_f32_16x16x32_bf16 v[30:33], v[248:251], v[200:203], v[30:33]
	v_mfma_f32_16x16x32_bf16 v[30:33], v[156:159], v[204:207], v[30:33]
	v_mfma_f32_16x16x32_bf16 v[26:29], v[164:167], v[204:207], v[26:29]
	v_mfma_f32_16x16x32_bf16 v[26:29], v[160:163], v[200:203], v[26:29]
	v_mfma_f32_16x16x32_bf16 v[22:25], v[168:171], v[200:203], v[22:25]
	v_mfma_f32_16x16x32_bf16 v[22:25], v[172:175], v[204:207], v[22:25]
	v_mfma_f32_16x16x32_bf16 v[18:21], v[180:183], v[204:207], v[18:21]
	v_mfma_f32_16x16x32_bf16 v[18:21], v[176:179], v[200:203], v[18:21]
	v_mfma_f32_16x16x32_bf16 v[2:5], v[176:179], v[252:255], v[2:5]
	v_mfma_f32_16x16x32_bf16 v[2:5], v[180:183], v[212:215], v[2:5]
	v_mfma_f32_16x16x32_bf16 v[6:9], v[172:175], v[212:215], v[6:9]
	v_mfma_f32_16x16x32_bf16 v[6:9], v[168:171], v[252:255], v[6:9]
	v_mfma_f32_16x16x32_bf16 v[10:13], v[160:163], v[252:255], v[10:13]
	v_mfma_f32_16x16x32_bf16 v[10:13], v[164:167], v[212:215], v[10:13]
	v_mfma_f32_16x16x32_bf16 v[14:17], v[156:159], v[212:215], v[14:17]
	s_setprio 2
	s_barrier
	v_mfma_f32_16x16x32_bf16 v[14:17], v[248:251], v[252:255], v[14:17]
	s_setprio 0
	s_add_i32 s76, s76, 2
	s_add_u32 s74, s74, 0x100
	s_addc_u32 s75, s75, 0
	s_cmp_gt_u32 s76, 61
	s_cbranch_scc1 .LBB0_780
	s_mov_b64 s[40:41], s[8:9]
	s_branch .LBB0_784

; #define PG8_STAGE(bufoff, gbase, voff) do { _Pragma("unroll") for (int _i = 0; _i < 2; ++_i) \
;         asm volatile("s_mov_b32 m0, %2\n\ts_nop 0\n\tglobal_load_lds_dwordx4 %0, %1" :: "v"((voff)[_i]), "s"((const char*)(gbase)), "s"(ldsbase + (unsigned)(bufoff) + ldsw + (unsigned)_i * 8192u) : "memory", "m0"); } while (0)
; #define PG8_LDA(dst, b, h) do { _Pragma("unroll") for (int m = 0; m < 4; ++m) _Pragma("unroll") for (int k = 0; k < 2; ++k) dst[m][k] = *(const PG8_LAS bf16x8*)(lds + PG8_SA(b, h) + aoff + m * 2048 + k * 1024); } while (0)
; #define PG8_LDB(dst, b, h) do { _Pragma("unroll") for (int n = 0; n < 2; ++n) _Pragma("unroll") for (int k = 0; k < 2; ++k) dst[n][k] = *(const PG8_LAS bf16x8*)(lds + PG8_SB(b, h) + boff + n * 2048 + k * 1024); } while (0)
; #define PG8_MMA(ai, bj, At, Bt) do { __builtin_amdgcn_s_setprio(1); _Pragma("unroll") for (int m = 0; m < 4; ++m) _Pragma("unroll") for (int n = 0; n < 2; ++n) _Pragma("unroll") for (int k = 0; k < 2; ++k) \
;         acc[ai][bj][m][n] = __builtin_amdgcn_mfma_f32_16x16x32_bf16(Bt[n][k], At[m][k], acc[ai][bj][m][n], 0, 0, 0); __builtin_amdgcn_s_setprio(0); } while (0)
; #define PG8_WAIT_V(n) asm volatile("s_waitcnt vmcnt(" #n ")" ::: "memory")
; #define PG8_WAIT_L(n) asm volatile("s_waitcnt lgkmcnt(" #n ")" ::: "memory")
; #define PG8_BAR __builtin_amdgcn_s_barrier()
; #define PG8_SCHED __builtin_amdgcn_sched_barrier(0)
; template <class Epi, class Sched, bool ALIGN_EPI = false, bool SP2 = false>
; __device__ __forceinline__ void gemm_phase(PG8_LAS unsigned char* lds, const Gemm g, const Sched& S, const Epi& E) {
;     ...
;             PG8_LDB(B0, 0, 0); PG8_LDB(B1, 0, 1); PG8_SCHED; PG8_LDA(At, 0, 0); PG8_STAGE(PG8_SA(1, 1), a1 + hstep, voffA);
;             PG8_WAIT_V(8); PG8_WAIT_L(0); PG8_BAR; PG8_MMA(0, 0, At, B0); PG8_MMA(0, 1, At, B1); PG8_BAR; PG8_SCHED;
;             PG8_LDA(At, 0, 1); PG8_STAGE(PG8_SB(0, 0), b2, voffB); PG8_STAGE(PG8_SB(0, 1), b2 + hstep, voffB); PG8_STAGE(PG8_SA(0, 0), a2, voffA);
;             PG8_WAIT_V(8); PG8_WAIT_L(0); PG8_BAR; PG8_MMA(1, 0, At, B0); PG8_MMA(1, 1, At, B1); PG8_BAR; PG8_SCHED;
.LBB0_873:
	ds_read_b128 v[134:137], v145
	ds_read_b128 v[150:153], v145 offset:1024
	ds_read_b128 v[154:157], v145 offset:2048
	ds_read_b128 v[158:161], v145 offset:3072
	ds_read_b128 v[162:165], v146
	ds_read_b128 v[166:169], v146 offset:1024
	ds_read_b128 v[170:173], v146 offset:2048
	ds_read_b128 v[174:177], v146 offset:3072
	s_add_u32 s38, s36, 0x100
	s_addc_u32 s39, s37, 0
	s_cmpk_eq_i32 s69, 0xa8
	s_cselect_b32 s44, s4, s38
	s_cselect_b32 s45, s5, s39
	s_cselect_b32 s42, s22, s67
	s_cselect_b32 s43, s23, s68
	s_add_u32 s40, s44, 0x80
	s_addc_u32 s41, s45, 0
	ds_read_b128 v[178:181], v147
	ds_read_b128 v[182:185], v147 offset:1024
	ds_read_b128 v[186:189], v147 offset:2048
	ds_read_b128 v[190:193], v147 offset:3072
	ds_read_b128 v[194:197], v147 offset:4096
	ds_read_b128 v[198:201], v147 offset:5120
	ds_read_b128 v[202:205], v147 offset:6144
	ds_read_b128 v[206:209], v147 offset:7168
	s_add_u32 s36, s36, 0x2b0080
	s_addc_u32 s37, s37, 0
	s_mov_b32 m0, s60
	s_nop 0
	global_load_lds_dwordx4 v1, s[36:37]
	s_nop 0
	s_mov_b32 m0, s61
	s_nop 0
	global_load_lds_dwordx4 v141, s[36:37]
	s_waitcnt vmcnt(8)
	s_waitcnt lgkmcnt(0)
	s_barrier
	s_setprio 1
	s_waitcnt lgkmcnt(7)
	v_mfma_f32_16x16x32_bf16 v[126:129], v[134:137], v[178:181], v[126:129]
	v_mfma_f32_16x16x32_bf16 v[126:129], v[150:153], v[182:185], v[126:129]
	v_mfma_f32_16x16x32_bf16 v[122:125], v[158:161], v[182:185], v[122:125]
	v_mfma_f32_16x16x32_bf16 v[122:125], v[154:157], v[178:181], v[122:125]
	v_mfma_f32_16x16x32_bf16 v[118:121], v[162:165], v[178:181], v[118:121]
	v_mfma_f32_16x16x32_bf16 v[118:121], v[166:169], v[182:185], v[118:121]
	v_mfma_f32_16x16x32_bf16 v[114:117], v[174:177], v[182:185], v[114:117]
	v_mfma_f32_16x16x32_bf16 v[114:117], v[170:173], v[178:181], v[114:117]
	v_mfma_f32_16x16x32_bf16 v[98:101], v[170:173], v[186:189], v[98:101]
	v_mfma_f32_16x16x32_bf16 v[98:101], v[174:177], v[190:193], v[98:101]
	v_mfma_f32_16x16x32_bf16 v[102:105], v[166:169], v[190:193], v[102:105]
	v_mfma_f32_16x16x32_bf16 v[102:105], v[162:165], v[186:189], v[102:105]
	v_mfma_f32_16x16x32_bf16 v[106:109], v[154:157], v[186:189], v[106:109]
	v_mfma_f32_16x16x32_bf16 v[106:109], v[158:161], v[190:193], v[106:109]
	v_mfma_f32_16x16x32_bf16 v[110:113], v[150:153], v[190:193], v[110:113]
	v_mfma_f32_16x16x32_bf16 v[110:113], v[134:137], v[186:189], v[110:113]
	v_mfma_f32_16x16x32_bf16 v[94:97], v[134:137], v[194:197], v[94:97]
	v_mfma_f32_16x16x32_bf16 v[94:97], v[150:153], v[198:201], v[94:97]
	v_mfma_f32_16x16x32_bf16 v[90:93], v[158:161], v[198:201], v[90:93]
	v_mfma_f32_16x16x32_bf16 v[90:93], v[154:157], v[194:197], v[90:93]
	v_mfma_f32_16x16x32_bf16 v[86:89], v[162:165], v[194:197], v[86:89]
	v_mfma_f32_16x16x32_bf16 v[86:89], v[166:169], v[198:201], v[86:89]
	v_mfma_f32_16x16x32_bf16 v[82:85], v[174:177], v[198:201], v[82:85]
	v_mfma_f32_16x16x32_bf16 v[82:85], v[170:173], v[194:197], v[82:85]
	v_mfma_f32_16x16x32_bf16 v[66:69], v[170:173], v[202:205], v[66:69]
	v_mfma_f32_16x16x32_bf16 v[66:69], v[174:177], v[206:209], v[66:69]
	v_mfma_f32_16x16x32_bf16 v[70:73], v[166:169], v[206:209], v[70:73]
	v_mfma_f32_16x16x32_bf16 v[70:73], v[162:165], v[202:205], v[70:73]
	v_mfma_f32_16x16x32_bf16 v[74:77], v[154:157], v[202:205], v[74:77]
	v_mfma_f32_16x16x32_bf16 v[74:77], v[158:161], v[206:209], v[74:77]
	v_mfma_f32_16x16x32_bf16 v[78:81], v[150:153], v[206:209], v[78:81]
	s_setprio 2
	s_barrier
	v_mfma_f32_16x16x32_bf16 v[78:81], v[134:137], v[202:205], v[78:81]
	s_setprio 0
	ds_read_b128 v[178:181], v147 offset:16384
	ds_read_b128 v[182:185], v147 offset:17408
	ds_read_b128 v[186:189], v147 offset:18432
	ds_read_b128 v[190:193], v147 offset:19456
	ds_read_b128 v[194:197], v147 offset:20480
	ds_read_b128 v[198:201], v147 offset:21504
	ds_read_b128 v[252:255], v147 offset:22528
	ds_read_b128 v[206:209], v147 offset:23552
	s_mov_b32 m0, s47
	s_nop 0
	global_load_lds_dwordx4 v140, s[42:43]
	s_add_u32 s36, s42, 0x2b0000
	s_mov_b32 m0, s48
	s_nop 0
	global_load_lds_dwordx4 v142, s[42:43]
	s_addc_u32 s37, s43, 0
	s_mov_b32 m0, s49
	s_nop 0
	global_load_lds_dwordx4 v140, s[36:37]
	s_nop 0
	s_mov_b32 m0, s50
	s_nop 0
	global_load_lds_dwordx4 v142, s[36:37]
	s_nop 0
	s_mov_b32 m0, s46
	s_nop 0
	global_load_lds_dwordx4 v1, s[44:45]
	s_nop 0
	s_mov_b32 m0, s51
	s_nop 0
	global_load_lds_dwordx4 v141, s[44:45]
	s_waitcnt vmcnt(8)
	s_waitcnt lgkmcnt(0)
	s_barrier
	s_setprio 1
	s_waitcnt lgkmcnt(7)
	v_mfma_f32_16x16x32_bf16 v[62:65], v[134:137], v[178:181], v[62:65]
	v_mfma_f32_16x16x32_bf16 v[62:65], v[150:153], v[182:185], v[62:65]
	v_mfma_f32_16x16x32_bf16 v[58:61], v[158:161], v[182:185], v[58:61]
	v_mfma_f32_16x16x32_bf16 v[58:61], v[154:157], v[178:181], v[58:61]
	v_mfma_f32_16x16x32_bf16 v[54:57], v[162:165], v[178:181], v[54:57]
	v_mfma_f32_16x16x32_bf16 v[54:57], v[166:169], v[182:185], v[54:57]
	v_mfma_f32_16x16x32_bf16 v[50:53], v[174:177], v[182:185], v[50:53]
	v_mfma_f32_16x16x32_bf16 v[50:53], v[170:173], v[178:181], v[50:53]
	v_mfma_f32_16x16x32_bf16 v[34:37], v[170:173], v[186:189], v[34:37]
	v_mfma_f32_16x16x32_bf16 v[34:37], v[174:177], v[190:193], v[34:37]
	v_mfma_f32_16x16x32_bf16 v[38:41], v[166:169], v[190:193], v[38:41]
	v_mfma_f32_16x16x32_bf16 v[38:41], v[162:165], v[186:189], v[38:41]
	v_mfma_f32_16x16x32_bf16 v[42:45], v[154:157], v[186:189], v[42:45]
	v_mfma_f32_16x16x32_bf16 v[42:45], v[158:161], v[190:193], v[42:45]
	v_mfma_f32_16x16x32_bf16 v[46:49], v[150:153], v[190:193], v[46:49]
	v_mfma_f32_16x16x32_bf16 v[46:49], v[134:137], v[186:189], v[46:49]
	v_mfma_f32_16x16x32_bf16 v[30:33], v[134:137], v[194:197], v[30:33]
	v_mfma_f32_16x16x32_bf16 v[30:33], v[150:153], v[198:201], v[30:33]
	v_mfma_f32_16x16x32_bf16 v[26:29], v[158:161], v[198:201], v[26:29]
	v_mfma_f32_16x16x32_bf16 v[26:29], v[154:157], v[194:197], v[26:29]
	v_mfma_f32_16x16x32_bf16 v[22:25], v[162:165], v[194:197], v[22:25]
	v_mfma_f32_16x16x32_bf16 v[22:25], v[166:169], v[198:201], v[22:25]
	v_mfma_f32_16x16x32_bf16 v[18:21], v[174:177], v[198:201], v[18:21]
	v_mfma_f32_16x16x32_bf16 v[18:21], v[170:173], v[194:197], v[18:21]
	v_mfma_f32_16x16x32_bf16 v[2:5], v[170:173], v[252:255], v[2:5]
	v_mfma_f32_16x16x32_bf16 v[2:5], v[174:177], v[206:209], v[2:5]
	v_mfma_f32_16x16x32_bf16 v[6:9], v[166:169], v[206:209], v[6:9]
	v_mfma_f32_16x16x32_bf16 v[6:9], v[162:165], v[252:255], v[6:9]
	v_mfma_f32_16x16x32_bf16 v[10:13], v[154:157], v[252:255], v[10:13]
	v_mfma_f32_16x16x32_bf16 v[10:13], v[158:161], v[206:209], v[10:13]
	v_mfma_f32_16x16x32_bf16 v[14:17], v[150:153], v[206:209], v[14:17]
	s_setprio 2
	s_barrier
; #define PG8_STAGE(bufoff, gbase, voff) do { _Pragma("unroll") for (int _i = 0; _i < 2; ++_i) \
;         asm volatile("s_mov_b32 m0, %2\n\ts_nop 0\n\tglobal_load_lds_dwordx4 %0, %1" :: "v"((voff)[_i]), "s"((const char*)(gbase)), "s"(ldsbase + (unsigned)(bufoff) + ldsw + (unsigned)_i * 8192u) : "memory", "m0"); } while (0)
; #define PG8_LDA(dst, b, h) do { _Pragma("unroll") for (int m = 0; m < 4; ++m) _Pragma("unroll") for (int k = 0; k < 2; ++k) dst[m][k] = *(const PG8_LAS bf16x8*)(lds + PG8_SA(b, h) + aoff + m * 2048 + k * 1024); } while (0)
; #define PG8_LDB(dst, b, h) do { _Pragma("unroll") for (int n = 0; n < 2; ++n) _Pragma("unroll") for (int k = 0; k < 2; ++k) dst[n][k] = *(const PG8_LAS bf16x8*)(lds + PG8_SB(b, h) + boff + n * 2048 + k * 1024); } while (0)
; #define PG8_MMA(ai, bj, At, Bt) do { __builtin_amdgcn_s_setprio(1); _Pragma("unroll") for (int m = 0; m < 4; ++m) _Pragma("unroll") for (int n = 0; n < 2; ++n) _Pragma("unroll") for (int k = 0; k < 2; ++k) \
;         acc[ai][bj][m][n] = __builtin_amdgcn_mfma_f32_16x16x32_bf16(Bt[n][k], At[m][k], acc[ai][bj][m][n], 0, 0, 0); __builtin_amdgcn_s_setprio(0); } while (0)
; #define PG8_WAIT_V(n) asm volatile("s_waitcnt vmcnt(" #n ")" ::: "memory")
; #define PG8_WAIT_L(n) asm volatile("s_waitcnt lgkmcnt(" #n ")" ::: "memory")
; #define PG8_BAR __builtin_amdgcn_s_barrier()
; #define PG8_SCHED __builtin_amdgcn_sched_barrier(0)
; template <class Epi, class Sched, bool ALIGN_EPI = false, bool SP2 = false>
; __device__ __forceinline__ void gemm_phase(PG8_LAS unsigned char* lds, const Gemm g, const Sched& S, const Epi& E) {
;     ...
;         for (int t = 0; t < nt; t += 2) {
;             const bool last = (t == nt - 2);
;     ...
;             PG8_LDB(B0, 1, 0); PG8_LDB(B1, 1, 1); PG8_SCHED; PG8_LDA(At, 1, 0); PG8_STAGE(PG8_SA(0, 1), a2 + hstep, voffA);
;             PG8_WAIT_V(8); PG8_WAIT_L(0); PG8_BAR; PG8_MMA(0, 0, At, B0); PG8_MMA(0, 1, At, B1); PG8_BAR; PG8_SCHED;
;             PG8_LDA(At, 1, 1); PG8_STAGE(PG8_SB(1, 0), b3, voffB); PG8_STAGE(PG8_SB(1, 1), b3 + hstep, voffB); PG8_STAGE(PG8_SA(1, 0), a3, voffA);
;             PG8_WAIT_V(8); PG8_WAIT_L(0); PG8_BAR; PG8_MMA(1, 0, At, B0); PG8_MMA(1, 1, At, B1); PG8_BAR; PG8_SCHED;
	v_mfma_f32_16x16x32_bf16 v[14:17], v[134:137], v[252:255], v[14:17]
	s_setprio 0
	ds_read_b128 v[248:251], v148
	ds_read_b128 v[150:153], v148 offset:1024
	ds_read_b128 v[154:157], v148 offset:2048
	ds_read_b128 v[158:161], v148 offset:3072
	ds_read_b128 v[162:165], v149
	ds_read_b128 v[166:169], v149 offset:1024
	ds_read_b128 v[170:173], v149 offset:2048
	ds_read_b128 v[174:177], v149 offset:3072
	ds_read_b128 v[178:181], v147 offset:32768
	ds_read_b128 v[182:185], v147 offset:33792
	ds_read_b128 v[186:189], v147 offset:34816
	ds_read_b128 v[190:193], v147 offset:35840
	ds_read_b128 v[194:197], v147 offset:36864
	ds_read_b128 v[198:201], v147 offset:37888
	ds_read_b128 v[202:205], v147 offset:38912
	ds_read_b128 v[206:209], v147 offset:39936
	s_add_u32 s36, s44, 0x2b0000
	s_addc_u32 s37, s45, 0
	s_mov_b32 m0, s52
	s_nop 0
	global_load_lds_dwordx4 v1, s[36:37]
	s_nop 0
	s_mov_b32 m0, s53
	s_nop 0
	global_load_lds_dwordx4 v141, s[36:37]
	s_waitcnt vmcnt(8)
	s_waitcnt lgkmcnt(0)
	s_barrier
	s_setprio 1
	s_waitcnt lgkmcnt(7)
	v_mfma_f32_16x16x32_bf16 v[126:129], v[248:251], v[178:181], v[126:129]
	v_mfma_f32_16x16x32_bf16 v[126:129], v[150:153], v[182:185], v[126:129]
	v_mfma_f32_16x16x32_bf16 v[122:125], v[158:161], v[182:185], v[122:125]
	v_mfma_f32_16x16x32_bf16 v[122:125], v[154:157], v[178:181], v[122:125]
	v_mfma_f32_16x16x32_bf16 v[118:121], v[162:165], v[178:181], v[118:121]
	v_mfma_f32_16x16x32_bf16 v[118:121], v[166:169], v[182:185], v[118:121]
	v_mfma_f32_16x16x32_bf16 v[114:117], v[174:177], v[182:185], v[114:117]
	v_mfma_f32_16x16x32_bf16 v[114:117], v[170:173], v[178:181], v[114:117]
	v_mfma_f32_16x16x32_bf16 v[98:101], v[170:173], v[186:189], v[98:101]
	v_mfma_f32_16x16x32_bf16 v[98:101], v[174:177], v[190:193], v[98:101]
	v_mfma_f32_16x16x32_bf16 v[102:105], v[166:169], v[190:193], v[102:105]
	v_mfma_f32_16x16x32_bf16 v[102:105], v[162:165], v[186:189], v[102:105]
	v_mfma_f32_16x16x32_bf16 v[106:109], v[154:157], v[186:189], v[106:109]
	v_mfma_f32_16x16x32_bf16 v[106:109], v[158:161], v[190:193], v[106:109]
	v_mfma_f32_16x16x32_bf16 v[110:113], v[150:153], v[190:193], v[110:113]
	v_mfma_f32_16x16x32_bf16 v[110:113], v[248:251], v[186:189], v[110:113]
	v_mfma_f32_16x16x32_bf16 v[94:97], v[248:251], v[194:197], v[94:97]
	v_mfma_f32_16x16x32_bf16 v[94:97], v[150:153], v[198:201], v[94:97]
	v_mfma_f32_16x16x32_bf16 v[90:93], v[158:161], v[198:201], v[90:93]
	v_mfma_f32_16x16x32_bf16 v[90:93], v[154:157], v[194:197], v[90:93]
	v_mfma_f32_16x16x32_bf16 v[86:89], v[162:165], v[194:197], v[86:89]
	v_mfma_f32_16x16x32_bf16 v[86:89], v[166:169], v[198:201], v[86:89]
	v_mfma_f32_16x16x32_bf16 v[82:85], v[174:177], v[198:201], v[82:85]
	v_mfma_f32_16x16x32_bf16 v[82:85], v[170:173], v[194:197], v[82:85]
	v_mfma_f32_16x16x32_bf16 v[66:69], v[170:173], v[202:205], v[66:69]
	v_mfma_f32_16x16x32_bf16 v[66:69], v[174:177], v[206:209], v[66:69]
	v_mfma_f32_16x16x32_bf16 v[70:73], v[166:169], v[206:209], v[70:73]
	v_mfma_f32_16x16x32_bf16 v[70:73], v[162:165], v[202:205], v[70:73]
	v_mfma_f32_16x16x32_bf16 v[74:77], v[154:157], v[202:205], v[74:77]
	v_mfma_f32_16x16x32_bf16 v[74:77], v[158:161], v[206:209], v[74:77]
	v_mfma_f32_16x16x32_bf16 v[78:81], v[150:153], v[206:209], v[78:81]
	s_setprio 2
	s_barrier
	v_mfma_f32_16x16x32_bf16 v[78:81], v[248:251], v[202:205], v[78:81]
	s_setprio 0
	ds_read_b128 v[178:181], v147 offset:49152
	ds_read_b128 v[182:185], v147 offset:50176
	ds_read_b128 v[186:189], v147 offset:51200
	ds_read_b128 v[190:193], v147 offset:52224
	ds_read_b128 v[194:197], v147 offset:53248
	ds_read_b128 v[198:201], v147 offset:54272
	ds_read_b128 v[252:255], v147 offset:55296
	ds_read_b128 v[206:209], v147 offset:56320
	s_add_u32 s36, s42, 0x80
	s_addc_u32 s37, s43, 0
	s_mov_b32 m0, s54
	s_nop 0
	global_load_lds_dwordx4 v140, s[36:37]
	s_nop 0
	s_mov_b32 m0, s55
	s_nop 0
	global_load_lds_dwordx4 v142, s[36:37]
	s_add_u32 s36, s42, 0x2b0080
	s_addc_u32 s37, s43, 0
	s_mov_b32 m0, s58
	s_nop 0
	global_load_lds_dwordx4 v140, s[36:37]
	s_nop 0
	s_mov_b32 m0, s59
	s_nop 0
	global_load_lds_dwordx4 v142, s[36:37]
	s_nop 0
	s_mov_b32 m0, s56
	s_nop 0
	global_load_lds_dwordx4 v1, s[40:41]
	s_nop 0
	s_mov_b32 m0, s57
	s_nop 0
	global_load_lds_dwordx4 v141, s[40:41]
	s_waitcnt vmcnt(8)
	s_waitcnt lgkmcnt(0)
	s_barrier
	s_setprio 1
	s_waitcnt lgkmcnt(7)
	v_mfma_f32_16x16x32_bf16 v[62:65], v[248:251], v[178:181], v[62:65]
	v_mfma_f32_16x16x32_bf16 v[62:65], v[150:153], v[182:185], v[62:65]
	v_mfma_f32_16x16x32_bf16 v[58:61], v[158:161], v[182:185], v[58:61]
	v_mfma_f32_16x16x32_bf16 v[58:61], v[154:157], v[178:181], v[58:61]
	v_mfma_f32_16x16x32_bf16 v[54:57], v[162:165], v[178:181], v[54:57]
	v_mfma_f32_16x16x32_bf16 v[54:57], v[166:169], v[182:185], v[54:57]
	v_mfma_f32_16x16x32_bf16 v[50:53], v[174:177], v[182:185], v[50:53]
	v_mfma_f32_16x16x32_bf16 v[50:53], v[170:173], v[178:181], v[50:53]
	v_mfma_f32_16x16x32_bf16 v[34:37], v[170:173], v[186:189], v[34:37]
	v_mfma_f32_16x16x32_bf16 v[34:37], v[174:177], v[190:193], v[34:37]
	v_mfma_f32_16x16x32_bf16 v[38:41], v[166:169], v[190:193], v[38:41]
	v_mfma_f32_16x16x32_bf16 v[38:41], v[162:165], v[186:189], v[38:41]
	v_mfma_f32_16x16x32_bf16 v[42:45], v[154:157], v[186:189], v[42:45]
	v_mfma_f32_16x16x32_bf16 v[42:45], v[158:161], v[190:193], v[42:45]
	v_mfma_f32_16x16x32_bf16 v[46:49], v[150:153], v[190:193], v[46:49]
	v_mfma_f32_16x16x32_bf16 v[46:49], v[248:251], v[186:189], v[46:49]
	v_mfma_f32_16x16x32_bf16 v[30:33], v[248:251], v[194:197], v[30:33]
	v_mfma_f32_16x16x32_bf16 v[30:33], v[150:153], v[198:201], v[30:33]
	v_mfma_f32_16x16x32_bf16 v[26:29], v[158:161], v[198:201], v[26:29]
	v_mfma_f32_16x16x32_bf16 v[26:29], v[154:157], v[194:197], v[26:29]
	v_mfma_f32_16x16x32_bf16 v[22:25], v[162:165], v[194:197], v[22:25]
	v_mfma_f32_16x16x32_bf16 v[22:25], v[166:169], v[198:201], v[22:25]
	v_mfma_f32_16x16x32_bf16 v[18:21], v[174:177], v[198:201], v[18:21]
	v_mfma_f32_16x16x32_bf16 v[18:21], v[170:173], v[194:197], v[18:21]
	v_mfma_f32_16x16x32_bf16 v[2:5], v[170:173], v[252:255], v[2:5]
	v_mfma_f32_16x16x32_bf16 v[2:5], v[174:177], v[206:209], v[2:5]
	v_mfma_f32_16x16x32_bf16 v[6:9], v[166:169], v[206:209], v[6:9]
	v_mfma_f32_16x16x32_bf16 v[6:9], v[162:165], v[252:255], v[6:9]
	v_mfma_f32_16x16x32_bf16 v[10:13], v[154:157], v[252:255], v[10:13]
	v_mfma_f32_16x16x32_bf16 v[10:13], v[158:161], v[206:209], v[10:13]
	v_mfma_f32_16x16x32_bf16 v[14:17], v[150:153], v[206:209], v[14:17]
	s_setprio 2
	s_barrier
	v_mfma_f32_16x16x32_bf16 v[14:17], v[248:251], v[252:255], v[14:17]
	s_setprio 0
	s_add_i32 s69, s69, 2
	s_add_u32 s67, s67, 0x100
	s_addc_u32 s68, s68, 0
	s_cmpk_gt_u32 s69, 0xa9
	s_mov_b64 s[36:37], s[38:39]
	s_cbranch_scc0 .LBB0_873
	s_and_b64 vcc, exec, s[10:11]
	s_cbranch_vccz .LBB0_876
	s_barrier
